# kl_final: peeled final K-iteration (no dummy next-unit prefetch when has_next is false) in P1/P5/P7/P9/P11 K-loops, on top of v6
# speedup vs baseline: 1.0044x; 1.0041x over previous
; #define PG8_STAGE(bufoff, gbase, voff) do { _Pragma("unroll") for (int _i = 0; _i < 2; ++_i) \
;         __builtin_amdgcn_global_load_lds((const unsigned*)((const char*)(gbase) + (voff)[_i]), (PG8_LAS unsigned*)(lds + (bufoff) + ldsw + _i * 8192), 16, 0, 0); } while (0)
; #define PG8_LDA(dst, b, h) do { _Pragma("unroll") for (int m = 0; m < 4; ++m) _Pragma("unroll") for (int k = 0; k < 2; ++k) dst[m][k] = *(const PG8_LAS bf16x8*)(lds + PG8_SA(b, h) + aoff + m * 2048 + k * 1024); } while (0)
; #define PG8_LDB(dst, b, h) do { _Pragma("unroll") for (int n = 0; n < 2; ++n) _Pragma("unroll") for (int k = 0; k < 2; ++k) dst[n][k] = *(const PG8_LAS bf16x8*)(lds + PG8_SB(b, h) + boff + n * 2048 + k * 1024); } while (0)
; #define PG8_MMA(ai, bj, At, Bt) do { __builtin_amdgcn_s_setprio(1); _Pragma("unroll") for (int m = 0; m < 4; ++m) _Pragma("unroll") for (int n = 0; n < 2; ++n) _Pragma("unroll") for (int k = 0; k < 2; ++k) \
;         acc[ai][bj][m][n] = __builtin_amdgcn_mfma_f32_16x16x32_bf16(Bt[n][k], At[m][k], acc[ai][bj][m][n], 0, 0, 0); __builtin_amdgcn_s_setprio(0); } while (0)
; #define PG8_WAIT_V(n) asm volatile("s_waitcnt vmcnt(" #n ")" ::: "memory")
; #define PG8_WAIT_L(n) asm volatile("s_waitcnt lgkmcnt(" #n ")" ::: "memory")
; template <class Epi, class Sched, bool ALIGN_EPI = false, bool SP2 = false>
; __device__ __forceinline__ void gemm_phase(PG8_LAS unsigned char* lds, const Gemm g, const Sched& S, const Epi& E) {
;     ...
;             const bool last = (t == nt - 2);
;             const char* a1 = cA + (size_t)(t + 1) * kstep;
;             const char* a2 = last ? nA : cA + (size_t)(t + 2) * kstep; const char* b2 = last ? nB : cB + (size_t)(t + 2) * kstep;
;             const char* a3 = a2 + kstep; const char* b3 = b2 + kstep;
;             if (last && has_next) S.a_ready(nxt);
;             if constexpr (SP2) {
;             PG8_LDB(B0, 0, 0); PG8_LDB(B1, 0, 1); PG8_SCHED; PG8_LDA(At, 0, 0); PG8_STAGE(PG8_SA(1, 1), a1 + hstep, voffA);
;             PG8_WAIT_V(8); PG8_WAIT_L(0); PG8_BAR; PG8_MMA(0, 0, At, B0); PG8_MMA(0, 1, At, B1); PG8_BAR; PG8_SCHED;
;             PG8_LDA(At, 0, 1); PG8_STAGE(PG8_SB(0, 0), b2, voffB); PG8_STAGE(PG8_SB(0, 1), b2 + hstep, voffB); PG8_STAGE(PG8_SA(0, 0), a2, voffA);
;             PG8_WAIT_V(8); PG8_WAIT_L(0); PG8_BAR; PG8_MMA(1, 0, At, B0); PG8_MMA(1, 1, At, B1); PG8_BAR; PG8_SCHED;
.LBB0_136:
	s_cmp_eq_u32 s76, 12
	s_cbranch_scc0 .Lkf0_norm
	s_cmp_eq_u64 s[0:1], 0
	s_cbranch_scc1 .Lkf0_fin
.Lkf0_norm:
	ds_read_b128 v[158:161], v152
	ds_read_b128 v[162:165], v152 offset:1024
	ds_read_b128 v[166:169], v152 offset:2048
	ds_read_b128 v[170:173], v152 offset:3072
	ds_read_b128 v[174:177], v153
	ds_read_b128 v[178:181], v153 offset:1024
	ds_read_b128 v[182:185], v153 offset:2048
	ds_read_b128 v[186:189], v153 offset:3072
	s_add_u32 s64, s62, 0xfffc0080
	s_addc_u32 s65, s63, -1
	s_cmp_eq_u32 s76, 12
	s_cselect_b32 s71, s5, s65
	s_cselect_b32 s70, s26, s64
	s_cselect_b32 s65, s27, s75
	s_cselect_b32 s64, s53, s55
	s_add_i32 m0, s61, 0xc000
	ds_read_b128 v[190:193], v154
	ds_read_b128 v[194:197], v154 offset:1024
	ds_read_b128 v[198:201], v154 offset:2048
	ds_read_b128 v[206:209], v154 offset:3072
	ds_read_b128 v[210:213], v154 offset:4096
	ds_read_b128 v[214:217], v154 offset:5120
	ds_read_b128 v[218:221], v154 offset:6144
	ds_read_b128 v[222:225], v154 offset:7168
	global_load_lds_dwordx4 v138, s[62:63]
	s_add_i32 m0, s61, 0xe000
	s_nop 0
	global_load_lds_dwordx4 v140, s[62:63]
	s_waitcnt vmcnt(8)
	s_waitcnt lgkmcnt(0)
	s_setprio 1
	s_barrier
	v_mfma_f32_16x16x32_bf16 v[124:127], v[158:161], v[190:193], v[124:127]
	v_mfma_f32_16x16x32_bf16 v[120:123], v[166:169], v[190:193], v[120:123]
	v_mfma_f32_16x16x32_bf16 v[108:111], v[158:161], v[198:201], v[108:111]
	v_mfma_f32_16x16x32_bf16 v[104:107], v[166:169], v[198:201], v[104:107]
	v_mfma_f32_16x16x32_bf16 v[92:95], v[158:161], v[210:213], v[92:95]
	v_mfma_f32_16x16x32_bf16 v[88:91], v[166:169], v[210:213], v[88:91]
	v_mfma_f32_16x16x32_bf16 v[76:79], v[158:161], v[218:221], v[76:79]
	v_mfma_f32_16x16x32_bf16 v[72:75], v[166:169], v[218:221], v[72:75]
	v_mfma_f32_16x16x32_bf16 v[124:127], v[162:165], v[194:197], v[124:127]
	v_mfma_f32_16x16x32_bf16 v[120:123], v[170:173], v[194:197], v[120:123]
	v_mfma_f32_16x16x32_bf16 v[108:111], v[162:165], v[206:209], v[108:111]
	v_mfma_f32_16x16x32_bf16 v[104:107], v[170:173], v[206:209], v[104:107]
	v_mfma_f32_16x16x32_bf16 v[92:95], v[162:165], v[214:217], v[92:95]
	v_mfma_f32_16x16x32_bf16 v[88:91], v[170:173], v[214:217], v[88:91]
	v_mfma_f32_16x16x32_bf16 v[76:79], v[162:165], v[222:225], v[76:79]
	v_mfma_f32_16x16x32_bf16 v[72:75], v[170:173], v[222:225], v[72:75]
	v_mfma_f32_16x16x32_bf16 v[116:119], v[174:177], v[190:193], v[116:119]
	v_mfma_f32_16x16x32_bf16 v[112:115], v[182:185], v[190:193], v[112:115]
	v_mfma_f32_16x16x32_bf16 v[100:103], v[174:177], v[198:201], v[100:103]
	v_mfma_f32_16x16x32_bf16 v[96:99], v[182:185], v[198:201], v[96:99]
	v_mfma_f32_16x16x32_bf16 v[84:87], v[174:177], v[210:213], v[84:87]
	v_mfma_f32_16x16x32_bf16 v[80:83], v[182:185], v[210:213], v[80:83]
	v_mfma_f32_16x16x32_bf16 v[68:71], v[174:177], v[218:221], v[68:71]
	v_mfma_f32_16x16x32_bf16 v[64:67], v[182:185], v[218:221], v[64:67]
	v_mfma_f32_16x16x32_bf16 v[116:119], v[178:181], v[194:197], v[116:119]
	v_mfma_f32_16x16x32_bf16 v[112:115], v[186:189], v[194:197], v[112:115]
	v_mfma_f32_16x16x32_bf16 v[100:103], v[178:181], v[206:209], v[100:103]
	v_mfma_f32_16x16x32_bf16 v[96:99], v[186:189], v[206:209], v[96:99]
	v_mfma_f32_16x16x32_bf16 v[84:87], v[178:181], v[214:217], v[84:87]
	v_mfma_f32_16x16x32_bf16 v[80:83], v[186:189], v[214:217], v[80:83]
	v_mfma_f32_16x16x32_bf16 v[68:71], v[178:181], v[222:225], v[68:71]
	v_mfma_f32_16x16x32_bf16 v[64:67], v[186:189], v[222:225], v[64:67]
	s_setprio 0
	s_barrier
	s_add_i32 s77, s72, s33
	s_mov_b32 m0, s77
	ds_read_b128 v[190:193], v154 offset:16384
	ds_read_b128 v[194:197], v154 offset:17408
	ds_read_b128 v[198:201], v154 offset:18432
	ds_read_b128 v[206:209], v154 offset:19456
	ds_read_b128 v[210:213], v154 offset:20480
	ds_read_b128 v[214:217], v154 offset:21504
	ds_read_b128 v[218:221], v154 offset:22528
	ds_read_b128 v[222:225], v154 offset:23552
	global_load_lds_dwordx4 v132, s[64:65]
	s_add_i32 m0, s77, 0x2000
	s_add_u32 s98, s64, 0x80
	s_addc_u32 s99, s65, 0
	s_add_u32 s78, s64, 0x40000
	s_addc_u32 s79, s65, 0
	s_add_i32 s77, s73, s33
	global_load_lds_dwordx4 v136, s[64:65]
	s_mov_b32 m0, s77
	s_nop 0
	global_load_lds_dwordx4 v132, s[78:79]
	s_add_i32 m0, s77, 0x2000
	s_nop 0
	global_load_lds_dwordx4 v136, s[78:79]
	s_mov_b32 m0, s61
	s_nop 0
	global_load_lds_dwordx4 v130, s[70:71]
	s_mov_b32 m0, s66
	s_nop 0
	global_load_lds_dwordx4 v134, s[70:71]
	s_waitcnt vmcnt(8)
	s_waitcnt lgkmcnt(0)
	s_setprio 1
	s_barrier
	v_mfma_f32_16x16x32_bf16 v[60:63], v[158:161], v[190:193], v[60:63]
	v_mfma_f32_16x16x32_bf16 v[56:59], v[166:169], v[190:193], v[56:59]
	v_mfma_f32_16x16x32_bf16 v[44:47], v[158:161], v[198:201], v[44:47]
	v_mfma_f32_16x16x32_bf16 v[40:43], v[166:169], v[198:201], v[40:43]
	v_mfma_f32_16x16x32_bf16 v[28:31], v[158:161], v[210:213], v[28:31]
	v_mfma_f32_16x16x32_bf16 v[24:27], v[166:169], v[210:213], v[24:27]
	v_mfma_f32_16x16x32_bf16 v[12:15], v[158:161], v[218:221], v[12:15]
	v_mfma_f32_16x16x32_bf16 v[8:11], v[166:169], v[218:221], v[8:11]
	v_mfma_f32_16x16x32_bf16 v[60:63], v[162:165], v[194:197], v[60:63]
	v_mfma_f32_16x16x32_bf16 v[56:59], v[170:173], v[194:197], v[56:59]
	v_mfma_f32_16x16x32_bf16 v[44:47], v[162:165], v[206:209], v[44:47]
	v_mfma_f32_16x16x32_bf16 v[40:43], v[170:173], v[206:209], v[40:43]
	v_mfma_f32_16x16x32_bf16 v[28:31], v[162:165], v[214:217], v[28:31]
	v_mfma_f32_16x16x32_bf16 v[24:27], v[170:173], v[214:217], v[24:27]
	v_mfma_f32_16x16x32_bf16 v[12:15], v[162:165], v[222:225], v[12:15]
	v_mfma_f32_16x16x32_bf16 v[8:11], v[170:173], v[222:225], v[8:11]
	v_mfma_f32_16x16x32_bf16 v[52:55], v[174:177], v[190:193], v[52:55]
	v_mfma_f32_16x16x32_bf16 v[48:51], v[182:185], v[190:193], v[48:51]
	v_mfma_f32_16x16x32_bf16 v[36:39], v[174:177], v[198:201], v[36:39]
	v_mfma_f32_16x16x32_bf16 v[32:35], v[182:185], v[198:201], v[32:35]
	v_mfma_f32_16x16x32_bf16 v[20:23], v[174:177], v[210:213], v[20:23]
	v_mfma_f32_16x16x32_bf16 v[16:19], v[182:185], v[210:213], v[16:19]
	v_mfma_f32_16x16x32_bf16 v[4:7], v[174:177], v[218:221], v[4:7]
	v_mfma_f32_16x16x32_bf16 v[0:3], v[182:185], v[218:221], v[0:3]
	v_mfma_f32_16x16x32_bf16 v[52:55], v[178:181], v[194:197], v[52:55]
	v_mfma_f32_16x16x32_bf16 v[48:51], v[186:189], v[194:197], v[48:51]
	v_mfma_f32_16x16x32_bf16 v[36:39], v[178:181], v[206:209], v[36:39]
	v_mfma_f32_16x16x32_bf16 v[32:35], v[186:189], v[206:209], v[32:35]
	v_mfma_f32_16x16x32_bf16 v[20:23], v[178:181], v[214:217], v[20:23]
	v_mfma_f32_16x16x32_bf16 v[16:19], v[186:189], v[214:217], v[16:19]
	v_mfma_f32_16x16x32_bf16 v[4:7], v[178:181], v[222:225], v[4:7]
	v_mfma_f32_16x16x32_bf16 v[0:3], v[186:189], v[222:225], v[0:3]
	s_setprio 0
	s_barrier
; #define PG8_STAGE(bufoff, gbase, voff) do { _Pragma("unroll") for (int _i = 0; _i < 2; ++_i) \
;         __builtin_amdgcn_global_load_lds((const unsigned*)((const char*)(gbase) + (voff)[_i]), (PG8_LAS unsigned*)(lds + (bufoff) + ldsw + _i * 8192), 16, 0, 0); } while (0)
; #define PG8_LDA(dst, b, h) do { _Pragma("unroll") for (int m = 0; m < 4; ++m) _Pragma("unroll") for (int k = 0; k < 2; ++k) dst[m][k] = *(const PG8_LAS bf16x8*)(lds + PG8_SA(b, h) + aoff + m * 2048 + k * 1024); } while (0)
; #define PG8_LDB(dst, b, h) do { _Pragma("unroll") for (int n = 0; n < 2; ++n) _Pragma("unroll") for (int k = 0; k < 2; ++k) dst[n][k] = *(const PG8_LAS bf16x8*)(lds + PG8_SB(b, h) + boff + n * 2048 + k * 1024); } while (0)
; #define PG8_MMA(ai, bj, At, Bt) do { __builtin_amdgcn_s_setprio(1); _Pragma("unroll") for (int m = 0; m < 4; ++m) _Pragma("unroll") for (int n = 0; n < 2; ++n) _Pragma("unroll") for (int k = 0; k < 2; ++k) \
;         acc[ai][bj][m][n] = __builtin_amdgcn_mfma_f32_16x16x32_bf16(Bt[n][k], At[m][k], acc[ai][bj][m][n], 0, 0, 0); __builtin_amdgcn_s_setprio(0); } while (0)
; #define PG8_WAIT_V(n) asm volatile("s_waitcnt vmcnt(" #n ")" ::: "memory")
; #define PG8_WAIT_L(n) asm volatile("s_waitcnt lgkmcnt(" #n ")" ::: "memory")
; #define PG8_BAR __builtin_amdgcn_s_barrier()
; #define PG8_SCHED __builtin_amdgcn_sched_barrier(0)
; template <class Epi, class Sched, bool ALIGN_EPI = false, bool SP2 = false>
; __device__ __forceinline__ void gemm_phase(PG8_LAS unsigned char* lds, const Gemm g, const Sched& S, const Epi& E) {
;     ...
;             PG8_LDB(B0, 1, 0); PG8_LDB(B1, 1, 1); PG8_SCHED; PG8_LDA(At, 1, 0); PG8_STAGE(PG8_SA(0, 1), a2 + hstep, voffA);
;             PG8_WAIT_V(8); PG8_WAIT_L(0); PG8_BAR; PG8_MMA(0, 0, At, B0); PG8_MMA(0, 1, At, B1); PG8_BAR; PG8_SCHED;
;             PG8_LDA(At, 1, 1); PG8_STAGE(PG8_SB(1, 0), b3, voffB); PG8_STAGE(PG8_SB(1, 1), b3 + hstep, voffB); PG8_STAGE(PG8_SA(1, 0), a3, voffA);
;             PG8_WAIT_V(8); PG8_WAIT_L(0); PG8_BAR; PG8_MMA(1, 0, At, B0); PG8_MMA(1, 1, At, B1); PG8_BAR; PG8_SCHED;
	s_add_i32 s77, 0, 0x18000
	s_add_i32 s78, 0, 0x1c000
	ds_read_b128 v[158:161], v240
	ds_read_b128 v[162:165], v240 offset:1024
	ds_read_b128 v[166:169], v240 offset:2048
	ds_read_b128 v[170:173], v240 offset:3072
	ds_read_b128 v[174:177], v241
	ds_read_b128 v[178:181], v241 offset:1024
	ds_read_b128 v[182:185], v241 offset:2048
	ds_read_b128 v[186:189], v241 offset:3072
	s_add_u32 s100, s70, 0x80
	s_addc_u32 s101, s71, 0
	s_add_u32 s70, s70, 0x40000
	s_addc_u32 s71, s71, 0
	s_mov_b32 m0, s67
	ds_read_b128 v[190:193], v154 offset:32768
	ds_read_b128 v[194:197], v154 offset:33792
	ds_read_b128 v[198:201], v154 offset:34816
	ds_read_b128 v[206:209], v154 offset:35840
	ds_read_b128 v[210:213], v154 offset:36864
	ds_read_b128 v[214:217], v154 offset:37888
	ds_read_b128 v[218:221], v154 offset:38912
	ds_read_b128 v[222:225], v154 offset:39936
	global_load_lds_dwordx4 v130, s[70:71]
	s_mov_b32 m0, s88
	s_nop 0
	global_load_lds_dwordx4 v134, s[70:71]
	s_waitcnt vmcnt(8)
	s_waitcnt lgkmcnt(0)
	s_setprio 1
	s_barrier
	v_mfma_f32_16x16x32_bf16 v[124:127], v[158:161], v[190:193], v[124:127]
	v_mfma_f32_16x16x32_bf16 v[120:123], v[166:169], v[190:193], v[120:123]
	v_mfma_f32_16x16x32_bf16 v[108:111], v[158:161], v[198:201], v[108:111]
	v_mfma_f32_16x16x32_bf16 v[104:107], v[166:169], v[198:201], v[104:107]
	v_mfma_f32_16x16x32_bf16 v[92:95], v[158:161], v[210:213], v[92:95]
	v_mfma_f32_16x16x32_bf16 v[88:91], v[166:169], v[210:213], v[88:91]
	v_mfma_f32_16x16x32_bf16 v[76:79], v[158:161], v[218:221], v[76:79]
	v_mfma_f32_16x16x32_bf16 v[72:75], v[166:169], v[218:221], v[72:75]
	v_mfma_f32_16x16x32_bf16 v[124:127], v[162:165], v[194:197], v[124:127]
	v_mfma_f32_16x16x32_bf16 v[120:123], v[170:173], v[194:197], v[120:123]
	v_mfma_f32_16x16x32_bf16 v[108:111], v[162:165], v[206:209], v[108:111]
	v_mfma_f32_16x16x32_bf16 v[104:107], v[170:173], v[206:209], v[104:107]
	v_mfma_f32_16x16x32_bf16 v[92:95], v[162:165], v[214:217], v[92:95]
	v_mfma_f32_16x16x32_bf16 v[88:91], v[170:173], v[214:217], v[88:91]
	v_mfma_f32_16x16x32_bf16 v[76:79], v[162:165], v[222:225], v[76:79]
	v_mfma_f32_16x16x32_bf16 v[72:75], v[170:173], v[222:225], v[72:75]
	v_mfma_f32_16x16x32_bf16 v[116:119], v[174:177], v[190:193], v[116:119]
	v_mfma_f32_16x16x32_bf16 v[112:115], v[182:185], v[190:193], v[112:115]
	v_mfma_f32_16x16x32_bf16 v[100:103], v[174:177], v[198:201], v[100:103]
	v_mfma_f32_16x16x32_bf16 v[96:99], v[182:185], v[198:201], v[96:99]
	v_mfma_f32_16x16x32_bf16 v[84:87], v[174:177], v[210:213], v[84:87]
	v_mfma_f32_16x16x32_bf16 v[80:83], v[182:185], v[210:213], v[80:83]
	v_mfma_f32_16x16x32_bf16 v[68:71], v[174:177], v[218:221], v[68:71]
	v_mfma_f32_16x16x32_bf16 v[64:67], v[182:185], v[218:221], v[64:67]
	v_mfma_f32_16x16x32_bf16 v[116:119], v[178:181], v[194:197], v[116:119]
	v_mfma_f32_16x16x32_bf16 v[112:115], v[186:189], v[194:197], v[112:115]
	v_mfma_f32_16x16x32_bf16 v[100:103], v[178:181], v[206:209], v[100:103]
	v_mfma_f32_16x16x32_bf16 v[96:99], v[186:189], v[206:209], v[96:99]
	v_mfma_f32_16x16x32_bf16 v[84:87], v[178:181], v[214:217], v[84:87]
	v_mfma_f32_16x16x32_bf16 v[80:83], v[186:189], v[214:217], v[80:83]
	v_mfma_f32_16x16x32_bf16 v[68:71], v[178:181], v[222:225], v[68:71]
	v_mfma_f32_16x16x32_bf16 v[64:67], v[186:189], v[222:225], v[64:67]
	s_setprio 0
	s_barrier
	s_add_i32 s70, s77, s33
	s_mov_b32 m0, s70
	ds_read_b128 v[190:193], v154 offset:49152
	ds_read_b128 v[194:197], v154 offset:50176
	ds_read_b128 v[198:201], v154 offset:51200
	ds_read_b128 v[206:209], v154 offset:52224
	ds_read_b128 v[210:213], v154 offset:53248
	ds_read_b128 v[214:217], v154 offset:54272
	ds_read_b128 v[218:221], v154 offset:55296
	ds_read_b128 v[222:225], v154 offset:56320
	global_load_lds_dwordx4 v132, s[98:99]
	s_add_i32 m0, s70, 0x2000
	s_add_u32 s64, s64, 0x40080
	s_addc_u32 s65, s65, 0
	s_add_i32 s70, s78, s33
	global_load_lds_dwordx4 v136, s[98:99]
	s_mov_b32 m0, s70
	s_nop 0
	global_load_lds_dwordx4 v132, s[64:65]
	s_add_i32 m0, s70, 0x2000
	s_nop 0
	global_load_lds_dwordx4 v136, s[64:65]
	s_mov_b32 m0, s3
	s_nop 0
	global_load_lds_dwordx4 v130, s[100:101]
	s_mov_b32 m0, s68
	s_nop 0
	global_load_lds_dwordx4 v134, s[100:101]
	s_waitcnt vmcnt(8)
	s_waitcnt lgkmcnt(0)
	s_setprio 1
	s_barrier
	v_mfma_f32_16x16x32_bf16 v[60:63], v[158:161], v[190:193], v[60:63]
	v_mfma_f32_16x16x32_bf16 v[56:59], v[166:169], v[190:193], v[56:59]
	v_mfma_f32_16x16x32_bf16 v[44:47], v[158:161], v[198:201], v[44:47]
	v_mfma_f32_16x16x32_bf16 v[40:43], v[166:169], v[198:201], v[40:43]
	v_mfma_f32_16x16x32_bf16 v[28:31], v[158:161], v[210:213], v[28:31]
	v_mfma_f32_16x16x32_bf16 v[24:27], v[166:169], v[210:213], v[24:27]
	v_mfma_f32_16x16x32_bf16 v[12:15], v[158:161], v[218:221], v[12:15]
	v_mfma_f32_16x16x32_bf16 v[8:11], v[166:169], v[218:221], v[8:11]
	v_mfma_f32_16x16x32_bf16 v[60:63], v[162:165], v[194:197], v[60:63]
	v_mfma_f32_16x16x32_bf16 v[56:59], v[170:173], v[194:197], v[56:59]
	v_mfma_f32_16x16x32_bf16 v[44:47], v[162:165], v[206:209], v[44:47]
	v_mfma_f32_16x16x32_bf16 v[40:43], v[170:173], v[206:209], v[40:43]
	v_mfma_f32_16x16x32_bf16 v[28:31], v[162:165], v[214:217], v[28:31]
	v_mfma_f32_16x16x32_bf16 v[24:27], v[170:173], v[214:217], v[24:27]
	v_mfma_f32_16x16x32_bf16 v[12:15], v[162:165], v[222:225], v[12:15]
	v_mfma_f32_16x16x32_bf16 v[8:11], v[170:173], v[222:225], v[8:11]
	v_mfma_f32_16x16x32_bf16 v[52:55], v[174:177], v[190:193], v[52:55]
	v_mfma_f32_16x16x32_bf16 v[48:51], v[182:185], v[190:193], v[48:51]
	v_mfma_f32_16x16x32_bf16 v[36:39], v[174:177], v[198:201], v[36:39]
	v_mfma_f32_16x16x32_bf16 v[32:35], v[182:185], v[198:201], v[32:35]
	v_mfma_f32_16x16x32_bf16 v[20:23], v[174:177], v[210:213], v[20:23]
	v_mfma_f32_16x16x32_bf16 v[16:19], v[182:185], v[210:213], v[16:19]
	v_mfma_f32_16x16x32_bf16 v[4:7], v[174:177], v[218:221], v[4:7]
	v_mfma_f32_16x16x32_bf16 v[0:3], v[182:185], v[218:221], v[0:3]
	v_mfma_f32_16x16x32_bf16 v[52:55], v[178:181], v[194:197], v[52:55]
	v_mfma_f32_16x16x32_bf16 v[48:51], v[186:189], v[194:197], v[48:51]
	v_mfma_f32_16x16x32_bf16 v[36:39], v[178:181], v[206:209], v[36:39]
	v_mfma_f32_16x16x32_bf16 v[32:35], v[186:189], v[206:209], v[32:35]
	v_mfma_f32_16x16x32_bf16 v[20:23], v[178:181], v[214:217], v[20:23]
	v_mfma_f32_16x16x32_bf16 v[16:19], v[186:189], v[214:217], v[16:19]
	v_mfma_f32_16x16x32_bf16 v[4:7], v[178:181], v[222:225], v[4:7]
	v_mfma_f32_16x16x32_bf16 v[0:3], v[186:189], v[222:225], v[0:3]
	s_setprio 0
	s_barrier
	s_add_i32 s76, s76, 2
	s_add_u32 s62, s62, 0x100
	s_addc_u32 s63, s63, 0
	s_add_u32 s55, s55, 0x100
	s_addc_u32 s75, s75, 0
	s_cmp_gt_u32 s76, 13
	s_cbranch_scc0 .LBB0_136
	s_branch .Lkf0_exit
; #define PG8_STAGE(bufoff, gbase, voff) do { _Pragma("unroll") for (int _i = 0; _i < 2; ++_i) \
;         __builtin_amdgcn_global_load_lds((const unsigned*)((const char*)(gbase) + (voff)[_i]), (PG8_LAS unsigned*)(lds + (bufoff) + ldsw + _i * 8192), 16, 0, 0); } while (0)
; #define PG8_LDA(dst, b, h) do { _Pragma("unroll") for (int m = 0; m < 4; ++m) _Pragma("unroll") for (int k = 0; k < 2; ++k) dst[m][k] = *(const PG8_LAS bf16x8*)(lds + PG8_SA(b, h) + aoff + m * 2048 + k * 1024); } while (0)
; #define PG8_LDB(dst, b, h) do { _Pragma("unroll") for (int n = 0; n < 2; ++n) _Pragma("unroll") for (int k = 0; k < 2; ++k) dst[n][k] = *(const PG8_LAS bf16x8*)(lds + PG8_SB(b, h) + boff + n * 2048 + k * 1024); } while (0)
; #define PG8_MMA(ai, bj, At, Bt) do { __builtin_amdgcn_s_setprio(1); _Pragma("unroll") for (int m = 0; m < 4; ++m) _Pragma("unroll") for (int n = 0; n < 2; ++n) _Pragma("unroll") for (int k = 0; k < 2; ++k) \
;         acc[ai][bj][m][n] = __builtin_amdgcn_mfma_f32_16x16x32_bf16(Bt[n][k], At[m][k], acc[ai][bj][m][n], 0, 0, 0); __builtin_amdgcn_s_setprio(0); } while (0)
; #define PG8_WAIT_V(n) asm volatile("s_waitcnt vmcnt(" #n ")" ::: "memory")
; #define PG8_WAIT_L(n) asm volatile("s_waitcnt lgkmcnt(" #n ")" ::: "memory")
; #define PG8_BAR __builtin_amdgcn_s_barrier()
; #define PG8_SCHED __builtin_amdgcn_sched_barrier(0)
; template <class Epi, class Sched, bool ALIGN_EPI = false, bool SP2 = false>
; __device__ __forceinline__ void gemm_phase(PG8_LAS unsigned char* lds, const Gemm g, const Sched& S, const Epi& E) {
;     ...
;             PG8_LDB(B0, 0, 0); PG8_LDB(B1, 0, 1); PG8_SCHED; PG8_LDA(At, 0, 0); PG8_STAGE(PG8_SA(1, 1), a1 + hstep, voffA);
;             PG8_WAIT_V(8); PG8_WAIT_L(0); PG8_BAR; PG8_MMA(0, 0, At, B0); PG8_MMA(0, 1, At, B1); PG8_BAR; PG8_SCHED;
;             PG8_LDA(At, 0, 1); PG8_STAGE(PG8_SB(0, 0), b2, voffB); PG8_STAGE(PG8_SB(0, 1), b2 + hstep, voffB); PG8_STAGE(PG8_SA(0, 0), a2, voffA);
;             PG8_WAIT_V(8); PG8_WAIT_L(0); PG8_BAR; PG8_MMA(1, 0, At, B0); PG8_MMA(1, 1, At, B1); PG8_BAR; PG8_SCHED;
.Lkf0_fin:
	ds_read_b128 v[158:161], v152
	ds_read_b128 v[162:165], v152 offset:1024
	ds_read_b128 v[166:169], v152 offset:2048
	ds_read_b128 v[170:173], v152 offset:3072
	ds_read_b128 v[174:177], v153
	ds_read_b128 v[178:181], v153 offset:1024
	ds_read_b128 v[182:185], v153 offset:2048
	ds_read_b128 v[186:189], v153 offset:3072
	s_add_u32 s64, s62, 0xfffc0080
	s_addc_u32 s65, s63, -1
	s_cmp_eq_u32 s76, 12
	s_cselect_b32 s71, s5, s65
	s_cselect_b32 s70, s26, s64
	s_cselect_b32 s65, s27, s75
	s_cselect_b32 s64, s53, s55
	s_add_i32 m0, s61, 0xc000
	ds_read_b128 v[190:193], v154
	ds_read_b128 v[194:197], v154 offset:1024
	ds_read_b128 v[198:201], v154 offset:2048
	ds_read_b128 v[206:209], v154 offset:3072
	ds_read_b128 v[210:213], v154 offset:4096
	ds_read_b128 v[214:217], v154 offset:5120
	ds_read_b128 v[218:221], v154 offset:6144
	ds_read_b128 v[222:225], v154 offset:7168
	global_load_lds_dwordx4 v138, s[62:63]
	s_add_i32 m0, s61, 0xe000
	s_nop 0
	global_load_lds_dwordx4 v140, s[62:63]
	s_waitcnt vmcnt(8)
	s_waitcnt lgkmcnt(0)
	s_setprio 1
	s_barrier
	v_mfma_f32_16x16x32_bf16 v[124:127], v[158:161], v[190:193], v[124:127]
	v_mfma_f32_16x16x32_bf16 v[120:123], v[166:169], v[190:193], v[120:123]
	v_mfma_f32_16x16x32_bf16 v[108:111], v[158:161], v[198:201], v[108:111]
	v_mfma_f32_16x16x32_bf16 v[104:107], v[166:169], v[198:201], v[104:107]
	v_mfma_f32_16x16x32_bf16 v[92:95], v[158:161], v[210:213], v[92:95]
	v_mfma_f32_16x16x32_bf16 v[88:91], v[166:169], v[210:213], v[88:91]
	v_mfma_f32_16x16x32_bf16 v[76:79], v[158:161], v[218:221], v[76:79]
	v_mfma_f32_16x16x32_bf16 v[72:75], v[166:169], v[218:221], v[72:75]
	v_mfma_f32_16x16x32_bf16 v[124:127], v[162:165], v[194:197], v[124:127]
	v_mfma_f32_16x16x32_bf16 v[120:123], v[170:173], v[194:197], v[120:123]
	v_mfma_f32_16x16x32_bf16 v[108:111], v[162:165], v[206:209], v[108:111]
	v_mfma_f32_16x16x32_bf16 v[104:107], v[170:173], v[206:209], v[104:107]
	v_mfma_f32_16x16x32_bf16 v[92:95], v[162:165], v[214:217], v[92:95]
	v_mfma_f32_16x16x32_bf16 v[88:91], v[170:173], v[214:217], v[88:91]
	v_mfma_f32_16x16x32_bf16 v[76:79], v[162:165], v[222:225], v[76:79]
	v_mfma_f32_16x16x32_bf16 v[72:75], v[170:173], v[222:225], v[72:75]
	v_mfma_f32_16x16x32_bf16 v[116:119], v[174:177], v[190:193], v[116:119]
	v_mfma_f32_16x16x32_bf16 v[112:115], v[182:185], v[190:193], v[112:115]
	v_mfma_f32_16x16x32_bf16 v[100:103], v[174:177], v[198:201], v[100:103]
	v_mfma_f32_16x16x32_bf16 v[96:99], v[182:185], v[198:201], v[96:99]
	v_mfma_f32_16x16x32_bf16 v[84:87], v[174:177], v[210:213], v[84:87]
	v_mfma_f32_16x16x32_bf16 v[80:83], v[182:185], v[210:213], v[80:83]
	v_mfma_f32_16x16x32_bf16 v[68:71], v[174:177], v[218:221], v[68:71]
	v_mfma_f32_16x16x32_bf16 v[64:67], v[182:185], v[218:221], v[64:67]
	v_mfma_f32_16x16x32_bf16 v[116:119], v[178:181], v[194:197], v[116:119]
	v_mfma_f32_16x16x32_bf16 v[112:115], v[186:189], v[194:197], v[112:115]
	v_mfma_f32_16x16x32_bf16 v[100:103], v[178:181], v[206:209], v[100:103]
	v_mfma_f32_16x16x32_bf16 v[96:99], v[186:189], v[206:209], v[96:99]
	v_mfma_f32_16x16x32_bf16 v[84:87], v[178:181], v[214:217], v[84:87]
	v_mfma_f32_16x16x32_bf16 v[80:83], v[186:189], v[214:217], v[80:83]
	v_mfma_f32_16x16x32_bf16 v[68:71], v[178:181], v[222:225], v[68:71]
	v_mfma_f32_16x16x32_bf16 v[64:67], v[186:189], v[222:225], v[64:67]
	s_setprio 0
	s_barrier
	s_add_i32 s77, s72, s33
	s_mov_b32 m0, s77
	ds_read_b128 v[190:193], v154 offset:16384
	ds_read_b128 v[194:197], v154 offset:17408
	ds_read_b128 v[198:201], v154 offset:18432
	ds_read_b128 v[206:209], v154 offset:19456
	ds_read_b128 v[210:213], v154 offset:20480
	ds_read_b128 v[214:217], v154 offset:21504
	ds_read_b128 v[218:221], v154 offset:22528
	ds_read_b128 v[222:225], v154 offset:23552
	s_waitcnt vmcnt(2)
	s_waitcnt lgkmcnt(0)
	s_setprio 1
	s_barrier
	v_mfma_f32_16x16x32_bf16 v[60:63], v[158:161], v[190:193], v[60:63]
	v_mfma_f32_16x16x32_bf16 v[56:59], v[166:169], v[190:193], v[56:59]
	v_mfma_f32_16x16x32_bf16 v[44:47], v[158:161], v[198:201], v[44:47]
	v_mfma_f32_16x16x32_bf16 v[40:43], v[166:169], v[198:201], v[40:43]
	v_mfma_f32_16x16x32_bf16 v[28:31], v[158:161], v[210:213], v[28:31]
	v_mfma_f32_16x16x32_bf16 v[24:27], v[166:169], v[210:213], v[24:27]
	v_mfma_f32_16x16x32_bf16 v[12:15], v[158:161], v[218:221], v[12:15]
	v_mfma_f32_16x16x32_bf16 v[8:11], v[166:169], v[218:221], v[8:11]
	v_mfma_f32_16x16x32_bf16 v[60:63], v[162:165], v[194:197], v[60:63]
	v_mfma_f32_16x16x32_bf16 v[56:59], v[170:173], v[194:197], v[56:59]
	v_mfma_f32_16x16x32_bf16 v[44:47], v[162:165], v[206:209], v[44:47]
	v_mfma_f32_16x16x32_bf16 v[40:43], v[170:173], v[206:209], v[40:43]
	v_mfma_f32_16x16x32_bf16 v[28:31], v[162:165], v[214:217], v[28:31]
	v_mfma_f32_16x16x32_bf16 v[24:27], v[170:173], v[214:217], v[24:27]
	v_mfma_f32_16x16x32_bf16 v[12:15], v[162:165], v[222:225], v[12:15]
	v_mfma_f32_16x16x32_bf16 v[8:11], v[170:173], v[222:225], v[8:11]
	v_mfma_f32_16x16x32_bf16 v[52:55], v[174:177], v[190:193], v[52:55]
	v_mfma_f32_16x16x32_bf16 v[48:51], v[182:185], v[190:193], v[48:51]
	v_mfma_f32_16x16x32_bf16 v[36:39], v[174:177], v[198:201], v[36:39]
	v_mfma_f32_16x16x32_bf16 v[32:35], v[182:185], v[198:201], v[32:35]
	v_mfma_f32_16x16x32_bf16 v[20:23], v[174:177], v[210:213], v[20:23]
	v_mfma_f32_16x16x32_bf16 v[16:19], v[182:185], v[210:213], v[16:19]
	v_mfma_f32_16x16x32_bf16 v[4:7], v[174:177], v[218:221], v[4:7]
	v_mfma_f32_16x16x32_bf16 v[0:3], v[182:185], v[218:221], v[0:3]
	v_mfma_f32_16x16x32_bf16 v[52:55], v[178:181], v[194:197], v[52:55]
	v_mfma_f32_16x16x32_bf16 v[48:51], v[186:189], v[194:197], v[48:51]
	v_mfma_f32_16x16x32_bf16 v[36:39], v[178:181], v[206:209], v[36:39]
	v_mfma_f32_16x16x32_bf16 v[32:35], v[186:189], v[206:209], v[32:35]
	v_mfma_f32_16x16x32_bf16 v[20:23], v[178:181], v[214:217], v[20:23]
	v_mfma_f32_16x16x32_bf16 v[16:19], v[186:189], v[214:217], v[16:19]
	v_mfma_f32_16x16x32_bf16 v[4:7], v[178:181], v[222:225], v[4:7]
	v_mfma_f32_16x16x32_bf16 v[0:3], v[186:189], v[222:225], v[0:3]
	s_setprio 0
	s_barrier
; #define PG8_STAGE(bufoff, gbase, voff) do { _Pragma("unroll") for (int _i = 0; _i < 2; ++_i) \
;         __builtin_amdgcn_global_load_lds((const unsigned*)((const char*)(gbase) + (voff)[_i]), (PG8_LAS unsigned*)(lds + (bufoff) + ldsw + _i * 8192), 16, 0, 0); } while (0)
; #define PG8_LDA(dst, b, h) do { _Pragma("unroll") for (int m = 0; m < 4; ++m) _Pragma("unroll") for (int k = 0; k < 2; ++k) dst[m][k] = *(const PG8_LAS bf16x8*)(lds + PG8_SA(b, h) + aoff + m * 2048 + k * 1024); } while (0)
; #define PG8_LDB(dst, b, h) do { _Pragma("unroll") for (int n = 0; n < 2; ++n) _Pragma("unroll") for (int k = 0; k < 2; ++k) dst[n][k] = *(const PG8_LAS bf16x8*)(lds + PG8_SB(b, h) + boff + n * 2048 + k * 1024); } while (0)
; #define PG8_MMA(ai, bj, At, Bt) do { __builtin_amdgcn_s_setprio(1); _Pragma("unroll") for (int m = 0; m < 4; ++m) _Pragma("unroll") for (int n = 0; n < 2; ++n) _Pragma("unroll") for (int k = 0; k < 2; ++k) \
;         acc[ai][bj][m][n] = __builtin_amdgcn_mfma_f32_16x16x32_bf16(Bt[n][k], At[m][k], acc[ai][bj][m][n], 0, 0, 0); __builtin_amdgcn_s_setprio(0); } while (0)
; #define PG8_WAIT_V(n) asm volatile("s_waitcnt vmcnt(" #n ")" ::: "memory")
; #define PG8_WAIT_L(n) asm volatile("s_waitcnt lgkmcnt(" #n ")" ::: "memory")
; #define PG8_BAR __builtin_amdgcn_s_barrier()
; #define PG8_SCHED __builtin_amdgcn_sched_barrier(0)
; template <class Epi, class Sched, bool ALIGN_EPI = false, bool SP2 = false>
; __device__ __forceinline__ void gemm_phase(PG8_LAS unsigned char* lds, const Gemm g, const Sched& S, const Epi& E) {
;     ...
;             PG8_LDB(B0, 1, 0); PG8_LDB(B1, 1, 1); PG8_SCHED; PG8_LDA(At, 1, 0); PG8_STAGE(PG8_SA(0, 1), a2 + hstep, voffA);
;             PG8_WAIT_V(8); PG8_WAIT_L(0); PG8_BAR; PG8_MMA(0, 0, At, B0); PG8_MMA(0, 1, At, B1); PG8_BAR; PG8_SCHED;
;             PG8_LDA(At, 1, 1); PG8_STAGE(PG8_SB(1, 0), b3, voffB); PG8_STAGE(PG8_SB(1, 1), b3 + hstep, voffB); PG8_STAGE(PG8_SA(1, 0), a3, voffA);
;             PG8_WAIT_V(8); PG8_WAIT_L(0); PG8_BAR; PG8_MMA(1, 0, At, B0); PG8_MMA(1, 1, At, B1); PG8_BAR; PG8_SCHED;
;     ...
;         if constexpr (ALIGN_EPI) { if (wr == 0) PG8_BAR; }
	s_add_i32 s77, 0, 0x18000
	s_add_i32 s78, 0, 0x1c000
	ds_read_b128 v[158:161], v240
	ds_read_b128 v[162:165], v240 offset:1024
	ds_read_b128 v[166:169], v240 offset:2048
	ds_read_b128 v[170:173], v240 offset:3072
	ds_read_b128 v[174:177], v241
	ds_read_b128 v[178:181], v241 offset:1024
	ds_read_b128 v[182:185], v241 offset:2048
	ds_read_b128 v[186:189], v241 offset:3072
	ds_read_b128 v[190:193], v154 offset:32768
	ds_read_b128 v[194:197], v154 offset:33792
	ds_read_b128 v[198:201], v154 offset:34816
	ds_read_b128 v[206:209], v154 offset:35840
	ds_read_b128 v[210:213], v154 offset:36864
	ds_read_b128 v[214:217], v154 offset:37888
	ds_read_b128 v[218:221], v154 offset:38912
	ds_read_b128 v[222:225], v154 offset:39936
	s_waitcnt vmcnt(0)
	s_waitcnt lgkmcnt(0)
	s_setprio 1
	s_barrier
	v_mfma_f32_16x16x32_bf16 v[124:127], v[158:161], v[190:193], v[124:127]
	v_mfma_f32_16x16x32_bf16 v[120:123], v[166:169], v[190:193], v[120:123]
	v_mfma_f32_16x16x32_bf16 v[108:111], v[158:161], v[198:201], v[108:111]
	v_mfma_f32_16x16x32_bf16 v[104:107], v[166:169], v[198:201], v[104:107]
	v_mfma_f32_16x16x32_bf16 v[92:95], v[158:161], v[210:213], v[92:95]
	v_mfma_f32_16x16x32_bf16 v[88:91], v[166:169], v[210:213], v[88:91]
	v_mfma_f32_16x16x32_bf16 v[76:79], v[158:161], v[218:221], v[76:79]
	v_mfma_f32_16x16x32_bf16 v[72:75], v[166:169], v[218:221], v[72:75]
	v_mfma_f32_16x16x32_bf16 v[124:127], v[162:165], v[194:197], v[124:127]
	v_mfma_f32_16x16x32_bf16 v[120:123], v[170:173], v[194:197], v[120:123]
	v_mfma_f32_16x16x32_bf16 v[108:111], v[162:165], v[206:209], v[108:111]
	v_mfma_f32_16x16x32_bf16 v[104:107], v[170:173], v[206:209], v[104:107]
	v_mfma_f32_16x16x32_bf16 v[92:95], v[162:165], v[214:217], v[92:95]
	v_mfma_f32_16x16x32_bf16 v[88:91], v[170:173], v[214:217], v[88:91]
	v_mfma_f32_16x16x32_bf16 v[76:79], v[162:165], v[222:225], v[76:79]
	v_mfma_f32_16x16x32_bf16 v[72:75], v[170:173], v[222:225], v[72:75]
	v_mfma_f32_16x16x32_bf16 v[116:119], v[174:177], v[190:193], v[116:119]
	v_mfma_f32_16x16x32_bf16 v[112:115], v[182:185], v[190:193], v[112:115]
	v_mfma_f32_16x16x32_bf16 v[100:103], v[174:177], v[198:201], v[100:103]
	v_mfma_f32_16x16x32_bf16 v[96:99], v[182:185], v[198:201], v[96:99]
	v_mfma_f32_16x16x32_bf16 v[84:87], v[174:177], v[210:213], v[84:87]
	v_mfma_f32_16x16x32_bf16 v[80:83], v[182:185], v[210:213], v[80:83]
	v_mfma_f32_16x16x32_bf16 v[68:71], v[174:177], v[218:221], v[68:71]
	v_mfma_f32_16x16x32_bf16 v[64:67], v[182:185], v[218:221], v[64:67]
	v_mfma_f32_16x16x32_bf16 v[116:119], v[178:181], v[194:197], v[116:119]
	v_mfma_f32_16x16x32_bf16 v[112:115], v[186:189], v[194:197], v[112:115]
	v_mfma_f32_16x16x32_bf16 v[100:103], v[178:181], v[206:209], v[100:103]
	v_mfma_f32_16x16x32_bf16 v[96:99], v[186:189], v[206:209], v[96:99]
	v_mfma_f32_16x16x32_bf16 v[84:87], v[178:181], v[214:217], v[84:87]
	v_mfma_f32_16x16x32_bf16 v[80:83], v[186:189], v[214:217], v[80:83]
	v_mfma_f32_16x16x32_bf16 v[68:71], v[178:181], v[222:225], v[68:71]
	v_mfma_f32_16x16x32_bf16 v[64:67], v[186:189], v[222:225], v[64:67]
	s_setprio 0
	s_barrier
	ds_read_b128 v[190:193], v154 offset:49152
	ds_read_b128 v[194:197], v154 offset:50176
	ds_read_b128 v[198:201], v154 offset:51200
	ds_read_b128 v[206:209], v154 offset:52224
	ds_read_b128 v[210:213], v154 offset:53248
	ds_read_b128 v[214:217], v154 offset:54272
	ds_read_b128 v[218:221], v154 offset:55296
	ds_read_b128 v[222:225], v154 offset:56320
	s_waitcnt lgkmcnt(0)
	s_setprio 1
	s_barrier
	v_mfma_f32_16x16x32_bf16 v[60:63], v[158:161], v[190:193], v[60:63]
	v_mfma_f32_16x16x32_bf16 v[56:59], v[166:169], v[190:193], v[56:59]
	v_mfma_f32_16x16x32_bf16 v[44:47], v[158:161], v[198:201], v[44:47]
	v_mfma_f32_16x16x32_bf16 v[40:43], v[166:169], v[198:201], v[40:43]
	v_mfma_f32_16x16x32_bf16 v[28:31], v[158:161], v[210:213], v[28:31]
	v_mfma_f32_16x16x32_bf16 v[24:27], v[166:169], v[210:213], v[24:27]
	v_mfma_f32_16x16x32_bf16 v[12:15], v[158:161], v[218:221], v[12:15]
	v_mfma_f32_16x16x32_bf16 v[8:11], v[166:169], v[218:221], v[8:11]
	v_mfma_f32_16x16x32_bf16 v[60:63], v[162:165], v[194:197], v[60:63]
	v_mfma_f32_16x16x32_bf16 v[56:59], v[170:173], v[194:197], v[56:59]
	v_mfma_f32_16x16x32_bf16 v[44:47], v[162:165], v[206:209], v[44:47]
	v_mfma_f32_16x16x32_bf16 v[40:43], v[170:173], v[206:209], v[40:43]
	v_mfma_f32_16x16x32_bf16 v[28:31], v[162:165], v[214:217], v[28:31]
	v_mfma_f32_16x16x32_bf16 v[24:27], v[170:173], v[214:217], v[24:27]
	v_mfma_f32_16x16x32_bf16 v[12:15], v[162:165], v[222:225], v[12:15]
	v_mfma_f32_16x16x32_bf16 v[8:11], v[170:173], v[222:225], v[8:11]
	v_mfma_f32_16x16x32_bf16 v[52:55], v[174:177], v[190:193], v[52:55]
	v_mfma_f32_16x16x32_bf16 v[48:51], v[182:185], v[190:193], v[48:51]
	v_mfma_f32_16x16x32_bf16 v[36:39], v[174:177], v[198:201], v[36:39]
	v_mfma_f32_16x16x32_bf16 v[32:35], v[182:185], v[198:201], v[32:35]
	v_mfma_f32_16x16x32_bf16 v[20:23], v[174:177], v[210:213], v[20:23]
	v_mfma_f32_16x16x32_bf16 v[16:19], v[182:185], v[210:213], v[16:19]
	v_mfma_f32_16x16x32_bf16 v[4:7], v[174:177], v[218:221], v[4:7]
	v_mfma_f32_16x16x32_bf16 v[0:3], v[182:185], v[218:221], v[0:3]
	v_mfma_f32_16x16x32_bf16 v[52:55], v[178:181], v[194:197], v[52:55]
	v_mfma_f32_16x16x32_bf16 v[48:51], v[186:189], v[194:197], v[48:51]
	v_mfma_f32_16x16x32_bf16 v[36:39], v[178:181], v[206:209], v[36:39]
	v_mfma_f32_16x16x32_bf16 v[32:35], v[186:189], v[206:209], v[32:35]
	v_mfma_f32_16x16x32_bf16 v[20:23], v[178:181], v[214:217], v[20:23]
	v_mfma_f32_16x16x32_bf16 v[16:19], v[186:189], v[214:217], v[16:19]
	v_mfma_f32_16x16x32_bf16 v[4:7], v[178:181], v[222:225], v[4:7]
	v_mfma_f32_16x16x32_bf16 v[0:3], v[186:189], v[222:225], v[0:3]
	s_setprio 0
	s_barrier
	s_add_i32 s76, s76, 2
	s_add_u32 s62, s62, 0x100
	s_addc_u32 s63, s63, 0
	s_add_u32 s55, s55, 0x100
	s_addc_u32 s75, s75, 0
.Lkf0_exit:
	s_and_b64 vcc, exec, s[50:51]
	s_cbranch_vccz .LBB0_139
	s_barrier

; #define PG8_STAGE(bufoff, gbase, voff) do { _Pragma("unroll") for (int _i = 0; _i < 2; ++_i) \
;         __builtin_amdgcn_global_load_lds((const unsigned*)((const char*)(gbase) + (voff)[_i]), (PG8_LAS unsigned*)(lds + (bufoff) + ldsw + _i * 8192), 16, 0, 0); } while (0)
; #define PG8_LDA(dst, b, h) do { _Pragma("unroll") for (int m = 0; m < 4; ++m) _Pragma("unroll") for (int k = 0; k < 2; ++k) dst[m][k] = *(const PG8_LAS bf16x8*)(lds + PG8_SA(b, h) + aoff + m * 2048 + k * 1024); } while (0)
; #define PG8_LDB(dst, b, h) do { _Pragma("unroll") for (int n = 0; n < 2; ++n) _Pragma("unroll") for (int k = 0; k < 2; ++k) dst[n][k] = *(const PG8_LAS bf16x8*)(lds + PG8_SB(b, h) + boff + n * 2048 + k * 1024); } while (0)
; #define PG8_MMA(ai, bj, At, Bt) do { __builtin_amdgcn_s_setprio(1); _Pragma("unroll") for (int m = 0; m < 4; ++m) _Pragma("unroll") for (int n = 0; n < 2; ++n) _Pragma("unroll") for (int k = 0; k < 2; ++k) \
;         acc[ai][bj][m][n] = __builtin_amdgcn_mfma_f32_16x16x32_bf16(Bt[n][k], At[m][k], acc[ai][bj][m][n], 0, 0, 0); __builtin_amdgcn_s_setprio(0); } while (0)
; #define PG8_WAIT_V(n) asm volatile("s_waitcnt vmcnt(" #n ")" ::: "memory")
; #define PG8_WAIT_L(n) asm volatile("s_waitcnt lgkmcnt(" #n ")" ::: "memory")
; template <class Epi, class Sched, bool ALIGN_EPI = false, bool SP2 = false>
; __device__ __forceinline__ void gemm_phase(PG8_LAS unsigned char* lds, const Gemm g, const Sched& S, const Epi& E) {
;     ...
;             const bool last = (t == nt - 2);
;             const char* a1 = cA + (size_t)(t + 1) * kstep;
;             const char* a2 = last ? nA : cA + (size_t)(t + 2) * kstep; const char* b2 = last ? nB : cB + (size_t)(t + 2) * kstep;
;             const char* a3 = a2 + kstep; const char* b3 = b2 + kstep;
;             if (last && has_next) S.a_ready(nxt);
;             if constexpr (SP2) {
;             PG8_LDB(B0, 0, 0); PG8_LDB(B1, 0, 1); PG8_SCHED; PG8_LDA(At, 0, 0); PG8_STAGE(PG8_SA(1, 1), a1 + hstep, voffA);
;             PG8_WAIT_V(8); PG8_WAIT_L(0); PG8_BAR; PG8_MMA(0, 0, At, B0); PG8_MMA(0, 1, At, B1); PG8_BAR; PG8_SCHED;
;             PG8_LDA(At, 0, 1); PG8_STAGE(PG8_SB(0, 0), b2, voffB); PG8_STAGE(PG8_SB(0, 1), b2 + hstep, voffB); PG8_STAGE(PG8_SA(0, 0), a2, voffA);
;             PG8_WAIT_V(8); PG8_WAIT_L(0); PG8_BAR; PG8_MMA(1, 0, At, B0); PG8_MMA(1, 1, At, B1); PG8_BAR; PG8_SCHED;
.LBB0_520:
	s_cmp_eq_u32 s63, 12
	s_cbranch_scc0 .Lkf1_norm
	s_cmp_eq_u64 s[6:7], 0
	s_cbranch_scc1 .Lkf1_fin
.Lkf1_norm:
	ds_read_b128 v[146:149], v152
	ds_read_b128 v[156:159], v152 offset:1024
	ds_read_b128 v[160:163], v152 offset:2048
	ds_read_b128 v[164:167], v152 offset:3072
	ds_read_b128 v[168:171], v153
	ds_read_b128 v[172:175], v153 offset:1024
	ds_read_b128 v[176:179], v153 offset:2048
	ds_read_b128 v[180:183], v153 offset:3072
	s_add_u32 s46, s44, 0xfffc0080
	s_addc_u32 s47, s45, -1
	s_cmp_eq_u32 s63, 12
	s_cselect_b32 s49, s35, s47
	s_cselect_b32 s48, s41, s46
	s_cselect_b32 s47, s31, s62
	s_cselect_b32 s46, s60, s61
	s_add_i32 m0, s43, 0xc000
	ds_read_b128 v[184:187], v154
	ds_read_b128 v[188:191], v154 offset:1024
	ds_read_b128 v[192:195], v154 offset:2048
	ds_read_b128 v[196:199], v154 offset:3072
	ds_read_b128 v[200:203], v154 offset:4096
	ds_read_b128 v[206:209], v154 offset:5120
	ds_read_b128 v[210:213], v154 offset:6144
	ds_read_b128 v[214:217], v154 offset:7168
	global_load_lds_dwordx4 v138, s[44:45]
	s_add_i32 m0, s43, 0xe000
	s_nop 0
	global_load_lds_dwordx4 v140, s[44:45]
	s_waitcnt vmcnt(8)
	s_waitcnt lgkmcnt(0)
	s_setprio 1
	s_barrier
	v_mfma_f32_16x16x32_bf16 v[124:127], v[146:149], v[184:187], v[124:127]
	v_mfma_f32_16x16x32_bf16 v[120:123], v[160:163], v[184:187], v[120:123]
	v_mfma_f32_16x16x32_bf16 v[108:111], v[146:149], v[192:195], v[108:111]
	v_mfma_f32_16x16x32_bf16 v[104:107], v[160:163], v[192:195], v[104:107]
	v_mfma_f32_16x16x32_bf16 v[92:95], v[146:149], v[200:203], v[92:95]
	v_mfma_f32_16x16x32_bf16 v[88:91], v[160:163], v[200:203], v[88:91]
	v_mfma_f32_16x16x32_bf16 v[76:79], v[146:149], v[210:213], v[76:79]
	v_mfma_f32_16x16x32_bf16 v[72:75], v[160:163], v[210:213], v[72:75]
	v_mfma_f32_16x16x32_bf16 v[124:127], v[156:159], v[188:191], v[124:127]
	v_mfma_f32_16x16x32_bf16 v[120:123], v[164:167], v[188:191], v[120:123]
	v_mfma_f32_16x16x32_bf16 v[108:111], v[156:159], v[196:199], v[108:111]
	v_mfma_f32_16x16x32_bf16 v[104:107], v[164:167], v[196:199], v[104:107]
	v_mfma_f32_16x16x32_bf16 v[92:95], v[156:159], v[206:209], v[92:95]
	v_mfma_f32_16x16x32_bf16 v[88:91], v[164:167], v[206:209], v[88:91]
	v_mfma_f32_16x16x32_bf16 v[76:79], v[156:159], v[214:217], v[76:79]
	v_mfma_f32_16x16x32_bf16 v[72:75], v[164:167], v[214:217], v[72:75]
	v_mfma_f32_16x16x32_bf16 v[116:119], v[168:171], v[184:187], v[116:119]
	v_mfma_f32_16x16x32_bf16 v[112:115], v[176:179], v[184:187], v[112:115]
	v_mfma_f32_16x16x32_bf16 v[100:103], v[168:171], v[192:195], v[100:103]
	v_mfma_f32_16x16x32_bf16 v[96:99], v[176:179], v[192:195], v[96:99]
	v_mfma_f32_16x16x32_bf16 v[84:87], v[168:171], v[200:203], v[84:87]
	v_mfma_f32_16x16x32_bf16 v[80:83], v[176:179], v[200:203], v[80:83]
	v_mfma_f32_16x16x32_bf16 v[68:71], v[168:171], v[210:213], v[68:71]
	v_mfma_f32_16x16x32_bf16 v[64:67], v[176:179], v[210:213], v[64:67]
	v_mfma_f32_16x16x32_bf16 v[116:119], v[172:175], v[188:191], v[116:119]
	v_mfma_f32_16x16x32_bf16 v[112:115], v[180:183], v[188:191], v[112:115]
	v_mfma_f32_16x16x32_bf16 v[100:103], v[172:175], v[196:199], v[100:103]
	v_mfma_f32_16x16x32_bf16 v[96:99], v[180:183], v[196:199], v[96:99]
	v_mfma_f32_16x16x32_bf16 v[84:87], v[172:175], v[206:209], v[84:87]
	v_mfma_f32_16x16x32_bf16 v[80:83], v[180:183], v[206:209], v[80:83]
	v_mfma_f32_16x16x32_bf16 v[68:71], v[172:175], v[214:217], v[68:71]
	v_mfma_f32_16x16x32_bf16 v[64:67], v[180:183], v[214:217], v[64:67]
	s_setprio 0
	s_barrier
	s_add_i32 s64, s58, s13
	s_mov_b32 m0, s64
	ds_read_b128 v[184:187], v154 offset:16384
	ds_read_b128 v[188:191], v154 offset:17408
	ds_read_b128 v[192:195], v154 offset:18432
	ds_read_b128 v[196:199], v154 offset:19456
	ds_read_b128 v[200:203], v154 offset:20480
	ds_read_b128 v[206:209], v154 offset:21504
	ds_read_b128 v[210:213], v154 offset:22528
	ds_read_b128 v[214:217], v154 offset:23552
	global_load_lds_dwordx4 v132, s[46:47]
	s_add_i32 m0, s64, 0x2000
	s_add_u32 s98, s46, 0x80
	s_addc_u32 s99, s47, 0
	s_add_u32 s64, s46, 0x40000
	s_addc_u32 s65, s47, 0
	s_add_i32 s66, s59, s13
	global_load_lds_dwordx4 v136, s[46:47]
	s_mov_b32 m0, s66
	s_nop 0
	global_load_lds_dwordx4 v132, s[64:65]
	s_add_i32 m0, s66, 0x2000
	s_nop 0
	global_load_lds_dwordx4 v136, s[64:65]
	s_mov_b32 m0, s43
	s_nop 0
	global_load_lds_dwordx4 v130, s[48:49]
	s_mov_b32 m0, s50
	s_nop 0
	global_load_lds_dwordx4 v134, s[48:49]
	s_waitcnt vmcnt(8)
	s_waitcnt lgkmcnt(0)
	s_setprio 1
	s_barrier
	v_mfma_f32_16x16x32_bf16 v[60:63], v[146:149], v[184:187], v[60:63]
	v_mfma_f32_16x16x32_bf16 v[56:59], v[160:163], v[184:187], v[56:59]
	v_mfma_f32_16x16x32_bf16 v[44:47], v[146:149], v[192:195], v[44:47]
	v_mfma_f32_16x16x32_bf16 v[40:43], v[160:163], v[192:195], v[40:43]
	v_mfma_f32_16x16x32_bf16 v[28:31], v[146:149], v[200:203], v[28:31]
	v_mfma_f32_16x16x32_bf16 v[24:27], v[160:163], v[200:203], v[24:27]
	v_mfma_f32_16x16x32_bf16 v[12:15], v[146:149], v[210:213], v[12:15]
	v_mfma_f32_16x16x32_bf16 v[8:11], v[160:163], v[210:213], v[8:11]
	v_mfma_f32_16x16x32_bf16 v[60:63], v[156:159], v[188:191], v[60:63]
	v_mfma_f32_16x16x32_bf16 v[56:59], v[164:167], v[188:191], v[56:59]
	v_mfma_f32_16x16x32_bf16 v[44:47], v[156:159], v[196:199], v[44:47]
	v_mfma_f32_16x16x32_bf16 v[40:43], v[164:167], v[196:199], v[40:43]
	v_mfma_f32_16x16x32_bf16 v[28:31], v[156:159], v[206:209], v[28:31]
	v_mfma_f32_16x16x32_bf16 v[24:27], v[164:167], v[206:209], v[24:27]
	v_mfma_f32_16x16x32_bf16 v[12:15], v[156:159], v[214:217], v[12:15]
	v_mfma_f32_16x16x32_bf16 v[8:11], v[164:167], v[214:217], v[8:11]
	v_mfma_f32_16x16x32_bf16 v[52:55], v[168:171], v[184:187], v[52:55]
	v_mfma_f32_16x16x32_bf16 v[48:51], v[176:179], v[184:187], v[48:51]
	v_mfma_f32_16x16x32_bf16 v[36:39], v[168:171], v[192:195], v[36:39]
	v_mfma_f32_16x16x32_bf16 v[32:35], v[176:179], v[192:195], v[32:35]
	v_mfma_f32_16x16x32_bf16 v[20:23], v[168:171], v[200:203], v[20:23]
	v_mfma_f32_16x16x32_bf16 v[16:19], v[176:179], v[200:203], v[16:19]
	v_mfma_f32_16x16x32_bf16 v[4:7], v[168:171], v[210:213], v[4:7]
	v_mfma_f32_16x16x32_bf16 v[0:3], v[176:179], v[210:213], v[0:3]
	v_mfma_f32_16x16x32_bf16 v[52:55], v[172:175], v[188:191], v[52:55]
	v_mfma_f32_16x16x32_bf16 v[48:51], v[180:183], v[188:191], v[48:51]
	v_mfma_f32_16x16x32_bf16 v[36:39], v[172:175], v[196:199], v[36:39]
	v_mfma_f32_16x16x32_bf16 v[32:35], v[180:183], v[196:199], v[32:35]
	v_mfma_f32_16x16x32_bf16 v[20:23], v[172:175], v[206:209], v[20:23]
	v_mfma_f32_16x16x32_bf16 v[16:19], v[180:183], v[206:209], v[16:19]
	v_mfma_f32_16x16x32_bf16 v[4:7], v[172:175], v[214:217], v[4:7]
	v_mfma_f32_16x16x32_bf16 v[0:3], v[180:183], v[214:217], v[0:3]
	s_setprio 0
	s_barrier
; #define PG8_STAGE(bufoff, gbase, voff) do { _Pragma("unroll") for (int _i = 0; _i < 2; ++_i) \
;         __builtin_amdgcn_global_load_lds((const unsigned*)((const char*)(gbase) + (voff)[_i]), (PG8_LAS unsigned*)(lds + (bufoff) + ldsw + _i * 8192), 16, 0, 0); } while (0)
; #define PG8_LDA(dst, b, h) do { _Pragma("unroll") for (int m = 0; m < 4; ++m) _Pragma("unroll") for (int k = 0; k < 2; ++k) dst[m][k] = *(const PG8_LAS bf16x8*)(lds + PG8_SA(b, h) + aoff + m * 2048 + k * 1024); } while (0)
; #define PG8_LDB(dst, b, h) do { _Pragma("unroll") for (int n = 0; n < 2; ++n) _Pragma("unroll") for (int k = 0; k < 2; ++k) dst[n][k] = *(const PG8_LAS bf16x8*)(lds + PG8_SB(b, h) + boff + n * 2048 + k * 1024); } while (0)
; #define PG8_MMA(ai, bj, At, Bt) do { __builtin_amdgcn_s_setprio(1); _Pragma("unroll") for (int m = 0; m < 4; ++m) _Pragma("unroll") for (int n = 0; n < 2; ++n) _Pragma("unroll") for (int k = 0; k < 2; ++k) \
;         acc[ai][bj][m][n] = __builtin_amdgcn_mfma_f32_16x16x32_bf16(Bt[n][k], At[m][k], acc[ai][bj][m][n], 0, 0, 0); __builtin_amdgcn_s_setprio(0); } while (0)
; #define PG8_WAIT_V(n) asm volatile("s_waitcnt vmcnt(" #n ")" ::: "memory")
; #define PG8_WAIT_L(n) asm volatile("s_waitcnt lgkmcnt(" #n ")" ::: "memory")
; #define PG8_BAR __builtin_amdgcn_s_barrier()
; #define PG8_SCHED __builtin_amdgcn_sched_barrier(0)
; template <class Epi, class Sched, bool ALIGN_EPI = false, bool SP2 = false>
; __device__ __forceinline__ void gemm_phase(PG8_LAS unsigned char* lds, const Gemm g, const Sched& S, const Epi& E) {
;     ...
;             PG8_LDB(B0, 1, 0); PG8_LDB(B1, 1, 1); PG8_SCHED; PG8_LDA(At, 1, 0); PG8_STAGE(PG8_SA(0, 1), a2 + hstep, voffA);
;             PG8_WAIT_V(8); PG8_WAIT_L(0); PG8_BAR; PG8_MMA(0, 0, At, B0); PG8_MMA(0, 1, At, B1); PG8_BAR; PG8_SCHED;
;             PG8_LDA(At, 1, 1); PG8_STAGE(PG8_SB(1, 0), b3, voffB); PG8_STAGE(PG8_SB(1, 1), b3 + hstep, voffB); PG8_STAGE(PG8_SA(1, 0), a3, voffA);
;             PG8_WAIT_V(8); PG8_WAIT_L(0); PG8_BAR; PG8_MMA(1, 0, At, B0); PG8_MMA(1, 1, At, B1); PG8_BAR; PG8_SCHED;
	s_add_i32 s64, 0, 0x18000
	s_add_i32 s65, 0, 0x1c000
	ds_read_b128 v[146:149], v240
	ds_read_b128 v[156:159], v240 offset:1024
	ds_read_b128 v[160:163], v240 offset:2048
	ds_read_b128 v[164:167], v240 offset:3072
	ds_read_b128 v[168:171], v241
	ds_read_b128 v[172:175], v241 offset:1024
	ds_read_b128 v[176:179], v241 offset:2048
	ds_read_b128 v[180:183], v241 offset:3072
	s_add_u32 s100, s48, 0x80
	s_addc_u32 s101, s49, 0
	s_add_u32 s48, s48, 0x40000
	s_addc_u32 s49, s49, 0
	s_mov_b32 m0, s51
	ds_read_b128 v[184:187], v154 offset:32768
	ds_read_b128 v[188:191], v154 offset:33792
	ds_read_b128 v[192:195], v154 offset:34816
	ds_read_b128 v[196:199], v154 offset:35840
	ds_read_b128 v[200:203], v154 offset:36864
	ds_read_b128 v[206:209], v154 offset:37888
	ds_read_b128 v[210:213], v154 offset:38912
	ds_read_b128 v[214:217], v154 offset:39936
	global_load_lds_dwordx4 v130, s[48:49]
	s_mov_b32 m0, s52
	s_nop 0
	global_load_lds_dwordx4 v134, s[48:49]
	s_waitcnt vmcnt(8)
	s_waitcnt lgkmcnt(0)
	s_setprio 1
	s_barrier
	v_mfma_f32_16x16x32_bf16 v[124:127], v[146:149], v[184:187], v[124:127]
	v_mfma_f32_16x16x32_bf16 v[120:123], v[160:163], v[184:187], v[120:123]
	v_mfma_f32_16x16x32_bf16 v[108:111], v[146:149], v[192:195], v[108:111]
	v_mfma_f32_16x16x32_bf16 v[104:107], v[160:163], v[192:195], v[104:107]
	v_mfma_f32_16x16x32_bf16 v[92:95], v[146:149], v[200:203], v[92:95]
	v_mfma_f32_16x16x32_bf16 v[88:91], v[160:163], v[200:203], v[88:91]
	v_mfma_f32_16x16x32_bf16 v[76:79], v[146:149], v[210:213], v[76:79]
	v_mfma_f32_16x16x32_bf16 v[72:75], v[160:163], v[210:213], v[72:75]
	v_mfma_f32_16x16x32_bf16 v[124:127], v[156:159], v[188:191], v[124:127]
	v_mfma_f32_16x16x32_bf16 v[120:123], v[164:167], v[188:191], v[120:123]
	v_mfma_f32_16x16x32_bf16 v[108:111], v[156:159], v[196:199], v[108:111]
	v_mfma_f32_16x16x32_bf16 v[104:107], v[164:167], v[196:199], v[104:107]
	v_mfma_f32_16x16x32_bf16 v[92:95], v[156:159], v[206:209], v[92:95]
	v_mfma_f32_16x16x32_bf16 v[88:91], v[164:167], v[206:209], v[88:91]
	v_mfma_f32_16x16x32_bf16 v[76:79], v[156:159], v[214:217], v[76:79]
	v_mfma_f32_16x16x32_bf16 v[72:75], v[164:167], v[214:217], v[72:75]
	v_mfma_f32_16x16x32_bf16 v[116:119], v[168:171], v[184:187], v[116:119]
	v_mfma_f32_16x16x32_bf16 v[112:115], v[176:179], v[184:187], v[112:115]
	v_mfma_f32_16x16x32_bf16 v[100:103], v[168:171], v[192:195], v[100:103]
	v_mfma_f32_16x16x32_bf16 v[96:99], v[176:179], v[192:195], v[96:99]
	v_mfma_f32_16x16x32_bf16 v[84:87], v[168:171], v[200:203], v[84:87]
	v_mfma_f32_16x16x32_bf16 v[80:83], v[176:179], v[200:203], v[80:83]
	v_mfma_f32_16x16x32_bf16 v[68:71], v[168:171], v[210:213], v[68:71]
	v_mfma_f32_16x16x32_bf16 v[64:67], v[176:179], v[210:213], v[64:67]
	v_mfma_f32_16x16x32_bf16 v[116:119], v[172:175], v[188:191], v[116:119]
	v_mfma_f32_16x16x32_bf16 v[112:115], v[180:183], v[188:191], v[112:115]
	v_mfma_f32_16x16x32_bf16 v[100:103], v[172:175], v[196:199], v[100:103]
	v_mfma_f32_16x16x32_bf16 v[96:99], v[180:183], v[196:199], v[96:99]
	v_mfma_f32_16x16x32_bf16 v[84:87], v[172:175], v[206:209], v[84:87]
	v_mfma_f32_16x16x32_bf16 v[80:83], v[180:183], v[206:209], v[80:83]
	v_mfma_f32_16x16x32_bf16 v[68:71], v[172:175], v[214:217], v[68:71]
	v_mfma_f32_16x16x32_bf16 v[64:67], v[180:183], v[214:217], v[64:67]
	s_setprio 0
	s_barrier
	s_add_i32 s48, s64, s13
	s_mov_b32 m0, s48
	ds_read_b128 v[184:187], v154 offset:49152
	ds_read_b128 v[188:191], v154 offset:50176
	ds_read_b128 v[192:195], v154 offset:51200
	ds_read_b128 v[196:199], v154 offset:52224
	ds_read_b128 v[200:203], v154 offset:53248
	ds_read_b128 v[206:209], v154 offset:54272
	ds_read_b128 v[210:213], v154 offset:55296
	ds_read_b128 v[214:217], v154 offset:56320
	global_load_lds_dwordx4 v132, s[98:99]
	s_add_i32 m0, s48, 0x2000
	s_add_u32 s46, s46, 0x40080
	s_addc_u32 s47, s47, 0
	s_add_i32 s48, s65, s13
	global_load_lds_dwordx4 v136, s[98:99]
	s_mov_b32 m0, s48
	s_nop 0
	global_load_lds_dwordx4 v132, s[46:47]
	s_add_i32 m0, s48, 0x2000
	s_nop 0
	global_load_lds_dwordx4 v136, s[46:47]
	s_mov_b32 m0, s54
	s_nop 0
	global_load_lds_dwordx4 v130, s[100:101]
	s_mov_b32 m0, s55
	s_nop 0
	global_load_lds_dwordx4 v134, s[100:101]
	s_waitcnt vmcnt(8)
	s_waitcnt lgkmcnt(0)
	s_setprio 1
	s_barrier
	v_mfma_f32_16x16x32_bf16 v[60:63], v[146:149], v[184:187], v[60:63]
	v_mfma_f32_16x16x32_bf16 v[56:59], v[160:163], v[184:187], v[56:59]
	v_mfma_f32_16x16x32_bf16 v[44:47], v[146:149], v[192:195], v[44:47]
	v_mfma_f32_16x16x32_bf16 v[40:43], v[160:163], v[192:195], v[40:43]
	v_mfma_f32_16x16x32_bf16 v[28:31], v[146:149], v[200:203], v[28:31]
	v_mfma_f32_16x16x32_bf16 v[24:27], v[160:163], v[200:203], v[24:27]
	v_mfma_f32_16x16x32_bf16 v[12:15], v[146:149], v[210:213], v[12:15]
	v_mfma_f32_16x16x32_bf16 v[8:11], v[160:163], v[210:213], v[8:11]
	v_mfma_f32_16x16x32_bf16 v[60:63], v[156:159], v[188:191], v[60:63]
	v_mfma_f32_16x16x32_bf16 v[56:59], v[164:167], v[188:191], v[56:59]
	v_mfma_f32_16x16x32_bf16 v[44:47], v[156:159], v[196:199], v[44:47]
	v_mfma_f32_16x16x32_bf16 v[40:43], v[164:167], v[196:199], v[40:43]
	v_mfma_f32_16x16x32_bf16 v[28:31], v[156:159], v[206:209], v[28:31]
	v_mfma_f32_16x16x32_bf16 v[24:27], v[164:167], v[206:209], v[24:27]
	v_mfma_f32_16x16x32_bf16 v[12:15], v[156:159], v[214:217], v[12:15]
	v_mfma_f32_16x16x32_bf16 v[8:11], v[164:167], v[214:217], v[8:11]
	v_mfma_f32_16x16x32_bf16 v[52:55], v[168:171], v[184:187], v[52:55]
	v_mfma_f32_16x16x32_bf16 v[48:51], v[176:179], v[184:187], v[48:51]
	v_mfma_f32_16x16x32_bf16 v[36:39], v[168:171], v[192:195], v[36:39]
	v_mfma_f32_16x16x32_bf16 v[32:35], v[176:179], v[192:195], v[32:35]
	v_mfma_f32_16x16x32_bf16 v[20:23], v[168:171], v[200:203], v[20:23]
	v_mfma_f32_16x16x32_bf16 v[16:19], v[176:179], v[200:203], v[16:19]
	v_mfma_f32_16x16x32_bf16 v[4:7], v[168:171], v[210:213], v[4:7]
	v_mfma_f32_16x16x32_bf16 v[0:3], v[176:179], v[210:213], v[0:3]
	v_mfma_f32_16x16x32_bf16 v[52:55], v[172:175], v[188:191], v[52:55]
	v_mfma_f32_16x16x32_bf16 v[48:51], v[180:183], v[188:191], v[48:51]
	v_mfma_f32_16x16x32_bf16 v[36:39], v[172:175], v[196:199], v[36:39]
	v_mfma_f32_16x16x32_bf16 v[32:35], v[180:183], v[196:199], v[32:35]
	v_mfma_f32_16x16x32_bf16 v[20:23], v[172:175], v[206:209], v[20:23]
	v_mfma_f32_16x16x32_bf16 v[16:19], v[180:183], v[206:209], v[16:19]
	v_mfma_f32_16x16x32_bf16 v[4:7], v[172:175], v[214:217], v[4:7]
	v_mfma_f32_16x16x32_bf16 v[0:3], v[180:183], v[214:217], v[0:3]
	s_setprio 0
	s_barrier
	s_add_i32 s63, s63, 2
	s_add_u32 s44, s44, 0x100
	s_addc_u32 s45, s45, 0
	s_add_u32 s61, s61, 0x100
	s_addc_u32 s62, s62, 0
	s_cmp_gt_u32 s63, 13
	s_cbranch_scc0 .LBB0_520
	s_branch .Lkf1_exit
; #define PG8_STAGE(bufoff, gbase, voff) do { _Pragma("unroll") for (int _i = 0; _i < 2; ++_i) \
;         __builtin_amdgcn_global_load_lds((const unsigned*)((const char*)(gbase) + (voff)[_i]), (PG8_LAS unsigned*)(lds + (bufoff) + ldsw + _i * 8192), 16, 0, 0); } while (0)
; #define PG8_LDA(dst, b, h) do { _Pragma("unroll") for (int m = 0; m < 4; ++m) _Pragma("unroll") for (int k = 0; k < 2; ++k) dst[m][k] = *(const PG8_LAS bf16x8*)(lds + PG8_SA(b, h) + aoff + m * 2048 + k * 1024); } while (0)
; #define PG8_LDB(dst, b, h) do { _Pragma("unroll") for (int n = 0; n < 2; ++n) _Pragma("unroll") for (int k = 0; k < 2; ++k) dst[n][k] = *(const PG8_LAS bf16x8*)(lds + PG8_SB(b, h) + boff + n * 2048 + k * 1024); } while (0)
; #define PG8_MMA(ai, bj, At, Bt) do { __builtin_amdgcn_s_setprio(1); _Pragma("unroll") for (int m = 0; m < 4; ++m) _Pragma("unroll") for (int n = 0; n < 2; ++n) _Pragma("unroll") for (int k = 0; k < 2; ++k) \
;         acc[ai][bj][m][n] = __builtin_amdgcn_mfma_f32_16x16x32_bf16(Bt[n][k], At[m][k], acc[ai][bj][m][n], 0, 0, 0); __builtin_amdgcn_s_setprio(0); } while (0)
; #define PG8_WAIT_V(n) asm volatile("s_waitcnt vmcnt(" #n ")" ::: "memory")
; #define PG8_WAIT_L(n) asm volatile("s_waitcnt lgkmcnt(" #n ")" ::: "memory")
; #define PG8_BAR __builtin_amdgcn_s_barrier()
; #define PG8_SCHED __builtin_amdgcn_sched_barrier(0)
; template <class Epi, class Sched, bool ALIGN_EPI = false, bool SP2 = false>
; __device__ __forceinline__ void gemm_phase(PG8_LAS unsigned char* lds, const Gemm g, const Sched& S, const Epi& E) {
;     ...
;             PG8_LDB(B0, 0, 0); PG8_LDB(B1, 0, 1); PG8_SCHED; PG8_LDA(At, 0, 0); PG8_STAGE(PG8_SA(1, 1), a1 + hstep, voffA);
;             PG8_WAIT_V(8); PG8_WAIT_L(0); PG8_BAR; PG8_MMA(0, 0, At, B0); PG8_MMA(0, 1, At, B1); PG8_BAR; PG8_SCHED;
;             PG8_LDA(At, 0, 1); PG8_STAGE(PG8_SB(0, 0), b2, voffB); PG8_STAGE(PG8_SB(0, 1), b2 + hstep, voffB); PG8_STAGE(PG8_SA(0, 0), a2, voffA);
;             PG8_WAIT_V(8); PG8_WAIT_L(0); PG8_BAR; PG8_MMA(1, 0, At, B0); PG8_MMA(1, 1, At, B1); PG8_BAR; PG8_SCHED;
.Lkf1_fin:
	ds_read_b128 v[146:149], v152
	ds_read_b128 v[156:159], v152 offset:1024
	ds_read_b128 v[160:163], v152 offset:2048
	ds_read_b128 v[164:167], v152 offset:3072
	ds_read_b128 v[168:171], v153
	ds_read_b128 v[172:175], v153 offset:1024
	ds_read_b128 v[176:179], v153 offset:2048
	ds_read_b128 v[180:183], v153 offset:3072
	s_add_u32 s46, s44, 0xfffc0080
	s_addc_u32 s47, s45, -1
	s_cmp_eq_u32 s63, 12
	s_cselect_b32 s49, s35, s47
	s_cselect_b32 s48, s41, s46
	s_cselect_b32 s47, s31, s62
	s_cselect_b32 s46, s60, s61
	s_add_i32 m0, s43, 0xc000
	ds_read_b128 v[184:187], v154
	ds_read_b128 v[188:191], v154 offset:1024
	ds_read_b128 v[192:195], v154 offset:2048
	ds_read_b128 v[196:199], v154 offset:3072
	ds_read_b128 v[200:203], v154 offset:4096
	ds_read_b128 v[206:209], v154 offset:5120
	ds_read_b128 v[210:213], v154 offset:6144
	ds_read_b128 v[214:217], v154 offset:7168
	global_load_lds_dwordx4 v138, s[44:45]
	s_add_i32 m0, s43, 0xe000
	s_nop 0
	global_load_lds_dwordx4 v140, s[44:45]
	s_waitcnt vmcnt(8)
	s_waitcnt lgkmcnt(0)
	s_setprio 1
	s_barrier
	v_mfma_f32_16x16x32_bf16 v[124:127], v[146:149], v[184:187], v[124:127]
	v_mfma_f32_16x16x32_bf16 v[120:123], v[160:163], v[184:187], v[120:123]
	v_mfma_f32_16x16x32_bf16 v[108:111], v[146:149], v[192:195], v[108:111]
	v_mfma_f32_16x16x32_bf16 v[104:107], v[160:163], v[192:195], v[104:107]
	v_mfma_f32_16x16x32_bf16 v[92:95], v[146:149], v[200:203], v[92:95]
	v_mfma_f32_16x16x32_bf16 v[88:91], v[160:163], v[200:203], v[88:91]
	v_mfma_f32_16x16x32_bf16 v[76:79], v[146:149], v[210:213], v[76:79]
	v_mfma_f32_16x16x32_bf16 v[72:75], v[160:163], v[210:213], v[72:75]
	v_mfma_f32_16x16x32_bf16 v[124:127], v[156:159], v[188:191], v[124:127]
	v_mfma_f32_16x16x32_bf16 v[120:123], v[164:167], v[188:191], v[120:123]
	v_mfma_f32_16x16x32_bf16 v[108:111], v[156:159], v[196:199], v[108:111]
	v_mfma_f32_16x16x32_bf16 v[104:107], v[164:167], v[196:199], v[104:107]
	v_mfma_f32_16x16x32_bf16 v[92:95], v[156:159], v[206:209], v[92:95]
	v_mfma_f32_16x16x32_bf16 v[88:91], v[164:167], v[206:209], v[88:91]
	v_mfma_f32_16x16x32_bf16 v[76:79], v[156:159], v[214:217], v[76:79]
	v_mfma_f32_16x16x32_bf16 v[72:75], v[164:167], v[214:217], v[72:75]
	v_mfma_f32_16x16x32_bf16 v[116:119], v[168:171], v[184:187], v[116:119]
	v_mfma_f32_16x16x32_bf16 v[112:115], v[176:179], v[184:187], v[112:115]
	v_mfma_f32_16x16x32_bf16 v[100:103], v[168:171], v[192:195], v[100:103]
	v_mfma_f32_16x16x32_bf16 v[96:99], v[176:179], v[192:195], v[96:99]
	v_mfma_f32_16x16x32_bf16 v[84:87], v[168:171], v[200:203], v[84:87]
	v_mfma_f32_16x16x32_bf16 v[80:83], v[176:179], v[200:203], v[80:83]
	v_mfma_f32_16x16x32_bf16 v[68:71], v[168:171], v[210:213], v[68:71]
	v_mfma_f32_16x16x32_bf16 v[64:67], v[176:179], v[210:213], v[64:67]
	v_mfma_f32_16x16x32_bf16 v[116:119], v[172:175], v[188:191], v[116:119]
	v_mfma_f32_16x16x32_bf16 v[112:115], v[180:183], v[188:191], v[112:115]
	v_mfma_f32_16x16x32_bf16 v[100:103], v[172:175], v[196:199], v[100:103]
	v_mfma_f32_16x16x32_bf16 v[96:99], v[180:183], v[196:199], v[96:99]
	v_mfma_f32_16x16x32_bf16 v[84:87], v[172:175], v[206:209], v[84:87]
	v_mfma_f32_16x16x32_bf16 v[80:83], v[180:183], v[206:209], v[80:83]
	v_mfma_f32_16x16x32_bf16 v[68:71], v[172:175], v[214:217], v[68:71]
	v_mfma_f32_16x16x32_bf16 v[64:67], v[180:183], v[214:217], v[64:67]
	s_setprio 0
	s_barrier
	s_add_i32 s64, s58, s13
	s_mov_b32 m0, s64
	ds_read_b128 v[184:187], v154 offset:16384
	ds_read_b128 v[188:191], v154 offset:17408
	ds_read_b128 v[192:195], v154 offset:18432
	ds_read_b128 v[196:199], v154 offset:19456
	ds_read_b128 v[200:203], v154 offset:20480
	ds_read_b128 v[206:209], v154 offset:21504
	ds_read_b128 v[210:213], v154 offset:22528
	ds_read_b128 v[214:217], v154 offset:23552
	s_waitcnt vmcnt(2)
	s_waitcnt lgkmcnt(0)
	s_setprio 1
	s_barrier
	v_mfma_f32_16x16x32_bf16 v[60:63], v[146:149], v[184:187], v[60:63]
	v_mfma_f32_16x16x32_bf16 v[56:59], v[160:163], v[184:187], v[56:59]
	v_mfma_f32_16x16x32_bf16 v[44:47], v[146:149], v[192:195], v[44:47]
	v_mfma_f32_16x16x32_bf16 v[40:43], v[160:163], v[192:195], v[40:43]
	v_mfma_f32_16x16x32_bf16 v[28:31], v[146:149], v[200:203], v[28:31]
	v_mfma_f32_16x16x32_bf16 v[24:27], v[160:163], v[200:203], v[24:27]
	v_mfma_f32_16x16x32_bf16 v[12:15], v[146:149], v[210:213], v[12:15]
	v_mfma_f32_16x16x32_bf16 v[8:11], v[160:163], v[210:213], v[8:11]
	v_mfma_f32_16x16x32_bf16 v[60:63], v[156:159], v[188:191], v[60:63]
	v_mfma_f32_16x16x32_bf16 v[56:59], v[164:167], v[188:191], v[56:59]
	v_mfma_f32_16x16x32_bf16 v[44:47], v[156:159], v[196:199], v[44:47]
	v_mfma_f32_16x16x32_bf16 v[40:43], v[164:167], v[196:199], v[40:43]
	v_mfma_f32_16x16x32_bf16 v[28:31], v[156:159], v[206:209], v[28:31]
	v_mfma_f32_16x16x32_bf16 v[24:27], v[164:167], v[206:209], v[24:27]
	v_mfma_f32_16x16x32_bf16 v[12:15], v[156:159], v[214:217], v[12:15]
	v_mfma_f32_16x16x32_bf16 v[8:11], v[164:167], v[214:217], v[8:11]
	v_mfma_f32_16x16x32_bf16 v[52:55], v[168:171], v[184:187], v[52:55]
	v_mfma_f32_16x16x32_bf16 v[48:51], v[176:179], v[184:187], v[48:51]
	v_mfma_f32_16x16x32_bf16 v[36:39], v[168:171], v[192:195], v[36:39]
	v_mfma_f32_16x16x32_bf16 v[32:35], v[176:179], v[192:195], v[32:35]
	v_mfma_f32_16x16x32_bf16 v[20:23], v[168:171], v[200:203], v[20:23]
	v_mfma_f32_16x16x32_bf16 v[16:19], v[176:179], v[200:203], v[16:19]
	v_mfma_f32_16x16x32_bf16 v[4:7], v[168:171], v[210:213], v[4:7]
	v_mfma_f32_16x16x32_bf16 v[0:3], v[176:179], v[210:213], v[0:3]
	v_mfma_f32_16x16x32_bf16 v[52:55], v[172:175], v[188:191], v[52:55]
	v_mfma_f32_16x16x32_bf16 v[48:51], v[180:183], v[188:191], v[48:51]
	v_mfma_f32_16x16x32_bf16 v[36:39], v[172:175], v[196:199], v[36:39]
	v_mfma_f32_16x16x32_bf16 v[32:35], v[180:183], v[196:199], v[32:35]
	v_mfma_f32_16x16x32_bf16 v[20:23], v[172:175], v[206:209], v[20:23]
	v_mfma_f32_16x16x32_bf16 v[16:19], v[180:183], v[206:209], v[16:19]
	v_mfma_f32_16x16x32_bf16 v[4:7], v[172:175], v[214:217], v[4:7]
	v_mfma_f32_16x16x32_bf16 v[0:3], v[180:183], v[214:217], v[0:3]
	s_setprio 0
	s_barrier
; #define PG8_STAGE(bufoff, gbase, voff) do { _Pragma("unroll") for (int _i = 0; _i < 2; ++_i) \
;         __builtin_amdgcn_global_load_lds((const unsigned*)((const char*)(gbase) + (voff)[_i]), (PG8_LAS unsigned*)(lds + (bufoff) + ldsw + _i * 8192), 16, 0, 0); } while (0)
; #define PG8_LDA(dst, b, h) do { _Pragma("unroll") for (int m = 0; m < 4; ++m) _Pragma("unroll") for (int k = 0; k < 2; ++k) dst[m][k] = *(const PG8_LAS bf16x8*)(lds + PG8_SA(b, h) + aoff + m * 2048 + k * 1024); } while (0)
; #define PG8_LDB(dst, b, h) do { _Pragma("unroll") for (int n = 0; n < 2; ++n) _Pragma("unroll") for (int k = 0; k < 2; ++k) dst[n][k] = *(const PG8_LAS bf16x8*)(lds + PG8_SB(b, h) + boff + n * 2048 + k * 1024); } while (0)
; #define PG8_MMA(ai, bj, At, Bt) do { __builtin_amdgcn_s_setprio(1); _Pragma("unroll") for (int m = 0; m < 4; ++m) _Pragma("unroll") for (int n = 0; n < 2; ++n) _Pragma("unroll") for (int k = 0; k < 2; ++k) \
;         acc[ai][bj][m][n] = __builtin_amdgcn_mfma_f32_16x16x32_bf16(Bt[n][k], At[m][k], acc[ai][bj][m][n], 0, 0, 0); __builtin_amdgcn_s_setprio(0); } while (0)
; #define PG8_WAIT_V(n) asm volatile("s_waitcnt vmcnt(" #n ")" ::: "memory")
; #define PG8_WAIT_L(n) asm volatile("s_waitcnt lgkmcnt(" #n ")" ::: "memory")
; #define PG8_BAR __builtin_amdgcn_s_barrier()
; #define PG8_SCHED __builtin_amdgcn_sched_barrier(0)
; template <class Epi, class Sched, bool ALIGN_EPI = false, bool SP2 = false>
; __device__ __forceinline__ void gemm_phase(PG8_LAS unsigned char* lds, const Gemm g, const Sched& S, const Epi& E) {
;     ...
;             PG8_LDB(B0, 1, 0); PG8_LDB(B1, 1, 1); PG8_SCHED; PG8_LDA(At, 1, 0); PG8_STAGE(PG8_SA(0, 1), a2 + hstep, voffA);
;             PG8_WAIT_V(8); PG8_WAIT_L(0); PG8_BAR; PG8_MMA(0, 0, At, B0); PG8_MMA(0, 1, At, B1); PG8_BAR; PG8_SCHED;
;             PG8_LDA(At, 1, 1); PG8_STAGE(PG8_SB(1, 0), b3, voffB); PG8_STAGE(PG8_SB(1, 1), b3 + hstep, voffB); PG8_STAGE(PG8_SA(1, 0), a3, voffA);
;             PG8_WAIT_V(8); PG8_WAIT_L(0); PG8_BAR; PG8_MMA(1, 0, At, B0); PG8_MMA(1, 1, At, B1); PG8_BAR; PG8_SCHED;
;     ...
;         if constexpr (ALIGN_EPI) { if (wr == 0) PG8_BAR; }
	s_add_i32 s64, 0, 0x18000
	s_add_i32 s65, 0, 0x1c000
	ds_read_b128 v[146:149], v240
	ds_read_b128 v[156:159], v240 offset:1024
	ds_read_b128 v[160:163], v240 offset:2048
	ds_read_b128 v[164:167], v240 offset:3072
	ds_read_b128 v[168:171], v241
	ds_read_b128 v[172:175], v241 offset:1024
	ds_read_b128 v[176:179], v241 offset:2048
	ds_read_b128 v[180:183], v241 offset:3072
	ds_read_b128 v[184:187], v154 offset:32768
	ds_read_b128 v[188:191], v154 offset:33792
	ds_read_b128 v[192:195], v154 offset:34816
	ds_read_b128 v[196:199], v154 offset:35840
	ds_read_b128 v[200:203], v154 offset:36864
	ds_read_b128 v[206:209], v154 offset:37888
	ds_read_b128 v[210:213], v154 offset:38912
	ds_read_b128 v[214:217], v154 offset:39936
	s_waitcnt vmcnt(0)
	s_waitcnt lgkmcnt(0)
	s_setprio 1
	s_barrier
	v_mfma_f32_16x16x32_bf16 v[124:127], v[146:149], v[184:187], v[124:127]
	v_mfma_f32_16x16x32_bf16 v[120:123], v[160:163], v[184:187], v[120:123]
	v_mfma_f32_16x16x32_bf16 v[108:111], v[146:149], v[192:195], v[108:111]
	v_mfma_f32_16x16x32_bf16 v[104:107], v[160:163], v[192:195], v[104:107]
	v_mfma_f32_16x16x32_bf16 v[92:95], v[146:149], v[200:203], v[92:95]
	v_mfma_f32_16x16x32_bf16 v[88:91], v[160:163], v[200:203], v[88:91]
	v_mfma_f32_16x16x32_bf16 v[76:79], v[146:149], v[210:213], v[76:79]
	v_mfma_f32_16x16x32_bf16 v[72:75], v[160:163], v[210:213], v[72:75]
	v_mfma_f32_16x16x32_bf16 v[124:127], v[156:159], v[188:191], v[124:127]
	v_mfma_f32_16x16x32_bf16 v[120:123], v[164:167], v[188:191], v[120:123]
	v_mfma_f32_16x16x32_bf16 v[108:111], v[156:159], v[196:199], v[108:111]
	v_mfma_f32_16x16x32_bf16 v[104:107], v[164:167], v[196:199], v[104:107]
	v_mfma_f32_16x16x32_bf16 v[92:95], v[156:159], v[206:209], v[92:95]
	v_mfma_f32_16x16x32_bf16 v[88:91], v[164:167], v[206:209], v[88:91]
	v_mfma_f32_16x16x32_bf16 v[76:79], v[156:159], v[214:217], v[76:79]
	v_mfma_f32_16x16x32_bf16 v[72:75], v[164:167], v[214:217], v[72:75]
	v_mfma_f32_16x16x32_bf16 v[116:119], v[168:171], v[184:187], v[116:119]
	v_mfma_f32_16x16x32_bf16 v[112:115], v[176:179], v[184:187], v[112:115]
	v_mfma_f32_16x16x32_bf16 v[100:103], v[168:171], v[192:195], v[100:103]
	v_mfma_f32_16x16x32_bf16 v[96:99], v[176:179], v[192:195], v[96:99]
	v_mfma_f32_16x16x32_bf16 v[84:87], v[168:171], v[200:203], v[84:87]
	v_mfma_f32_16x16x32_bf16 v[80:83], v[176:179], v[200:203], v[80:83]
	v_mfma_f32_16x16x32_bf16 v[68:71], v[168:171], v[210:213], v[68:71]
	v_mfma_f32_16x16x32_bf16 v[64:67], v[176:179], v[210:213], v[64:67]
	v_mfma_f32_16x16x32_bf16 v[116:119], v[172:175], v[188:191], v[116:119]
	v_mfma_f32_16x16x32_bf16 v[112:115], v[180:183], v[188:191], v[112:115]
	v_mfma_f32_16x16x32_bf16 v[100:103], v[172:175], v[196:199], v[100:103]
	v_mfma_f32_16x16x32_bf16 v[96:99], v[180:183], v[196:199], v[96:99]
	v_mfma_f32_16x16x32_bf16 v[84:87], v[172:175], v[206:209], v[84:87]
	v_mfma_f32_16x16x32_bf16 v[80:83], v[180:183], v[206:209], v[80:83]
	v_mfma_f32_16x16x32_bf16 v[68:71], v[172:175], v[214:217], v[68:71]
	v_mfma_f32_16x16x32_bf16 v[64:67], v[180:183], v[214:217], v[64:67]
	s_setprio 0
	s_barrier
	ds_read_b128 v[184:187], v154 offset:49152
	ds_read_b128 v[188:191], v154 offset:50176
	ds_read_b128 v[192:195], v154 offset:51200
	ds_read_b128 v[196:199], v154 offset:52224
	ds_read_b128 v[200:203], v154 offset:53248
	ds_read_b128 v[206:209], v154 offset:54272
	ds_read_b128 v[210:213], v154 offset:55296
	ds_read_b128 v[214:217], v154 offset:56320
	s_waitcnt lgkmcnt(0)
	s_setprio 1
	s_barrier
	v_mfma_f32_16x16x32_bf16 v[60:63], v[146:149], v[184:187], v[60:63]
	v_mfma_f32_16x16x32_bf16 v[56:59], v[160:163], v[184:187], v[56:59]
	v_mfma_f32_16x16x32_bf16 v[44:47], v[146:149], v[192:195], v[44:47]
	v_mfma_f32_16x16x32_bf16 v[40:43], v[160:163], v[192:195], v[40:43]
	v_mfma_f32_16x16x32_bf16 v[28:31], v[146:149], v[200:203], v[28:31]
	v_mfma_f32_16x16x32_bf16 v[24:27], v[160:163], v[200:203], v[24:27]
	v_mfma_f32_16x16x32_bf16 v[12:15], v[146:149], v[210:213], v[12:15]
	v_mfma_f32_16x16x32_bf16 v[8:11], v[160:163], v[210:213], v[8:11]
	v_mfma_f32_16x16x32_bf16 v[60:63], v[156:159], v[188:191], v[60:63]
	v_mfma_f32_16x16x32_bf16 v[56:59], v[164:167], v[188:191], v[56:59]
	v_mfma_f32_16x16x32_bf16 v[44:47], v[156:159], v[196:199], v[44:47]
	v_mfma_f32_16x16x32_bf16 v[40:43], v[164:167], v[196:199], v[40:43]
	v_mfma_f32_16x16x32_bf16 v[28:31], v[156:159], v[206:209], v[28:31]
	v_mfma_f32_16x16x32_bf16 v[24:27], v[164:167], v[206:209], v[24:27]
	v_mfma_f32_16x16x32_bf16 v[12:15], v[156:159], v[214:217], v[12:15]
	v_mfma_f32_16x16x32_bf16 v[8:11], v[164:167], v[214:217], v[8:11]
	v_mfma_f32_16x16x32_bf16 v[52:55], v[168:171], v[184:187], v[52:55]
	v_mfma_f32_16x16x32_bf16 v[48:51], v[176:179], v[184:187], v[48:51]
	v_mfma_f32_16x16x32_bf16 v[36:39], v[168:171], v[192:195], v[36:39]
	v_mfma_f32_16x16x32_bf16 v[32:35], v[176:179], v[192:195], v[32:35]
	v_mfma_f32_16x16x32_bf16 v[20:23], v[168:171], v[200:203], v[20:23]
	v_mfma_f32_16x16x32_bf16 v[16:19], v[176:179], v[200:203], v[16:19]
	v_mfma_f32_16x16x32_bf16 v[4:7], v[168:171], v[210:213], v[4:7]
	v_mfma_f32_16x16x32_bf16 v[0:3], v[176:179], v[210:213], v[0:3]
	v_mfma_f32_16x16x32_bf16 v[52:55], v[172:175], v[188:191], v[52:55]
	v_mfma_f32_16x16x32_bf16 v[48:51], v[180:183], v[188:191], v[48:51]
	v_mfma_f32_16x16x32_bf16 v[36:39], v[172:175], v[196:199], v[36:39]
	v_mfma_f32_16x16x32_bf16 v[32:35], v[180:183], v[196:199], v[32:35]
	v_mfma_f32_16x16x32_bf16 v[20:23], v[172:175], v[206:209], v[20:23]
	v_mfma_f32_16x16x32_bf16 v[16:19], v[180:183], v[206:209], v[16:19]
	v_mfma_f32_16x16x32_bf16 v[4:7], v[172:175], v[214:217], v[4:7]
	v_mfma_f32_16x16x32_bf16 v[0:3], v[180:183], v[214:217], v[0:3]
	s_setprio 0
	s_barrier
	s_add_i32 s63, s63, 2
	s_add_u32 s44, s44, 0x100
	s_addc_u32 s45, s45, 0
	s_add_u32 s61, s61, 0x100
	s_addc_u32 s62, s62, 0
.Lkf1_exit:
	s_and_b64 vcc, exec, s[28:29]
	s_cbranch_vccz .LBB0_523
	s_barrier

; #define PG8_STAGE(bufoff, gbase, voff) do { _Pragma("unroll") for (int _i = 0; _i < 2; ++_i) \
;         __builtin_amdgcn_global_load_lds((const unsigned*)((const char*)(gbase) + (voff)[_i]), (PG8_LAS unsigned*)(lds + (bufoff) + ldsw + _i * 8192), 16, 0, 0); } while (0)
; #define PG8_LDA(dst, b, h) do { _Pragma("unroll") for (int m = 0; m < 4; ++m) _Pragma("unroll") for (int k = 0; k < 2; ++k) dst[m][k] = *(const PG8_LAS bf16x8*)(lds + PG8_SA(b, h) + aoff + m * 2048 + k * 1024); } while (0)
; #define PG8_LDB(dst, b, h) do { _Pragma("unroll") for (int n = 0; n < 2; ++n) _Pragma("unroll") for (int k = 0; k < 2; ++k) dst[n][k] = *(const PG8_LAS bf16x8*)(lds + PG8_SB(b, h) + boff + n * 2048 + k * 1024); } while (0)
; #define PG8_MMA(ai, bj, At, Bt) do { __builtin_amdgcn_s_setprio(1); _Pragma("unroll") for (int m = 0; m < 4; ++m) _Pragma("unroll") for (int n = 0; n < 2; ++n) _Pragma("unroll") for (int k = 0; k < 2; ++k) \
;         acc[ai][bj][m][n] = __builtin_amdgcn_mfma_f32_16x16x32_bf16(Bt[n][k], At[m][k], acc[ai][bj][m][n], 0, 0, 0); __builtin_amdgcn_s_setprio(0); } while (0)
; #define PG8_WAIT_V(n) asm volatile("s_waitcnt vmcnt(" #n ")" ::: "memory")
; #define PG8_WAIT_L(n) asm volatile("s_waitcnt lgkmcnt(" #n ")" ::: "memory")
; template <class Epi, class Sched, bool ALIGN_EPI = false, bool SP2 = false>
; __device__ __forceinline__ void gemm_phase(PG8_LAS unsigned char* lds, const Gemm g, const Sched& S, const Epi& E) {
;     ...
;             const bool last = (t == nt - 2);
;             const char* a1 = cA + (size_t)(t + 1) * kstep;
;             const char* a2 = last ? nA : cA + (size_t)(t + 2) * kstep; const char* b2 = last ? nB : cB + (size_t)(t + 2) * kstep;
;             const char* a3 = a2 + kstep; const char* b3 = b2 + kstep;
;             if (last && has_next) S.a_ready(nxt);
;             if constexpr (SP2) {
;             PG8_LDB(B0, 0, 0); PG8_LDB(B1, 0, 1); PG8_SCHED; PG8_LDA(At, 0, 0); PG8_STAGE(PG8_SA(1, 1), a1 + hstep, voffA);
;             PG8_WAIT_V(8); PG8_WAIT_L(0); PG8_BAR; PG8_MMA(0, 0, At, B0); PG8_MMA(0, 1, At, B1); PG8_BAR; PG8_SCHED;
;             PG8_LDA(At, 0, 1); PG8_STAGE(PG8_SB(0, 0), b2, voffB); PG8_STAGE(PG8_SB(0, 1), b2 + hstep, voffB); PG8_STAGE(PG8_SA(0, 0), a2, voffA);
;             PG8_WAIT_V(8); PG8_WAIT_L(0); PG8_BAR; PG8_MMA(1, 0, At, B0); PG8_MMA(1, 1, At, B1); PG8_BAR; PG8_SCHED;
.LBB0_627:
	s_cmp_eq_u32 s64, 12
	s_cbranch_scc0 .Lkf2_norm
	s_cmp_eq_u64 s[4:5], 0
	s_cbranch_scc1 .Lkf2_fin
.Lkf2_norm:
	ds_read_b128 v[154:157], v149
	ds_read_b128 v[158:161], v149 offset:1024
	ds_read_b128 v[162:165], v149 offset:2048
	ds_read_b128 v[166:169], v149 offset:3072
	ds_read_b128 v[170:173], v150
	ds_read_b128 v[174:177], v150 offset:1024
	ds_read_b128 v[178:181], v150 offset:2048
	ds_read_b128 v[182:185], v150 offset:3072
	s_add_u32 s44, s42, 0xfffc0080
	s_addc_u32 s45, s43, -1
	s_cmp_eq_u32 s64, 12
	s_cselect_b32 s47, s37, s45
	s_cselect_b32 s46, s60, s44
	s_cselect_b32 s45, s35, s63
	s_cselect_b32 s44, s61, s62
	s_add_i32 m0, s48, 0xc000
	ds_read_b128 v[186:189], v151
	ds_read_b128 v[190:193], v151 offset:1024
	ds_read_b128 v[194:197], v151 offset:2048
	ds_read_b128 v[198:201], v151 offset:3072
	ds_read_b128 v[206:209], v151 offset:4096
	ds_read_b128 v[210:213], v151 offset:5120
	ds_read_b128 v[214:217], v151 offset:6144
	ds_read_b128 v[218:221], v151 offset:7168
	global_load_lds_dwordx4 v138, s[42:43]
	s_add_i32 m0, s48, 0xe000
	s_nop 0
	global_load_lds_dwordx4 v140, s[42:43]
	s_waitcnt vmcnt(8)
	s_waitcnt lgkmcnt(0)
	s_setprio 1
	s_barrier
	v_mfma_f32_16x16x32_bf16 v[124:127], v[154:157], v[186:189], v[124:127]
	v_mfma_f32_16x16x32_bf16 v[120:123], v[162:165], v[186:189], v[120:123]
	v_mfma_f32_16x16x32_bf16 v[108:111], v[154:157], v[194:197], v[108:111]
	v_mfma_f32_16x16x32_bf16 v[104:107], v[162:165], v[194:197], v[104:107]
	v_mfma_f32_16x16x32_bf16 v[92:95], v[154:157], v[206:209], v[92:95]
	v_mfma_f32_16x16x32_bf16 v[88:91], v[162:165], v[206:209], v[88:91]
	v_mfma_f32_16x16x32_bf16 v[76:79], v[154:157], v[214:217], v[76:79]
	v_mfma_f32_16x16x32_bf16 v[72:75], v[162:165], v[214:217], v[72:75]
	v_mfma_f32_16x16x32_bf16 v[124:127], v[158:161], v[190:193], v[124:127]
	v_mfma_f32_16x16x32_bf16 v[120:123], v[166:169], v[190:193], v[120:123]
	v_mfma_f32_16x16x32_bf16 v[108:111], v[158:161], v[198:201], v[108:111]
	v_mfma_f32_16x16x32_bf16 v[104:107], v[166:169], v[198:201], v[104:107]
	v_mfma_f32_16x16x32_bf16 v[92:95], v[158:161], v[210:213], v[92:95]
	v_mfma_f32_16x16x32_bf16 v[88:91], v[166:169], v[210:213], v[88:91]
	v_mfma_f32_16x16x32_bf16 v[76:79], v[158:161], v[218:221], v[76:79]
	v_mfma_f32_16x16x32_bf16 v[72:75], v[166:169], v[218:221], v[72:75]
	v_mfma_f32_16x16x32_bf16 v[116:119], v[170:173], v[186:189], v[116:119]
	v_mfma_f32_16x16x32_bf16 v[112:115], v[178:181], v[186:189], v[112:115]
	v_mfma_f32_16x16x32_bf16 v[100:103], v[170:173], v[194:197], v[100:103]
	v_mfma_f32_16x16x32_bf16 v[96:99], v[178:181], v[194:197], v[96:99]
	v_mfma_f32_16x16x32_bf16 v[84:87], v[170:173], v[206:209], v[84:87]
	v_mfma_f32_16x16x32_bf16 v[80:83], v[178:181], v[206:209], v[80:83]
	v_mfma_f32_16x16x32_bf16 v[68:71], v[170:173], v[214:217], v[68:71]
	v_mfma_f32_16x16x32_bf16 v[64:67], v[178:181], v[214:217], v[64:67]
	v_mfma_f32_16x16x32_bf16 v[116:119], v[174:177], v[190:193], v[116:119]
	v_mfma_f32_16x16x32_bf16 v[112:115], v[182:185], v[190:193], v[112:115]
	v_mfma_f32_16x16x32_bf16 v[100:103], v[174:177], v[198:201], v[100:103]
	v_mfma_f32_16x16x32_bf16 v[96:99], v[182:185], v[198:201], v[96:99]
	v_mfma_f32_16x16x32_bf16 v[84:87], v[174:177], v[210:213], v[84:87]
	v_mfma_f32_16x16x32_bf16 v[80:83], v[182:185], v[210:213], v[80:83]
	v_mfma_f32_16x16x32_bf16 v[68:71], v[174:177], v[218:221], v[68:71]
	v_mfma_f32_16x16x32_bf16 v[64:67], v[182:185], v[218:221], v[64:67]
	s_setprio 0
	s_barrier
	s_add_i32 s65, s57, s13
	s_mov_b32 m0, s65
	ds_read_b128 v[186:189], v151 offset:16384
	ds_read_b128 v[190:193], v151 offset:17408
	ds_read_b128 v[194:197], v151 offset:18432
	ds_read_b128 v[198:201], v151 offset:19456
	ds_read_b128 v[206:209], v151 offset:20480
	ds_read_b128 v[210:213], v151 offset:21504
	ds_read_b128 v[214:217], v151 offset:22528
	ds_read_b128 v[218:221], v151 offset:23552
	global_load_lds_dwordx4 v132, s[44:45]
	s_add_i32 m0, s65, 0x2000
	s_add_u32 s98, s44, 0x80
	s_addc_u32 s99, s45, 0
	s_add_u32 s66, s44, 0x40000
	s_addc_u32 s67, s45, 0
	s_add_i32 s65, s58, s13
	global_load_lds_dwordx4 v136, s[44:45]
	s_mov_b32 m0, s65
	s_nop 0
	global_load_lds_dwordx4 v132, s[66:67]
	s_add_i32 m0, s65, 0x2000
	s_nop 0
	global_load_lds_dwordx4 v136, s[66:67]
	s_mov_b32 m0, s48
	s_nop 0
	global_load_lds_dwordx4 v130, s[46:47]
	s_mov_b32 m0, s49
	s_nop 0
	global_load_lds_dwordx4 v134, s[46:47]
	s_waitcnt vmcnt(8)
	s_waitcnt lgkmcnt(0)
	s_setprio 1
	s_barrier
	v_mfma_f32_16x16x32_bf16 v[60:63], v[154:157], v[186:189], v[60:63]
	v_mfma_f32_16x16x32_bf16 v[56:59], v[162:165], v[186:189], v[56:59]
	v_mfma_f32_16x16x32_bf16 v[44:47], v[154:157], v[194:197], v[44:47]
	v_mfma_f32_16x16x32_bf16 v[40:43], v[162:165], v[194:197], v[40:43]
	v_mfma_f32_16x16x32_bf16 v[28:31], v[154:157], v[206:209], v[28:31]
	v_mfma_f32_16x16x32_bf16 v[24:27], v[162:165], v[206:209], v[24:27]
	v_mfma_f32_16x16x32_bf16 v[12:15], v[154:157], v[214:217], v[12:15]
	v_mfma_f32_16x16x32_bf16 v[8:11], v[162:165], v[214:217], v[8:11]
	v_mfma_f32_16x16x32_bf16 v[60:63], v[158:161], v[190:193], v[60:63]
	v_mfma_f32_16x16x32_bf16 v[56:59], v[166:169], v[190:193], v[56:59]
	v_mfma_f32_16x16x32_bf16 v[44:47], v[158:161], v[198:201], v[44:47]
	v_mfma_f32_16x16x32_bf16 v[40:43], v[166:169], v[198:201], v[40:43]
	v_mfma_f32_16x16x32_bf16 v[28:31], v[158:161], v[210:213], v[28:31]
	v_mfma_f32_16x16x32_bf16 v[24:27], v[166:169], v[210:213], v[24:27]
	v_mfma_f32_16x16x32_bf16 v[12:15], v[158:161], v[218:221], v[12:15]
	v_mfma_f32_16x16x32_bf16 v[8:11], v[166:169], v[218:221], v[8:11]
	v_mfma_f32_16x16x32_bf16 v[52:55], v[170:173], v[186:189], v[52:55]
	v_mfma_f32_16x16x32_bf16 v[48:51], v[178:181], v[186:189], v[48:51]
	v_mfma_f32_16x16x32_bf16 v[36:39], v[170:173], v[194:197], v[36:39]
	v_mfma_f32_16x16x32_bf16 v[32:35], v[178:181], v[194:197], v[32:35]
	v_mfma_f32_16x16x32_bf16 v[20:23], v[170:173], v[206:209], v[20:23]
	v_mfma_f32_16x16x32_bf16 v[16:19], v[178:181], v[206:209], v[16:19]
	v_mfma_f32_16x16x32_bf16 v[4:7], v[170:173], v[214:217], v[4:7]
	v_mfma_f32_16x16x32_bf16 v[0:3], v[178:181], v[214:217], v[0:3]
	v_mfma_f32_16x16x32_bf16 v[52:55], v[174:177], v[190:193], v[52:55]
	v_mfma_f32_16x16x32_bf16 v[48:51], v[182:185], v[190:193], v[48:51]
	v_mfma_f32_16x16x32_bf16 v[36:39], v[174:177], v[198:201], v[36:39]
	v_mfma_f32_16x16x32_bf16 v[32:35], v[182:185], v[198:201], v[32:35]
	v_mfma_f32_16x16x32_bf16 v[20:23], v[174:177], v[210:213], v[20:23]
	v_mfma_f32_16x16x32_bf16 v[16:19], v[182:185], v[210:213], v[16:19]
	v_mfma_f32_16x16x32_bf16 v[4:7], v[174:177], v[218:221], v[4:7]
	v_mfma_f32_16x16x32_bf16 v[0:3], v[182:185], v[218:221], v[0:3]
	s_setprio 0
	s_barrier
; #define PG8_STAGE(bufoff, gbase, voff) do { _Pragma("unroll") for (int _i = 0; _i < 2; ++_i) \
;         __builtin_amdgcn_global_load_lds((const unsigned*)((const char*)(gbase) + (voff)[_i]), (PG8_LAS unsigned*)(lds + (bufoff) + ldsw + _i * 8192), 16, 0, 0); } while (0)
; #define PG8_LDA(dst, b, h) do { _Pragma("unroll") for (int m = 0; m < 4; ++m) _Pragma("unroll") for (int k = 0; k < 2; ++k) dst[m][k] = *(const PG8_LAS bf16x8*)(lds + PG8_SA(b, h) + aoff + m * 2048 + k * 1024); } while (0)
; #define PG8_LDB(dst, b, h) do { _Pragma("unroll") for (int n = 0; n < 2; ++n) _Pragma("unroll") for (int k = 0; k < 2; ++k) dst[n][k] = *(const PG8_LAS bf16x8*)(lds + PG8_SB(b, h) + boff + n * 2048 + k * 1024); } while (0)
; #define PG8_MMA(ai, bj, At, Bt) do { __builtin_amdgcn_s_setprio(1); _Pragma("unroll") for (int m = 0; m < 4; ++m) _Pragma("unroll") for (int n = 0; n < 2; ++n) _Pragma("unroll") for (int k = 0; k < 2; ++k) \
;         acc[ai][bj][m][n] = __builtin_amdgcn_mfma_f32_16x16x32_bf16(Bt[n][k], At[m][k], acc[ai][bj][m][n], 0, 0, 0); __builtin_amdgcn_s_setprio(0); } while (0)
; #define PG8_WAIT_V(n) asm volatile("s_waitcnt vmcnt(" #n ")" ::: "memory")
; #define PG8_WAIT_L(n) asm volatile("s_waitcnt lgkmcnt(" #n ")" ::: "memory")
; #define PG8_BAR __builtin_amdgcn_s_barrier()
; #define PG8_SCHED __builtin_amdgcn_sched_barrier(0)
; template <class Epi, class Sched, bool ALIGN_EPI = false, bool SP2 = false>
; __device__ __forceinline__ void gemm_phase(PG8_LAS unsigned char* lds, const Gemm g, const Sched& S, const Epi& E) {
;     ...
;             PG8_LDB(B0, 1, 0); PG8_LDB(B1, 1, 1); PG8_SCHED; PG8_LDA(At, 1, 0); PG8_STAGE(PG8_SA(0, 1), a2 + hstep, voffA);
;             PG8_WAIT_V(8); PG8_WAIT_L(0); PG8_BAR; PG8_MMA(0, 0, At, B0); PG8_MMA(0, 1, At, B1); PG8_BAR; PG8_SCHED;
;             PG8_LDA(At, 1, 1); PG8_STAGE(PG8_SB(1, 0), b3, voffB); PG8_STAGE(PG8_SB(1, 1), b3 + hstep, voffB); PG8_STAGE(PG8_SA(1, 0), a3, voffA);
;             PG8_WAIT_V(8); PG8_WAIT_L(0); PG8_BAR; PG8_MMA(1, 0, At, B0); PG8_MMA(1, 1, At, B1); PG8_BAR; PG8_SCHED;
	s_add_i32 s65, 0, 0x18000
	s_add_i32 s66, 0, 0x1c000
	ds_read_b128 v[154:157], v240
	ds_read_b128 v[158:161], v240 offset:1024
	ds_read_b128 v[162:165], v240 offset:2048
	ds_read_b128 v[166:169], v240 offset:3072
	ds_read_b128 v[170:173], v241
	ds_read_b128 v[174:177], v241 offset:1024
	ds_read_b128 v[178:181], v241 offset:2048
	ds_read_b128 v[182:185], v241 offset:3072
	s_add_u32 s100, s46, 0x80
	s_addc_u32 s101, s47, 0
	s_add_u32 s46, s46, 0x40000
	s_addc_u32 s47, s47, 0
	s_mov_b32 m0, s50
	ds_read_b128 v[186:189], v151 offset:32768
	ds_read_b128 v[190:193], v151 offset:33792
	ds_read_b128 v[194:197], v151 offset:34816
	ds_read_b128 v[198:201], v151 offset:35840
	ds_read_b128 v[206:209], v151 offset:36864
	ds_read_b128 v[210:213], v151 offset:37888
	ds_read_b128 v[214:217], v151 offset:38912
	ds_read_b128 v[218:221], v151 offset:39936
	global_load_lds_dwordx4 v130, s[46:47]
	s_mov_b32 m0, s51
	s_nop 0
	global_load_lds_dwordx4 v134, s[46:47]
	s_waitcnt vmcnt(8)
	s_waitcnt lgkmcnt(0)
	s_setprio 1
	s_barrier
	v_mfma_f32_16x16x32_bf16 v[124:127], v[154:157], v[186:189], v[124:127]
	v_mfma_f32_16x16x32_bf16 v[120:123], v[162:165], v[186:189], v[120:123]
	v_mfma_f32_16x16x32_bf16 v[108:111], v[154:157], v[194:197], v[108:111]
	v_mfma_f32_16x16x32_bf16 v[104:107], v[162:165], v[194:197], v[104:107]
	v_mfma_f32_16x16x32_bf16 v[92:95], v[154:157], v[206:209], v[92:95]
	v_mfma_f32_16x16x32_bf16 v[88:91], v[162:165], v[206:209], v[88:91]
	v_mfma_f32_16x16x32_bf16 v[76:79], v[154:157], v[214:217], v[76:79]
	v_mfma_f32_16x16x32_bf16 v[72:75], v[162:165], v[214:217], v[72:75]
	v_mfma_f32_16x16x32_bf16 v[124:127], v[158:161], v[190:193], v[124:127]
	v_mfma_f32_16x16x32_bf16 v[120:123], v[166:169], v[190:193], v[120:123]
	v_mfma_f32_16x16x32_bf16 v[108:111], v[158:161], v[198:201], v[108:111]
	v_mfma_f32_16x16x32_bf16 v[104:107], v[166:169], v[198:201], v[104:107]
	v_mfma_f32_16x16x32_bf16 v[92:95], v[158:161], v[210:213], v[92:95]
	v_mfma_f32_16x16x32_bf16 v[88:91], v[166:169], v[210:213], v[88:91]
	v_mfma_f32_16x16x32_bf16 v[76:79], v[158:161], v[218:221], v[76:79]
	v_mfma_f32_16x16x32_bf16 v[72:75], v[166:169], v[218:221], v[72:75]
	v_mfma_f32_16x16x32_bf16 v[116:119], v[170:173], v[186:189], v[116:119]
	v_mfma_f32_16x16x32_bf16 v[112:115], v[178:181], v[186:189], v[112:115]
	v_mfma_f32_16x16x32_bf16 v[100:103], v[170:173], v[194:197], v[100:103]
	v_mfma_f32_16x16x32_bf16 v[96:99], v[178:181], v[194:197], v[96:99]
	v_mfma_f32_16x16x32_bf16 v[84:87], v[170:173], v[206:209], v[84:87]
	v_mfma_f32_16x16x32_bf16 v[80:83], v[178:181], v[206:209], v[80:83]
	v_mfma_f32_16x16x32_bf16 v[68:71], v[170:173], v[214:217], v[68:71]
	v_mfma_f32_16x16x32_bf16 v[64:67], v[178:181], v[214:217], v[64:67]
	v_mfma_f32_16x16x32_bf16 v[116:119], v[174:177], v[190:193], v[116:119]
	v_mfma_f32_16x16x32_bf16 v[112:115], v[182:185], v[190:193], v[112:115]
	v_mfma_f32_16x16x32_bf16 v[100:103], v[174:177], v[198:201], v[100:103]
	v_mfma_f32_16x16x32_bf16 v[96:99], v[182:185], v[198:201], v[96:99]
	v_mfma_f32_16x16x32_bf16 v[84:87], v[174:177], v[210:213], v[84:87]
	v_mfma_f32_16x16x32_bf16 v[80:83], v[182:185], v[210:213], v[80:83]
	v_mfma_f32_16x16x32_bf16 v[68:71], v[174:177], v[218:221], v[68:71]
	v_mfma_f32_16x16x32_bf16 v[64:67], v[182:185], v[218:221], v[64:67]
	s_setprio 0
	s_barrier
	s_add_i32 s46, s65, s13
	s_mov_b32 m0, s46
	ds_read_b128 v[186:189], v151 offset:49152
	ds_read_b128 v[190:193], v151 offset:50176
	ds_read_b128 v[194:197], v151 offset:51200
	ds_read_b128 v[198:201], v151 offset:52224
	ds_read_b128 v[206:209], v151 offset:53248
	ds_read_b128 v[210:213], v151 offset:54272
	ds_read_b128 v[214:217], v151 offset:55296
	ds_read_b128 v[218:221], v151 offset:56320
	global_load_lds_dwordx4 v132, s[98:99]
	s_add_i32 m0, s46, 0x2000
	s_add_u32 s44, s44, 0x40080
	s_addc_u32 s45, s45, 0
	s_add_i32 s46, s66, s13
	global_load_lds_dwordx4 v136, s[98:99]
	s_mov_b32 m0, s46
	s_nop 0
	global_load_lds_dwordx4 v132, s[44:45]
	s_add_i32 m0, s46, 0x2000
	s_nop 0
	global_load_lds_dwordx4 v136, s[44:45]
	s_mov_b32 m0, s54
	s_nop 0
	global_load_lds_dwordx4 v130, s[100:101]
	s_mov_b32 m0, s55
	s_nop 0
	global_load_lds_dwordx4 v134, s[100:101]
	s_waitcnt vmcnt(8)
	s_waitcnt lgkmcnt(0)
	s_setprio 1
	s_barrier
	v_mfma_f32_16x16x32_bf16 v[60:63], v[154:157], v[186:189], v[60:63]
	v_mfma_f32_16x16x32_bf16 v[56:59], v[162:165], v[186:189], v[56:59]
	v_mfma_f32_16x16x32_bf16 v[44:47], v[154:157], v[194:197], v[44:47]
	v_mfma_f32_16x16x32_bf16 v[40:43], v[162:165], v[194:197], v[40:43]
	v_mfma_f32_16x16x32_bf16 v[28:31], v[154:157], v[206:209], v[28:31]
	v_mfma_f32_16x16x32_bf16 v[24:27], v[162:165], v[206:209], v[24:27]
	v_mfma_f32_16x16x32_bf16 v[12:15], v[154:157], v[214:217], v[12:15]
	v_mfma_f32_16x16x32_bf16 v[8:11], v[162:165], v[214:217], v[8:11]
	v_mfma_f32_16x16x32_bf16 v[60:63], v[158:161], v[190:193], v[60:63]
	v_mfma_f32_16x16x32_bf16 v[56:59], v[166:169], v[190:193], v[56:59]
	v_mfma_f32_16x16x32_bf16 v[44:47], v[158:161], v[198:201], v[44:47]
	v_mfma_f32_16x16x32_bf16 v[40:43], v[166:169], v[198:201], v[40:43]
	v_mfma_f32_16x16x32_bf16 v[28:31], v[158:161], v[210:213], v[28:31]
	v_mfma_f32_16x16x32_bf16 v[24:27], v[166:169], v[210:213], v[24:27]
	v_mfma_f32_16x16x32_bf16 v[12:15], v[158:161], v[218:221], v[12:15]
	v_mfma_f32_16x16x32_bf16 v[8:11], v[166:169], v[218:221], v[8:11]
	v_mfma_f32_16x16x32_bf16 v[52:55], v[170:173], v[186:189], v[52:55]
	v_mfma_f32_16x16x32_bf16 v[48:51], v[178:181], v[186:189], v[48:51]
	v_mfma_f32_16x16x32_bf16 v[36:39], v[170:173], v[194:197], v[36:39]
	v_mfma_f32_16x16x32_bf16 v[32:35], v[178:181], v[194:197], v[32:35]
	v_mfma_f32_16x16x32_bf16 v[20:23], v[170:173], v[206:209], v[20:23]
	v_mfma_f32_16x16x32_bf16 v[16:19], v[178:181], v[206:209], v[16:19]
	v_mfma_f32_16x16x32_bf16 v[4:7], v[170:173], v[214:217], v[4:7]
	v_mfma_f32_16x16x32_bf16 v[0:3], v[178:181], v[214:217], v[0:3]
	v_mfma_f32_16x16x32_bf16 v[52:55], v[174:177], v[190:193], v[52:55]
	v_mfma_f32_16x16x32_bf16 v[48:51], v[182:185], v[190:193], v[48:51]
	v_mfma_f32_16x16x32_bf16 v[36:39], v[174:177], v[198:201], v[36:39]
	v_mfma_f32_16x16x32_bf16 v[32:35], v[182:185], v[198:201], v[32:35]
	v_mfma_f32_16x16x32_bf16 v[20:23], v[174:177], v[210:213], v[20:23]
	v_mfma_f32_16x16x32_bf16 v[16:19], v[182:185], v[210:213], v[16:19]
	v_mfma_f32_16x16x32_bf16 v[4:7], v[174:177], v[218:221], v[4:7]
	v_mfma_f32_16x16x32_bf16 v[0:3], v[182:185], v[218:221], v[0:3]
	s_setprio 0
	s_barrier
	s_add_i32 s64, s64, 2
	s_add_u32 s42, s42, 0x100
	s_addc_u32 s43, s43, 0
	s_add_u32 s62, s62, 0x100
	s_addc_u32 s63, s63, 0
	s_cmp_gt_u32 s64, 13
	s_cbranch_scc0 .LBB0_627
	s_branch .Lkf2_exit
; #define PG8_STAGE(bufoff, gbase, voff) do { _Pragma("unroll") for (int _i = 0; _i < 2; ++_i) \
;         __builtin_amdgcn_global_load_lds((const unsigned*)((const char*)(gbase) + (voff)[_i]), (PG8_LAS unsigned*)(lds + (bufoff) + ldsw + _i * 8192), 16, 0, 0); } while (0)
; #define PG8_LDA(dst, b, h) do { _Pragma("unroll") for (int m = 0; m < 4; ++m) _Pragma("unroll") for (int k = 0; k < 2; ++k) dst[m][k] = *(const PG8_LAS bf16x8*)(lds + PG8_SA(b, h) + aoff + m * 2048 + k * 1024); } while (0)
; #define PG8_LDB(dst, b, h) do { _Pragma("unroll") for (int n = 0; n < 2; ++n) _Pragma("unroll") for (int k = 0; k < 2; ++k) dst[n][k] = *(const PG8_LAS bf16x8*)(lds + PG8_SB(b, h) + boff + n * 2048 + k * 1024); } while (0)
; #define PG8_MMA(ai, bj, At, Bt) do { __builtin_amdgcn_s_setprio(1); _Pragma("unroll") for (int m = 0; m < 4; ++m) _Pragma("unroll") for (int n = 0; n < 2; ++n) _Pragma("unroll") for (int k = 0; k < 2; ++k) \
;         acc[ai][bj][m][n] = __builtin_amdgcn_mfma_f32_16x16x32_bf16(Bt[n][k], At[m][k], acc[ai][bj][m][n], 0, 0, 0); __builtin_amdgcn_s_setprio(0); } while (0)
; #define PG8_WAIT_V(n) asm volatile("s_waitcnt vmcnt(" #n ")" ::: "memory")
; #define PG8_WAIT_L(n) asm volatile("s_waitcnt lgkmcnt(" #n ")" ::: "memory")
; #define PG8_BAR __builtin_amdgcn_s_barrier()
; #define PG8_SCHED __builtin_amdgcn_sched_barrier(0)
; template <class Epi, class Sched, bool ALIGN_EPI = false, bool SP2 = false>
; __device__ __forceinline__ void gemm_phase(PG8_LAS unsigned char* lds, const Gemm g, const Sched& S, const Epi& E) {
;     ...
;             PG8_LDB(B0, 0, 0); PG8_LDB(B1, 0, 1); PG8_SCHED; PG8_LDA(At, 0, 0); PG8_STAGE(PG8_SA(1, 1), a1 + hstep, voffA);
;             PG8_WAIT_V(8); PG8_WAIT_L(0); PG8_BAR; PG8_MMA(0, 0, At, B0); PG8_MMA(0, 1, At, B1); PG8_BAR; PG8_SCHED;
;             PG8_LDA(At, 0, 1); PG8_STAGE(PG8_SB(0, 0), b2, voffB); PG8_STAGE(PG8_SB(0, 1), b2 + hstep, voffB); PG8_STAGE(PG8_SA(0, 0), a2, voffA);
;             PG8_WAIT_V(8); PG8_WAIT_L(0); PG8_BAR; PG8_MMA(1, 0, At, B0); PG8_MMA(1, 1, At, B1); PG8_BAR; PG8_SCHED;
.Lkf2_fin:
	ds_read_b128 v[154:157], v149
	ds_read_b128 v[158:161], v149 offset:1024
	ds_read_b128 v[162:165], v149 offset:2048
	ds_read_b128 v[166:169], v149 offset:3072
	ds_read_b128 v[170:173], v150
	ds_read_b128 v[174:177], v150 offset:1024
	ds_read_b128 v[178:181], v150 offset:2048
	ds_read_b128 v[182:185], v150 offset:3072
	s_add_u32 s44, s42, 0xfffc0080
	s_addc_u32 s45, s43, -1
	s_cmp_eq_u32 s64, 12
	s_cselect_b32 s47, s37, s45
	s_cselect_b32 s46, s60, s44
	s_cselect_b32 s45, s35, s63
	s_cselect_b32 s44, s61, s62
	s_add_i32 m0, s48, 0xc000
	ds_read_b128 v[186:189], v151
	ds_read_b128 v[190:193], v151 offset:1024
	ds_read_b128 v[194:197], v151 offset:2048
	ds_read_b128 v[198:201], v151 offset:3072
	ds_read_b128 v[206:209], v151 offset:4096
	ds_read_b128 v[210:213], v151 offset:5120
	ds_read_b128 v[214:217], v151 offset:6144
	ds_read_b128 v[218:221], v151 offset:7168
	global_load_lds_dwordx4 v138, s[42:43]
	s_add_i32 m0, s48, 0xe000
	s_nop 0
	global_load_lds_dwordx4 v140, s[42:43]
	s_waitcnt vmcnt(8)
	s_waitcnt lgkmcnt(0)
	s_setprio 1
	s_barrier
	v_mfma_f32_16x16x32_bf16 v[124:127], v[154:157], v[186:189], v[124:127]
	v_mfma_f32_16x16x32_bf16 v[120:123], v[162:165], v[186:189], v[120:123]
	v_mfma_f32_16x16x32_bf16 v[108:111], v[154:157], v[194:197], v[108:111]
	v_mfma_f32_16x16x32_bf16 v[104:107], v[162:165], v[194:197], v[104:107]
	v_mfma_f32_16x16x32_bf16 v[92:95], v[154:157], v[206:209], v[92:95]
	v_mfma_f32_16x16x32_bf16 v[88:91], v[162:165], v[206:209], v[88:91]
	v_mfma_f32_16x16x32_bf16 v[76:79], v[154:157], v[214:217], v[76:79]
	v_mfma_f32_16x16x32_bf16 v[72:75], v[162:165], v[214:217], v[72:75]
	v_mfma_f32_16x16x32_bf16 v[124:127], v[158:161], v[190:193], v[124:127]
	v_mfma_f32_16x16x32_bf16 v[120:123], v[166:169], v[190:193], v[120:123]
	v_mfma_f32_16x16x32_bf16 v[108:111], v[158:161], v[198:201], v[108:111]
	v_mfma_f32_16x16x32_bf16 v[104:107], v[166:169], v[198:201], v[104:107]
	v_mfma_f32_16x16x32_bf16 v[92:95], v[158:161], v[210:213], v[92:95]
	v_mfma_f32_16x16x32_bf16 v[88:91], v[166:169], v[210:213], v[88:91]
	v_mfma_f32_16x16x32_bf16 v[76:79], v[158:161], v[218:221], v[76:79]
	v_mfma_f32_16x16x32_bf16 v[72:75], v[166:169], v[218:221], v[72:75]
	v_mfma_f32_16x16x32_bf16 v[116:119], v[170:173], v[186:189], v[116:119]
	v_mfma_f32_16x16x32_bf16 v[112:115], v[178:181], v[186:189], v[112:115]
	v_mfma_f32_16x16x32_bf16 v[100:103], v[170:173], v[194:197], v[100:103]
	v_mfma_f32_16x16x32_bf16 v[96:99], v[178:181], v[194:197], v[96:99]
	v_mfma_f32_16x16x32_bf16 v[84:87], v[170:173], v[206:209], v[84:87]
	v_mfma_f32_16x16x32_bf16 v[80:83], v[178:181], v[206:209], v[80:83]
	v_mfma_f32_16x16x32_bf16 v[68:71], v[170:173], v[214:217], v[68:71]
	v_mfma_f32_16x16x32_bf16 v[64:67], v[178:181], v[214:217], v[64:67]
	v_mfma_f32_16x16x32_bf16 v[116:119], v[174:177], v[190:193], v[116:119]
	v_mfma_f32_16x16x32_bf16 v[112:115], v[182:185], v[190:193], v[112:115]
	v_mfma_f32_16x16x32_bf16 v[100:103], v[174:177], v[198:201], v[100:103]
	v_mfma_f32_16x16x32_bf16 v[96:99], v[182:185], v[198:201], v[96:99]
	v_mfma_f32_16x16x32_bf16 v[84:87], v[174:177], v[210:213], v[84:87]
	v_mfma_f32_16x16x32_bf16 v[80:83], v[182:185], v[210:213], v[80:83]
	v_mfma_f32_16x16x32_bf16 v[68:71], v[174:177], v[218:221], v[68:71]
	v_mfma_f32_16x16x32_bf16 v[64:67], v[182:185], v[218:221], v[64:67]
	s_setprio 0
	s_barrier
	s_add_i32 s65, s57, s13
	s_mov_b32 m0, s65
	ds_read_b128 v[186:189], v151 offset:16384
	ds_read_b128 v[190:193], v151 offset:17408
	ds_read_b128 v[194:197], v151 offset:18432
	ds_read_b128 v[198:201], v151 offset:19456
	ds_read_b128 v[206:209], v151 offset:20480
	ds_read_b128 v[210:213], v151 offset:21504
	ds_read_b128 v[214:217], v151 offset:22528
	ds_read_b128 v[218:221], v151 offset:23552
	s_waitcnt vmcnt(2)
	s_waitcnt lgkmcnt(0)
	s_setprio 1
	s_barrier
	v_mfma_f32_16x16x32_bf16 v[60:63], v[154:157], v[186:189], v[60:63]
	v_mfma_f32_16x16x32_bf16 v[56:59], v[162:165], v[186:189], v[56:59]
	v_mfma_f32_16x16x32_bf16 v[44:47], v[154:157], v[194:197], v[44:47]
	v_mfma_f32_16x16x32_bf16 v[40:43], v[162:165], v[194:197], v[40:43]
	v_mfma_f32_16x16x32_bf16 v[28:31], v[154:157], v[206:209], v[28:31]
	v_mfma_f32_16x16x32_bf16 v[24:27], v[162:165], v[206:209], v[24:27]
	v_mfma_f32_16x16x32_bf16 v[12:15], v[154:157], v[214:217], v[12:15]
	v_mfma_f32_16x16x32_bf16 v[8:11], v[162:165], v[214:217], v[8:11]
	v_mfma_f32_16x16x32_bf16 v[60:63], v[158:161], v[190:193], v[60:63]
	v_mfma_f32_16x16x32_bf16 v[56:59], v[166:169], v[190:193], v[56:59]
	v_mfma_f32_16x16x32_bf16 v[44:47], v[158:161], v[198:201], v[44:47]
	v_mfma_f32_16x16x32_bf16 v[40:43], v[166:169], v[198:201], v[40:43]
	v_mfma_f32_16x16x32_bf16 v[28:31], v[158:161], v[210:213], v[28:31]
	v_mfma_f32_16x16x32_bf16 v[24:27], v[166:169], v[210:213], v[24:27]
	v_mfma_f32_16x16x32_bf16 v[12:15], v[158:161], v[218:221], v[12:15]
	v_mfma_f32_16x16x32_bf16 v[8:11], v[166:169], v[218:221], v[8:11]
	v_mfma_f32_16x16x32_bf16 v[52:55], v[170:173], v[186:189], v[52:55]
	v_mfma_f32_16x16x32_bf16 v[48:51], v[178:181], v[186:189], v[48:51]
	v_mfma_f32_16x16x32_bf16 v[36:39], v[170:173], v[194:197], v[36:39]
	v_mfma_f32_16x16x32_bf16 v[32:35], v[178:181], v[194:197], v[32:35]
	v_mfma_f32_16x16x32_bf16 v[20:23], v[170:173], v[206:209], v[20:23]
	v_mfma_f32_16x16x32_bf16 v[16:19], v[178:181], v[206:209], v[16:19]
	v_mfma_f32_16x16x32_bf16 v[4:7], v[170:173], v[214:217], v[4:7]
	v_mfma_f32_16x16x32_bf16 v[0:3], v[178:181], v[214:217], v[0:3]
	v_mfma_f32_16x16x32_bf16 v[52:55], v[174:177], v[190:193], v[52:55]
	v_mfma_f32_16x16x32_bf16 v[48:51], v[182:185], v[190:193], v[48:51]
	v_mfma_f32_16x16x32_bf16 v[36:39], v[174:177], v[198:201], v[36:39]
	v_mfma_f32_16x16x32_bf16 v[32:35], v[182:185], v[198:201], v[32:35]
	v_mfma_f32_16x16x32_bf16 v[20:23], v[174:177], v[210:213], v[20:23]
	v_mfma_f32_16x16x32_bf16 v[16:19], v[182:185], v[210:213], v[16:19]
	v_mfma_f32_16x16x32_bf16 v[4:7], v[174:177], v[218:221], v[4:7]
	v_mfma_f32_16x16x32_bf16 v[0:3], v[182:185], v[218:221], v[0:3]
	s_setprio 0
	s_barrier
; #define PG8_STAGE(bufoff, gbase, voff) do { _Pragma("unroll") for (int _i = 0; _i < 2; ++_i) \
;         __builtin_amdgcn_global_load_lds((const unsigned*)((const char*)(gbase) + (voff)[_i]), (PG8_LAS unsigned*)(lds + (bufoff) + ldsw + _i * 8192), 16, 0, 0); } while (0)
; #define PG8_LDA(dst, b, h) do { _Pragma("unroll") for (int m = 0; m < 4; ++m) _Pragma("unroll") for (int k = 0; k < 2; ++k) dst[m][k] = *(const PG8_LAS bf16x8*)(lds + PG8_SA(b, h) + aoff + m * 2048 + k * 1024); } while (0)
; #define PG8_LDB(dst, b, h) do { _Pragma("unroll") for (int n = 0; n < 2; ++n) _Pragma("unroll") for (int k = 0; k < 2; ++k) dst[n][k] = *(const PG8_LAS bf16x8*)(lds + PG8_SB(b, h) + boff + n * 2048 + k * 1024); } while (0)
; #define PG8_MMA(ai, bj, At, Bt) do { __builtin_amdgcn_s_setprio(1); _Pragma("unroll") for (int m = 0; m < 4; ++m) _Pragma("unroll") for (int n = 0; n < 2; ++n) _Pragma("unroll") for (int k = 0; k < 2; ++k) \
;         acc[ai][bj][m][n] = __builtin_amdgcn_mfma_f32_16x16x32_bf16(Bt[n][k], At[m][k], acc[ai][bj][m][n], 0, 0, 0); __builtin_amdgcn_s_setprio(0); } while (0)
; #define PG8_WAIT_V(n) asm volatile("s_waitcnt vmcnt(" #n ")" ::: "memory")
; #define PG8_WAIT_L(n) asm volatile("s_waitcnt lgkmcnt(" #n ")" ::: "memory")
; #define PG8_BAR __builtin_amdgcn_s_barrier()
; #define PG8_SCHED __builtin_amdgcn_sched_barrier(0)
; template <class Epi, class Sched, bool ALIGN_EPI = false, bool SP2 = false>
; __device__ __forceinline__ void gemm_phase(PG8_LAS unsigned char* lds, const Gemm g, const Sched& S, const Epi& E) {
;     ...
;             PG8_LDB(B0, 1, 0); PG8_LDB(B1, 1, 1); PG8_SCHED; PG8_LDA(At, 1, 0); PG8_STAGE(PG8_SA(0, 1), a2 + hstep, voffA);
;             PG8_WAIT_V(8); PG8_WAIT_L(0); PG8_BAR; PG8_MMA(0, 0, At, B0); PG8_MMA(0, 1, At, B1); PG8_BAR; PG8_SCHED;
;             PG8_LDA(At, 1, 1); PG8_STAGE(PG8_SB(1, 0), b3, voffB); PG8_STAGE(PG8_SB(1, 1), b3 + hstep, voffB); PG8_STAGE(PG8_SA(1, 0), a3, voffA);
;             PG8_WAIT_V(8); PG8_WAIT_L(0); PG8_BAR; PG8_MMA(1, 0, At, B0); PG8_MMA(1, 1, At, B1); PG8_BAR; PG8_SCHED;
;     ...
;         if constexpr (ALIGN_EPI) { if (wr == 0) PG8_BAR; }
	s_add_i32 s65, 0, 0x18000
	s_add_i32 s66, 0, 0x1c000
	ds_read_b128 v[154:157], v240
	ds_read_b128 v[158:161], v240 offset:1024
	ds_read_b128 v[162:165], v240 offset:2048
	ds_read_b128 v[166:169], v240 offset:3072
	ds_read_b128 v[170:173], v241
	ds_read_b128 v[174:177], v241 offset:1024
	ds_read_b128 v[178:181], v241 offset:2048
	ds_read_b128 v[182:185], v241 offset:3072
	ds_read_b128 v[186:189], v151 offset:32768
	ds_read_b128 v[190:193], v151 offset:33792
	ds_read_b128 v[194:197], v151 offset:34816
	ds_read_b128 v[198:201], v151 offset:35840
	ds_read_b128 v[206:209], v151 offset:36864
	ds_read_b128 v[210:213], v151 offset:37888
	ds_read_b128 v[214:217], v151 offset:38912
	ds_read_b128 v[218:221], v151 offset:39936
	s_waitcnt vmcnt(0)
	s_waitcnt lgkmcnt(0)
	s_setprio 1
	s_barrier
	v_mfma_f32_16x16x32_bf16 v[124:127], v[154:157], v[186:189], v[124:127]
	v_mfma_f32_16x16x32_bf16 v[120:123], v[162:165], v[186:189], v[120:123]
	v_mfma_f32_16x16x32_bf16 v[108:111], v[154:157], v[194:197], v[108:111]
	v_mfma_f32_16x16x32_bf16 v[104:107], v[162:165], v[194:197], v[104:107]
	v_mfma_f32_16x16x32_bf16 v[92:95], v[154:157], v[206:209], v[92:95]
	v_mfma_f32_16x16x32_bf16 v[88:91], v[162:165], v[206:209], v[88:91]
	v_mfma_f32_16x16x32_bf16 v[76:79], v[154:157], v[214:217], v[76:79]
	v_mfma_f32_16x16x32_bf16 v[72:75], v[162:165], v[214:217], v[72:75]
	v_mfma_f32_16x16x32_bf16 v[124:127], v[158:161], v[190:193], v[124:127]
	v_mfma_f32_16x16x32_bf16 v[120:123], v[166:169], v[190:193], v[120:123]
	v_mfma_f32_16x16x32_bf16 v[108:111], v[158:161], v[198:201], v[108:111]
	v_mfma_f32_16x16x32_bf16 v[104:107], v[166:169], v[198:201], v[104:107]
	v_mfma_f32_16x16x32_bf16 v[92:95], v[158:161], v[210:213], v[92:95]
	v_mfma_f32_16x16x32_bf16 v[88:91], v[166:169], v[210:213], v[88:91]
	v_mfma_f32_16x16x32_bf16 v[76:79], v[158:161], v[218:221], v[76:79]
	v_mfma_f32_16x16x32_bf16 v[72:75], v[166:169], v[218:221], v[72:75]
	v_mfma_f32_16x16x32_bf16 v[116:119], v[170:173], v[186:189], v[116:119]
	v_mfma_f32_16x16x32_bf16 v[112:115], v[178:181], v[186:189], v[112:115]
	v_mfma_f32_16x16x32_bf16 v[100:103], v[170:173], v[194:197], v[100:103]
	v_mfma_f32_16x16x32_bf16 v[96:99], v[178:181], v[194:197], v[96:99]
	v_mfma_f32_16x16x32_bf16 v[84:87], v[170:173], v[206:209], v[84:87]
	v_mfma_f32_16x16x32_bf16 v[80:83], v[178:181], v[206:209], v[80:83]
	v_mfma_f32_16x16x32_bf16 v[68:71], v[170:173], v[214:217], v[68:71]
	v_mfma_f32_16x16x32_bf16 v[64:67], v[178:181], v[214:217], v[64:67]
	v_mfma_f32_16x16x32_bf16 v[116:119], v[174:177], v[190:193], v[116:119]
	v_mfma_f32_16x16x32_bf16 v[112:115], v[182:185], v[190:193], v[112:115]
	v_mfma_f32_16x16x32_bf16 v[100:103], v[174:177], v[198:201], v[100:103]
	v_mfma_f32_16x16x32_bf16 v[96:99], v[182:185], v[198:201], v[96:99]
	v_mfma_f32_16x16x32_bf16 v[84:87], v[174:177], v[210:213], v[84:87]
	v_mfma_f32_16x16x32_bf16 v[80:83], v[182:185], v[210:213], v[80:83]
	v_mfma_f32_16x16x32_bf16 v[68:71], v[174:177], v[218:221], v[68:71]
	v_mfma_f32_16x16x32_bf16 v[64:67], v[182:185], v[218:221], v[64:67]
	s_setprio 0
	s_barrier
	ds_read_b128 v[186:189], v151 offset:49152
	ds_read_b128 v[190:193], v151 offset:50176
	ds_read_b128 v[194:197], v151 offset:51200
	ds_read_b128 v[198:201], v151 offset:52224
	ds_read_b128 v[206:209], v151 offset:53248
	ds_read_b128 v[210:213], v151 offset:54272
	ds_read_b128 v[214:217], v151 offset:55296
	ds_read_b128 v[218:221], v151 offset:56320
	s_waitcnt lgkmcnt(0)
	s_setprio 1
	s_barrier
	v_mfma_f32_16x16x32_bf16 v[60:63], v[154:157], v[186:189], v[60:63]
	v_mfma_f32_16x16x32_bf16 v[56:59], v[162:165], v[186:189], v[56:59]
	v_mfma_f32_16x16x32_bf16 v[44:47], v[154:157], v[194:197], v[44:47]
	v_mfma_f32_16x16x32_bf16 v[40:43], v[162:165], v[194:197], v[40:43]
	v_mfma_f32_16x16x32_bf16 v[28:31], v[154:157], v[206:209], v[28:31]
	v_mfma_f32_16x16x32_bf16 v[24:27], v[162:165], v[206:209], v[24:27]
	v_mfma_f32_16x16x32_bf16 v[12:15], v[154:157], v[214:217], v[12:15]
	v_mfma_f32_16x16x32_bf16 v[8:11], v[162:165], v[214:217], v[8:11]
	v_mfma_f32_16x16x32_bf16 v[60:63], v[158:161], v[190:193], v[60:63]
	v_mfma_f32_16x16x32_bf16 v[56:59], v[166:169], v[190:193], v[56:59]
	v_mfma_f32_16x16x32_bf16 v[44:47], v[158:161], v[198:201], v[44:47]
	v_mfma_f32_16x16x32_bf16 v[40:43], v[166:169], v[198:201], v[40:43]
	v_mfma_f32_16x16x32_bf16 v[28:31], v[158:161], v[210:213], v[28:31]
	v_mfma_f32_16x16x32_bf16 v[24:27], v[166:169], v[210:213], v[24:27]
	v_mfma_f32_16x16x32_bf16 v[12:15], v[158:161], v[218:221], v[12:15]
	v_mfma_f32_16x16x32_bf16 v[8:11], v[166:169], v[218:221], v[8:11]
	v_mfma_f32_16x16x32_bf16 v[52:55], v[170:173], v[186:189], v[52:55]
	v_mfma_f32_16x16x32_bf16 v[48:51], v[178:181], v[186:189], v[48:51]
	v_mfma_f32_16x16x32_bf16 v[36:39], v[170:173], v[194:197], v[36:39]
	v_mfma_f32_16x16x32_bf16 v[32:35], v[178:181], v[194:197], v[32:35]
	v_mfma_f32_16x16x32_bf16 v[20:23], v[170:173], v[206:209], v[20:23]
	v_mfma_f32_16x16x32_bf16 v[16:19], v[178:181], v[206:209], v[16:19]
	v_mfma_f32_16x16x32_bf16 v[4:7], v[170:173], v[214:217], v[4:7]
	v_mfma_f32_16x16x32_bf16 v[0:3], v[178:181], v[214:217], v[0:3]
	v_mfma_f32_16x16x32_bf16 v[52:55], v[174:177], v[190:193], v[52:55]
	v_mfma_f32_16x16x32_bf16 v[48:51], v[182:185], v[190:193], v[48:51]
	v_mfma_f32_16x16x32_bf16 v[36:39], v[174:177], v[198:201], v[36:39]
	v_mfma_f32_16x16x32_bf16 v[32:35], v[182:185], v[198:201], v[32:35]
	v_mfma_f32_16x16x32_bf16 v[20:23], v[174:177], v[210:213], v[20:23]
	v_mfma_f32_16x16x32_bf16 v[16:19], v[182:185], v[210:213], v[16:19]
	v_mfma_f32_16x16x32_bf16 v[4:7], v[174:177], v[218:221], v[4:7]
	v_mfma_f32_16x16x32_bf16 v[0:3], v[182:185], v[218:221], v[0:3]
	s_setprio 0
	s_barrier
	s_add_i32 s64, s64, 2
	s_add_u32 s42, s42, 0x100
	s_addc_u32 s43, s43, 0
	s_add_u32 s62, s62, 0x100
	s_addc_u32 s63, s63, 0
.Lkf2_exit:
	s_and_b64 vcc, exec, s[30:31]
	s_cbranch_vccz .LBB0_630
	s_barrier

; #define PG8_STAGE(bufoff, gbase, voff) do { _Pragma("unroll") for (int _i = 0; _i < 2; ++_i) \
;         __builtin_amdgcn_global_load_lds((const unsigned*)((const char*)(gbase) + (voff)[_i]), (PG8_LAS unsigned*)(lds + (bufoff) + ldsw + _i * 8192), 16, 0, 0); } while (0)
; #define PG8_LDA(dst, b, h) do { _Pragma("unroll") for (int m = 0; m < 4; ++m) _Pragma("unroll") for (int k = 0; k < 2; ++k) dst[m][k] = *(const PG8_LAS bf16x8*)(lds + PG8_SA(b, h) + aoff + m * 2048 + k * 1024); } while (0)
; #define PG8_LDB(dst, b, h) do { _Pragma("unroll") for (int n = 0; n < 2; ++n) _Pragma("unroll") for (int k = 0; k < 2; ++k) dst[n][k] = *(const PG8_LAS bf16x8*)(lds + PG8_SB(b, h) + boff + n * 2048 + k * 1024); } while (0)
; #define PG8_MMA(ai, bj, At, Bt) do { __builtin_amdgcn_s_setprio(1); _Pragma("unroll") for (int m = 0; m < 4; ++m) _Pragma("unroll") for (int n = 0; n < 2; ++n) _Pragma("unroll") for (int k = 0; k < 2; ++k) \
;         acc[ai][bj][m][n] = __builtin_amdgcn_mfma_f32_16x16x32_bf16(Bt[n][k], At[m][k], acc[ai][bj][m][n], 0, 0, 0); __builtin_amdgcn_s_setprio(0); } while (0)
; #define PG8_WAIT_V(n) asm volatile("s_waitcnt vmcnt(" #n ")" ::: "memory")
; #define PG8_WAIT_L(n) asm volatile("s_waitcnt lgkmcnt(" #n ")" ::: "memory")
; template <class Epi, class Sched, bool ALIGN_EPI = false, bool SP2 = false>
; __device__ __forceinline__ void gemm_phase(PG8_LAS unsigned char* lds, const Gemm g, const Sched& S, const Epi& E) {
;     ...
;             const bool last = (t == nt - 2);
;             const char* a1 = cA + (size_t)(t + 1) * kstep;
;             const char* a2 = last ? nA : cA + (size_t)(t + 2) * kstep; const char* b2 = last ? nB : cB + (size_t)(t + 2) * kstep;
;             const char* a3 = a2 + kstep; const char* b3 = b2 + kstep;
;             if (last && has_next) S.a_ready(nxt);
;             if constexpr (SP2) {
;             PG8_LDB(B0, 0, 0); PG8_LDB(B1, 0, 1); PG8_SCHED; PG8_LDA(At, 0, 0); PG8_STAGE(PG8_SA(1, 1), a1 + hstep, voffA);
;             PG8_WAIT_V(8); PG8_WAIT_L(0); PG8_BAR; PG8_MMA(0, 0, At, B0); PG8_MMA(0, 1, At, B1); PG8_BAR; PG8_SCHED;
;             PG8_LDA(At, 0, 1); PG8_STAGE(PG8_SB(0, 0), b2, voffB); PG8_STAGE(PG8_SB(0, 1), b2 + hstep, voffB); PG8_STAGE(PG8_SA(0, 0), a2, voffA);
;             PG8_WAIT_V(8); PG8_WAIT_L(0); PG8_BAR; PG8_MMA(1, 0, At, B0); PG8_MMA(1, 1, At, B1); PG8_BAR; PG8_SCHED;
.LBB0_798:
	s_cmp_eq_u32 s63, 12
	s_cbranch_scc0 .Lkf3_norm
	s_cmp_eq_u64 s[8:9], 0
	s_cbranch_scc1 .Lkf3_fin
.Lkf3_norm:
	ds_read_b128 v[146:149], v152
	ds_read_b128 v[156:159], v152 offset:1024
	ds_read_b128 v[160:163], v152 offset:2048
	ds_read_b128 v[164:167], v152 offset:3072
	ds_read_b128 v[168:171], v153
	ds_read_b128 v[172:175], v153 offset:1024
	ds_read_b128 v[176:179], v153 offset:2048
	ds_read_b128 v[180:183], v153 offset:3072
	s_add_u32 s46, s44, 0xfffc0080
	s_addc_u32 s47, s45, -1
	s_cmp_eq_u32 s63, 12
	s_cselect_b32 s49, s35, s47
	s_cselect_b32 s48, s41, s46
	s_cselect_b32 s47, s31, s62
	s_cselect_b32 s46, s60, s61
	s_add_i32 m0, s43, 0xc000
	ds_read_b128 v[184:187], v154
	ds_read_b128 v[188:191], v154 offset:1024
	ds_read_b128 v[192:195], v154 offset:2048
	ds_read_b128 v[196:199], v154 offset:3072
	ds_read_b128 v[200:203], v154 offset:4096
	ds_read_b128 v[206:209], v154 offset:5120
	ds_read_b128 v[210:213], v154 offset:6144
	ds_read_b128 v[214:217], v154 offset:7168
	global_load_lds_dwordx4 v138, s[44:45]
	s_add_i32 m0, s43, 0xe000
	s_nop 0
	global_load_lds_dwordx4 v140, s[44:45]
	s_waitcnt vmcnt(8)
	s_waitcnt lgkmcnt(0)
	s_setprio 1
	s_barrier
	v_mfma_f32_16x16x32_bf16 v[124:127], v[146:149], v[184:187], v[124:127]
	v_mfma_f32_16x16x32_bf16 v[120:123], v[160:163], v[184:187], v[120:123]
	v_mfma_f32_16x16x32_bf16 v[108:111], v[146:149], v[192:195], v[108:111]
	v_mfma_f32_16x16x32_bf16 v[104:107], v[160:163], v[192:195], v[104:107]
	v_mfma_f32_16x16x32_bf16 v[92:95], v[146:149], v[200:203], v[92:95]
	v_mfma_f32_16x16x32_bf16 v[88:91], v[160:163], v[200:203], v[88:91]
	v_mfma_f32_16x16x32_bf16 v[76:79], v[146:149], v[210:213], v[76:79]
	v_mfma_f32_16x16x32_bf16 v[72:75], v[160:163], v[210:213], v[72:75]
	v_mfma_f32_16x16x32_bf16 v[124:127], v[156:159], v[188:191], v[124:127]
	v_mfma_f32_16x16x32_bf16 v[120:123], v[164:167], v[188:191], v[120:123]
	v_mfma_f32_16x16x32_bf16 v[108:111], v[156:159], v[196:199], v[108:111]
	v_mfma_f32_16x16x32_bf16 v[104:107], v[164:167], v[196:199], v[104:107]
	v_mfma_f32_16x16x32_bf16 v[92:95], v[156:159], v[206:209], v[92:95]
	v_mfma_f32_16x16x32_bf16 v[88:91], v[164:167], v[206:209], v[88:91]
	v_mfma_f32_16x16x32_bf16 v[76:79], v[156:159], v[214:217], v[76:79]
	v_mfma_f32_16x16x32_bf16 v[72:75], v[164:167], v[214:217], v[72:75]
	v_mfma_f32_16x16x32_bf16 v[116:119], v[168:171], v[184:187], v[116:119]
	v_mfma_f32_16x16x32_bf16 v[112:115], v[176:179], v[184:187], v[112:115]
	v_mfma_f32_16x16x32_bf16 v[100:103], v[168:171], v[192:195], v[100:103]
	v_mfma_f32_16x16x32_bf16 v[96:99], v[176:179], v[192:195], v[96:99]
	v_mfma_f32_16x16x32_bf16 v[84:87], v[168:171], v[200:203], v[84:87]
	v_mfma_f32_16x16x32_bf16 v[80:83], v[176:179], v[200:203], v[80:83]
	v_mfma_f32_16x16x32_bf16 v[68:71], v[168:171], v[210:213], v[68:71]
	v_mfma_f32_16x16x32_bf16 v[64:67], v[176:179], v[210:213], v[64:67]
	v_mfma_f32_16x16x32_bf16 v[116:119], v[172:175], v[188:191], v[116:119]
	v_mfma_f32_16x16x32_bf16 v[112:115], v[180:183], v[188:191], v[112:115]
	v_mfma_f32_16x16x32_bf16 v[100:103], v[172:175], v[196:199], v[100:103]
	v_mfma_f32_16x16x32_bf16 v[96:99], v[180:183], v[196:199], v[96:99]
	v_mfma_f32_16x16x32_bf16 v[84:87], v[172:175], v[206:209], v[84:87]
	v_mfma_f32_16x16x32_bf16 v[80:83], v[180:183], v[206:209], v[80:83]
	v_mfma_f32_16x16x32_bf16 v[68:71], v[172:175], v[214:217], v[68:71]
	v_mfma_f32_16x16x32_bf16 v[64:67], v[180:183], v[214:217], v[64:67]
	s_setprio 0
	s_barrier
	s_add_i32 s64, s58, s33
	s_mov_b32 m0, s64
	ds_read_b128 v[184:187], v154 offset:16384
	ds_read_b128 v[188:191], v154 offset:17408
	ds_read_b128 v[192:195], v154 offset:18432
	ds_read_b128 v[196:199], v154 offset:19456
	ds_read_b128 v[200:203], v154 offset:20480
	ds_read_b128 v[206:209], v154 offset:21504
	ds_read_b128 v[210:213], v154 offset:22528
	ds_read_b128 v[214:217], v154 offset:23552
	global_load_lds_dwordx4 v132, s[46:47]
	s_add_i32 m0, s64, 0x2000
	s_add_u32 s98, s46, 0x80
	s_addc_u32 s99, s47, 0
	s_add_u32 s64, s46, 0x40000
	s_addc_u32 s65, s47, 0
	s_add_i32 s66, s59, s33
	global_load_lds_dwordx4 v136, s[46:47]
	s_mov_b32 m0, s66
	s_nop 0
	global_load_lds_dwordx4 v132, s[64:65]
	s_add_i32 m0, s66, 0x2000
	s_nop 0
	global_load_lds_dwordx4 v136, s[64:65]
	s_mov_b32 m0, s43
	s_nop 0
	global_load_lds_dwordx4 v130, s[48:49]
	s_mov_b32 m0, s50
	s_nop 0
	global_load_lds_dwordx4 v134, s[48:49]
	s_waitcnt vmcnt(8)
	s_waitcnt lgkmcnt(0)
	s_setprio 1
	s_barrier
	v_mfma_f32_16x16x32_bf16 v[60:63], v[146:149], v[184:187], v[60:63]
	v_mfma_f32_16x16x32_bf16 v[56:59], v[160:163], v[184:187], v[56:59]
	v_mfma_f32_16x16x32_bf16 v[44:47], v[146:149], v[192:195], v[44:47]
	v_mfma_f32_16x16x32_bf16 v[40:43], v[160:163], v[192:195], v[40:43]
	v_mfma_f32_16x16x32_bf16 v[28:31], v[146:149], v[200:203], v[28:31]
	v_mfma_f32_16x16x32_bf16 v[24:27], v[160:163], v[200:203], v[24:27]
	v_mfma_f32_16x16x32_bf16 v[12:15], v[146:149], v[210:213], v[12:15]
	v_mfma_f32_16x16x32_bf16 v[8:11], v[160:163], v[210:213], v[8:11]
	v_mfma_f32_16x16x32_bf16 v[60:63], v[156:159], v[188:191], v[60:63]
	v_mfma_f32_16x16x32_bf16 v[56:59], v[164:167], v[188:191], v[56:59]
	v_mfma_f32_16x16x32_bf16 v[44:47], v[156:159], v[196:199], v[44:47]
	v_mfma_f32_16x16x32_bf16 v[40:43], v[164:167], v[196:199], v[40:43]
	v_mfma_f32_16x16x32_bf16 v[28:31], v[156:159], v[206:209], v[28:31]
	v_mfma_f32_16x16x32_bf16 v[24:27], v[164:167], v[206:209], v[24:27]
	v_mfma_f32_16x16x32_bf16 v[12:15], v[156:159], v[214:217], v[12:15]
	v_mfma_f32_16x16x32_bf16 v[8:11], v[164:167], v[214:217], v[8:11]
	v_mfma_f32_16x16x32_bf16 v[52:55], v[168:171], v[184:187], v[52:55]
	v_mfma_f32_16x16x32_bf16 v[48:51], v[176:179], v[184:187], v[48:51]
	v_mfma_f32_16x16x32_bf16 v[36:39], v[168:171], v[192:195], v[36:39]
	v_mfma_f32_16x16x32_bf16 v[32:35], v[176:179], v[192:195], v[32:35]
	v_mfma_f32_16x16x32_bf16 v[20:23], v[168:171], v[200:203], v[20:23]
	v_mfma_f32_16x16x32_bf16 v[16:19], v[176:179], v[200:203], v[16:19]
	v_mfma_f32_16x16x32_bf16 v[4:7], v[168:171], v[210:213], v[4:7]
	v_mfma_f32_16x16x32_bf16 v[0:3], v[176:179], v[210:213], v[0:3]
	v_mfma_f32_16x16x32_bf16 v[52:55], v[172:175], v[188:191], v[52:55]
	v_mfma_f32_16x16x32_bf16 v[48:51], v[180:183], v[188:191], v[48:51]
	v_mfma_f32_16x16x32_bf16 v[36:39], v[172:175], v[196:199], v[36:39]
	v_mfma_f32_16x16x32_bf16 v[32:35], v[180:183], v[196:199], v[32:35]
	v_mfma_f32_16x16x32_bf16 v[20:23], v[172:175], v[206:209], v[20:23]
	v_mfma_f32_16x16x32_bf16 v[16:19], v[180:183], v[206:209], v[16:19]
	v_mfma_f32_16x16x32_bf16 v[4:7], v[172:175], v[214:217], v[4:7]
	v_mfma_f32_16x16x32_bf16 v[0:3], v[180:183], v[214:217], v[0:3]
	s_setprio 0
	s_barrier
; #define PG8_STAGE(bufoff, gbase, voff) do { _Pragma("unroll") for (int _i = 0; _i < 2; ++_i) \
;         __builtin_amdgcn_global_load_lds((const unsigned*)((const char*)(gbase) + (voff)[_i]), (PG8_LAS unsigned*)(lds + (bufoff) + ldsw + _i * 8192), 16, 0, 0); } while (0)
; #define PG8_LDA(dst, b, h) do { _Pragma("unroll") for (int m = 0; m < 4; ++m) _Pragma("unroll") for (int k = 0; k < 2; ++k) dst[m][k] = *(const PG8_LAS bf16x8*)(lds + PG8_SA(b, h) + aoff + m * 2048 + k * 1024); } while (0)
; #define PG8_LDB(dst, b, h) do { _Pragma("unroll") for (int n = 0; n < 2; ++n) _Pragma("unroll") for (int k = 0; k < 2; ++k) dst[n][k] = *(const PG8_LAS bf16x8*)(lds + PG8_SB(b, h) + boff + n * 2048 + k * 1024); } while (0)
; #define PG8_MMA(ai, bj, At, Bt) do { __builtin_amdgcn_s_setprio(1); _Pragma("unroll") for (int m = 0; m < 4; ++m) _Pragma("unroll") for (int n = 0; n < 2; ++n) _Pragma("unroll") for (int k = 0; k < 2; ++k) \
;         acc[ai][bj][m][n] = __builtin_amdgcn_mfma_f32_16x16x32_bf16(Bt[n][k], At[m][k], acc[ai][bj][m][n], 0, 0, 0); __builtin_amdgcn_s_setprio(0); } while (0)
; #define PG8_WAIT_V(n) asm volatile("s_waitcnt vmcnt(" #n ")" ::: "memory")
; #define PG8_WAIT_L(n) asm volatile("s_waitcnt lgkmcnt(" #n ")" ::: "memory")
; #define PG8_BAR __builtin_amdgcn_s_barrier()
; #define PG8_SCHED __builtin_amdgcn_sched_barrier(0)
; template <class Epi, class Sched, bool ALIGN_EPI = false, bool SP2 = false>
; __device__ __forceinline__ void gemm_phase(PG8_LAS unsigned char* lds, const Gemm g, const Sched& S, const Epi& E) {
;     ...
;             PG8_LDB(B0, 1, 0); PG8_LDB(B1, 1, 1); PG8_SCHED; PG8_LDA(At, 1, 0); PG8_STAGE(PG8_SA(0, 1), a2 + hstep, voffA);
;             PG8_WAIT_V(8); PG8_WAIT_L(0); PG8_BAR; PG8_MMA(0, 0, At, B0); PG8_MMA(0, 1, At, B1); PG8_BAR; PG8_SCHED;
;             PG8_LDA(At, 1, 1); PG8_STAGE(PG8_SB(1, 0), b3, voffB); PG8_STAGE(PG8_SB(1, 1), b3 + hstep, voffB); PG8_STAGE(PG8_SA(1, 0), a3, voffA);
;             PG8_WAIT_V(8); PG8_WAIT_L(0); PG8_BAR; PG8_MMA(1, 0, At, B0); PG8_MMA(1, 1, At, B1); PG8_BAR; PG8_SCHED;
	s_add_i32 s64, 0, 0x18000
	s_add_i32 s65, 0, 0x1c000
	ds_read_b128 v[146:149], v240
	ds_read_b128 v[156:159], v240 offset:1024
	ds_read_b128 v[160:163], v240 offset:2048
	ds_read_b128 v[164:167], v240 offset:3072
	ds_read_b128 v[168:171], v241
	ds_read_b128 v[172:175], v241 offset:1024
	ds_read_b128 v[176:179], v241 offset:2048
	ds_read_b128 v[180:183], v241 offset:3072
	s_add_u32 s100, s48, 0x80
	s_addc_u32 s101, s49, 0
	s_add_u32 s48, s48, 0x40000
	s_addc_u32 s49, s49, 0
	s_mov_b32 m0, s51
	ds_read_b128 v[184:187], v154 offset:32768
	ds_read_b128 v[188:191], v154 offset:33792
	ds_read_b128 v[192:195], v154 offset:34816
	ds_read_b128 v[196:199], v154 offset:35840
	ds_read_b128 v[200:203], v154 offset:36864
	ds_read_b128 v[206:209], v154 offset:37888
	ds_read_b128 v[210:213], v154 offset:38912
	ds_read_b128 v[214:217], v154 offset:39936
	global_load_lds_dwordx4 v130, s[48:49]
	s_mov_b32 m0, s52
	s_nop 0
	global_load_lds_dwordx4 v134, s[48:49]
	s_waitcnt vmcnt(8)
	s_waitcnt lgkmcnt(0)
	s_setprio 1
	s_barrier
	v_mfma_f32_16x16x32_bf16 v[124:127], v[146:149], v[184:187], v[124:127]
	v_mfma_f32_16x16x32_bf16 v[120:123], v[160:163], v[184:187], v[120:123]
	v_mfma_f32_16x16x32_bf16 v[108:111], v[146:149], v[192:195], v[108:111]
	v_mfma_f32_16x16x32_bf16 v[104:107], v[160:163], v[192:195], v[104:107]
	v_mfma_f32_16x16x32_bf16 v[92:95], v[146:149], v[200:203], v[92:95]
	v_mfma_f32_16x16x32_bf16 v[88:91], v[160:163], v[200:203], v[88:91]
	v_mfma_f32_16x16x32_bf16 v[76:79], v[146:149], v[210:213], v[76:79]
	v_mfma_f32_16x16x32_bf16 v[72:75], v[160:163], v[210:213], v[72:75]
	v_mfma_f32_16x16x32_bf16 v[124:127], v[156:159], v[188:191], v[124:127]
	v_mfma_f32_16x16x32_bf16 v[120:123], v[164:167], v[188:191], v[120:123]
	v_mfma_f32_16x16x32_bf16 v[108:111], v[156:159], v[196:199], v[108:111]
	v_mfma_f32_16x16x32_bf16 v[104:107], v[164:167], v[196:199], v[104:107]
	v_mfma_f32_16x16x32_bf16 v[92:95], v[156:159], v[206:209], v[92:95]
	v_mfma_f32_16x16x32_bf16 v[88:91], v[164:167], v[206:209], v[88:91]
	v_mfma_f32_16x16x32_bf16 v[76:79], v[156:159], v[214:217], v[76:79]
	v_mfma_f32_16x16x32_bf16 v[72:75], v[164:167], v[214:217], v[72:75]
	v_mfma_f32_16x16x32_bf16 v[116:119], v[168:171], v[184:187], v[116:119]
	v_mfma_f32_16x16x32_bf16 v[112:115], v[176:179], v[184:187], v[112:115]
	v_mfma_f32_16x16x32_bf16 v[100:103], v[168:171], v[192:195], v[100:103]
	v_mfma_f32_16x16x32_bf16 v[96:99], v[176:179], v[192:195], v[96:99]
	v_mfma_f32_16x16x32_bf16 v[84:87], v[168:171], v[200:203], v[84:87]
	v_mfma_f32_16x16x32_bf16 v[80:83], v[176:179], v[200:203], v[80:83]
	v_mfma_f32_16x16x32_bf16 v[68:71], v[168:171], v[210:213], v[68:71]
	v_mfma_f32_16x16x32_bf16 v[64:67], v[176:179], v[210:213], v[64:67]
	v_mfma_f32_16x16x32_bf16 v[116:119], v[172:175], v[188:191], v[116:119]
	v_mfma_f32_16x16x32_bf16 v[112:115], v[180:183], v[188:191], v[112:115]
	v_mfma_f32_16x16x32_bf16 v[100:103], v[172:175], v[196:199], v[100:103]
	v_mfma_f32_16x16x32_bf16 v[96:99], v[180:183], v[196:199], v[96:99]
	v_mfma_f32_16x16x32_bf16 v[84:87], v[172:175], v[206:209], v[84:87]
	v_mfma_f32_16x16x32_bf16 v[80:83], v[180:183], v[206:209], v[80:83]
	v_mfma_f32_16x16x32_bf16 v[68:71], v[172:175], v[214:217], v[68:71]
	v_mfma_f32_16x16x32_bf16 v[64:67], v[180:183], v[214:217], v[64:67]
	s_setprio 0
	s_barrier
	s_add_i32 s48, s64, s33
	s_mov_b32 m0, s48
	ds_read_b128 v[184:187], v154 offset:49152
	ds_read_b128 v[188:191], v154 offset:50176
	ds_read_b128 v[192:195], v154 offset:51200
	ds_read_b128 v[196:199], v154 offset:52224
	ds_read_b128 v[200:203], v154 offset:53248
	ds_read_b128 v[206:209], v154 offset:54272
	ds_read_b128 v[210:213], v154 offset:55296
	ds_read_b128 v[214:217], v154 offset:56320
	global_load_lds_dwordx4 v132, s[98:99]
	s_add_i32 m0, s48, 0x2000
	s_add_u32 s46, s46, 0x40080
	s_addc_u32 s47, s47, 0
	s_add_i32 s48, s65, s33
	global_load_lds_dwordx4 v136, s[98:99]
	s_mov_b32 m0, s48
	s_nop 0
	global_load_lds_dwordx4 v132, s[46:47]
	s_add_i32 m0, s48, 0x2000
	s_nop 0
	global_load_lds_dwordx4 v136, s[46:47]
	s_mov_b32 m0, s54
	s_nop 0
	global_load_lds_dwordx4 v130, s[100:101]
	s_mov_b32 m0, s55
	s_nop 0
	global_load_lds_dwordx4 v134, s[100:101]
	s_waitcnt vmcnt(8)
	s_waitcnt lgkmcnt(0)
	s_setprio 1
	s_barrier
	v_mfma_f32_16x16x32_bf16 v[60:63], v[146:149], v[184:187], v[60:63]
	v_mfma_f32_16x16x32_bf16 v[56:59], v[160:163], v[184:187], v[56:59]
	v_mfma_f32_16x16x32_bf16 v[44:47], v[146:149], v[192:195], v[44:47]
	v_mfma_f32_16x16x32_bf16 v[40:43], v[160:163], v[192:195], v[40:43]
	v_mfma_f32_16x16x32_bf16 v[28:31], v[146:149], v[200:203], v[28:31]
	v_mfma_f32_16x16x32_bf16 v[24:27], v[160:163], v[200:203], v[24:27]
	v_mfma_f32_16x16x32_bf16 v[12:15], v[146:149], v[210:213], v[12:15]
	v_mfma_f32_16x16x32_bf16 v[8:11], v[160:163], v[210:213], v[8:11]
	v_mfma_f32_16x16x32_bf16 v[60:63], v[156:159], v[188:191], v[60:63]
	v_mfma_f32_16x16x32_bf16 v[56:59], v[164:167], v[188:191], v[56:59]
	v_mfma_f32_16x16x32_bf16 v[44:47], v[156:159], v[196:199], v[44:47]
	v_mfma_f32_16x16x32_bf16 v[40:43], v[164:167], v[196:199], v[40:43]
	v_mfma_f32_16x16x32_bf16 v[28:31], v[156:159], v[206:209], v[28:31]
	v_mfma_f32_16x16x32_bf16 v[24:27], v[164:167], v[206:209], v[24:27]
	v_mfma_f32_16x16x32_bf16 v[12:15], v[156:159], v[214:217], v[12:15]
	v_mfma_f32_16x16x32_bf16 v[8:11], v[164:167], v[214:217], v[8:11]
	v_mfma_f32_16x16x32_bf16 v[52:55], v[168:171], v[184:187], v[52:55]
	v_mfma_f32_16x16x32_bf16 v[48:51], v[176:179], v[184:187], v[48:51]
	v_mfma_f32_16x16x32_bf16 v[36:39], v[168:171], v[192:195], v[36:39]
	v_mfma_f32_16x16x32_bf16 v[32:35], v[176:179], v[192:195], v[32:35]
	v_mfma_f32_16x16x32_bf16 v[20:23], v[168:171], v[200:203], v[20:23]
	v_mfma_f32_16x16x32_bf16 v[16:19], v[176:179], v[200:203], v[16:19]
	v_mfma_f32_16x16x32_bf16 v[4:7], v[168:171], v[210:213], v[4:7]
	v_mfma_f32_16x16x32_bf16 v[0:3], v[176:179], v[210:213], v[0:3]
	v_mfma_f32_16x16x32_bf16 v[52:55], v[172:175], v[188:191], v[52:55]
	v_mfma_f32_16x16x32_bf16 v[48:51], v[180:183], v[188:191], v[48:51]
	v_mfma_f32_16x16x32_bf16 v[36:39], v[172:175], v[196:199], v[36:39]
	v_mfma_f32_16x16x32_bf16 v[32:35], v[180:183], v[196:199], v[32:35]
	v_mfma_f32_16x16x32_bf16 v[20:23], v[172:175], v[206:209], v[20:23]
	v_mfma_f32_16x16x32_bf16 v[16:19], v[180:183], v[206:209], v[16:19]
	v_mfma_f32_16x16x32_bf16 v[4:7], v[172:175], v[214:217], v[4:7]
	v_mfma_f32_16x16x32_bf16 v[0:3], v[180:183], v[214:217], v[0:3]
	s_setprio 0
	s_barrier
	s_add_i32 s63, s63, 2
	s_add_u32 s44, s44, 0x100
	s_addc_u32 s45, s45, 0
	s_add_u32 s61, s61, 0x100
	s_addc_u32 s62, s62, 0
	s_cmp_gt_u32 s63, 13
	s_cbranch_scc0 .LBB0_798
	s_branch .Lkf3_exit
; #define PG8_STAGE(bufoff, gbase, voff) do { _Pragma("unroll") for (int _i = 0; _i < 2; ++_i) \
;         __builtin_amdgcn_global_load_lds((const unsigned*)((const char*)(gbase) + (voff)[_i]), (PG8_LAS unsigned*)(lds + (bufoff) + ldsw + _i * 8192), 16, 0, 0); } while (0)
; #define PG8_LDA(dst, b, h) do { _Pragma("unroll") for (int m = 0; m < 4; ++m) _Pragma("unroll") for (int k = 0; k < 2; ++k) dst[m][k] = *(const PG8_LAS bf16x8*)(lds + PG8_SA(b, h) + aoff + m * 2048 + k * 1024); } while (0)
; #define PG8_LDB(dst, b, h) do { _Pragma("unroll") for (int n = 0; n < 2; ++n) _Pragma("unroll") for (int k = 0; k < 2; ++k) dst[n][k] = *(const PG8_LAS bf16x8*)(lds + PG8_SB(b, h) + boff + n * 2048 + k * 1024); } while (0)
; #define PG8_MMA(ai, bj, At, Bt) do { __builtin_amdgcn_s_setprio(1); _Pragma("unroll") for (int m = 0; m < 4; ++m) _Pragma("unroll") for (int n = 0; n < 2; ++n) _Pragma("unroll") for (int k = 0; k < 2; ++k) \
;         acc[ai][bj][m][n] = __builtin_amdgcn_mfma_f32_16x16x32_bf16(Bt[n][k], At[m][k], acc[ai][bj][m][n], 0, 0, 0); __builtin_amdgcn_s_setprio(0); } while (0)
; #define PG8_WAIT_V(n) asm volatile("s_waitcnt vmcnt(" #n ")" ::: "memory")
; #define PG8_WAIT_L(n) asm volatile("s_waitcnt lgkmcnt(" #n ")" ::: "memory")
; #define PG8_BAR __builtin_amdgcn_s_barrier()
; #define PG8_SCHED __builtin_amdgcn_sched_barrier(0)
; template <class Epi, class Sched, bool ALIGN_EPI = false, bool SP2 = false>
; __device__ __forceinline__ void gemm_phase(PG8_LAS unsigned char* lds, const Gemm g, const Sched& S, const Epi& E) {
;     ...
;             PG8_LDB(B0, 0, 0); PG8_LDB(B1, 0, 1); PG8_SCHED; PG8_LDA(At, 0, 0); PG8_STAGE(PG8_SA(1, 1), a1 + hstep, voffA);
;             PG8_WAIT_V(8); PG8_WAIT_L(0); PG8_BAR; PG8_MMA(0, 0, At, B0); PG8_MMA(0, 1, At, B1); PG8_BAR; PG8_SCHED;
;             PG8_LDA(At, 0, 1); PG8_STAGE(PG8_SB(0, 0), b2, voffB); PG8_STAGE(PG8_SB(0, 1), b2 + hstep, voffB); PG8_STAGE(PG8_SA(0, 0), a2, voffA);
;             PG8_WAIT_V(8); PG8_WAIT_L(0); PG8_BAR; PG8_MMA(1, 0, At, B0); PG8_MMA(1, 1, At, B1); PG8_BAR; PG8_SCHED;
.Lkf3_fin:
	ds_read_b128 v[146:149], v152
	ds_read_b128 v[156:159], v152 offset:1024
	ds_read_b128 v[160:163], v152 offset:2048
	ds_read_b128 v[164:167], v152 offset:3072
	ds_read_b128 v[168:171], v153
	ds_read_b128 v[172:175], v153 offset:1024
	ds_read_b128 v[176:179], v153 offset:2048
	ds_read_b128 v[180:183], v153 offset:3072
	s_add_u32 s46, s44, 0xfffc0080
	s_addc_u32 s47, s45, -1
	s_cmp_eq_u32 s63, 12
	s_cselect_b32 s49, s35, s47
	s_cselect_b32 s48, s41, s46
	s_cselect_b32 s47, s31, s62
	s_cselect_b32 s46, s60, s61
	s_add_i32 m0, s43, 0xc000
	ds_read_b128 v[184:187], v154
	ds_read_b128 v[188:191], v154 offset:1024
	ds_read_b128 v[192:195], v154 offset:2048
	ds_read_b128 v[196:199], v154 offset:3072
	ds_read_b128 v[200:203], v154 offset:4096
	ds_read_b128 v[206:209], v154 offset:5120
	ds_read_b128 v[210:213], v154 offset:6144
	ds_read_b128 v[214:217], v154 offset:7168
	global_load_lds_dwordx4 v138, s[44:45]
	s_add_i32 m0, s43, 0xe000
	s_nop 0
	global_load_lds_dwordx4 v140, s[44:45]
	s_waitcnt vmcnt(8)
	s_waitcnt lgkmcnt(0)
	s_setprio 1
	s_barrier
	v_mfma_f32_16x16x32_bf16 v[124:127], v[146:149], v[184:187], v[124:127]
	v_mfma_f32_16x16x32_bf16 v[120:123], v[160:163], v[184:187], v[120:123]
	v_mfma_f32_16x16x32_bf16 v[108:111], v[146:149], v[192:195], v[108:111]
	v_mfma_f32_16x16x32_bf16 v[104:107], v[160:163], v[192:195], v[104:107]
	v_mfma_f32_16x16x32_bf16 v[92:95], v[146:149], v[200:203], v[92:95]
	v_mfma_f32_16x16x32_bf16 v[88:91], v[160:163], v[200:203], v[88:91]
	v_mfma_f32_16x16x32_bf16 v[76:79], v[146:149], v[210:213], v[76:79]
	v_mfma_f32_16x16x32_bf16 v[72:75], v[160:163], v[210:213], v[72:75]
	v_mfma_f32_16x16x32_bf16 v[124:127], v[156:159], v[188:191], v[124:127]
	v_mfma_f32_16x16x32_bf16 v[120:123], v[164:167], v[188:191], v[120:123]
	v_mfma_f32_16x16x32_bf16 v[108:111], v[156:159], v[196:199], v[108:111]
	v_mfma_f32_16x16x32_bf16 v[104:107], v[164:167], v[196:199], v[104:107]
	v_mfma_f32_16x16x32_bf16 v[92:95], v[156:159], v[206:209], v[92:95]
	v_mfma_f32_16x16x32_bf16 v[88:91], v[164:167], v[206:209], v[88:91]
	v_mfma_f32_16x16x32_bf16 v[76:79], v[156:159], v[214:217], v[76:79]
	v_mfma_f32_16x16x32_bf16 v[72:75], v[164:167], v[214:217], v[72:75]
	v_mfma_f32_16x16x32_bf16 v[116:119], v[168:171], v[184:187], v[116:119]
	v_mfma_f32_16x16x32_bf16 v[112:115], v[176:179], v[184:187], v[112:115]
	v_mfma_f32_16x16x32_bf16 v[100:103], v[168:171], v[192:195], v[100:103]
	v_mfma_f32_16x16x32_bf16 v[96:99], v[176:179], v[192:195], v[96:99]
	v_mfma_f32_16x16x32_bf16 v[84:87], v[168:171], v[200:203], v[84:87]
	v_mfma_f32_16x16x32_bf16 v[80:83], v[176:179], v[200:203], v[80:83]
	v_mfma_f32_16x16x32_bf16 v[68:71], v[168:171], v[210:213], v[68:71]
	v_mfma_f32_16x16x32_bf16 v[64:67], v[176:179], v[210:213], v[64:67]
	v_mfma_f32_16x16x32_bf16 v[116:119], v[172:175], v[188:191], v[116:119]
	v_mfma_f32_16x16x32_bf16 v[112:115], v[180:183], v[188:191], v[112:115]
	v_mfma_f32_16x16x32_bf16 v[100:103], v[172:175], v[196:199], v[100:103]
	v_mfma_f32_16x16x32_bf16 v[96:99], v[180:183], v[196:199], v[96:99]
	v_mfma_f32_16x16x32_bf16 v[84:87], v[172:175], v[206:209], v[84:87]
	v_mfma_f32_16x16x32_bf16 v[80:83], v[180:183], v[206:209], v[80:83]
	v_mfma_f32_16x16x32_bf16 v[68:71], v[172:175], v[214:217], v[68:71]
	v_mfma_f32_16x16x32_bf16 v[64:67], v[180:183], v[214:217], v[64:67]
	s_setprio 0
	s_barrier
	s_add_i32 s64, s58, s33
	s_mov_b32 m0, s64
	ds_read_b128 v[184:187], v154 offset:16384
	ds_read_b128 v[188:191], v154 offset:17408
	ds_read_b128 v[192:195], v154 offset:18432
	ds_read_b128 v[196:199], v154 offset:19456
	ds_read_b128 v[200:203], v154 offset:20480
	ds_read_b128 v[206:209], v154 offset:21504
	ds_read_b128 v[210:213], v154 offset:22528
	ds_read_b128 v[214:217], v154 offset:23552
	s_waitcnt vmcnt(2)
	s_waitcnt lgkmcnt(0)
	s_setprio 1
	s_barrier
	v_mfma_f32_16x16x32_bf16 v[60:63], v[146:149], v[184:187], v[60:63]
	v_mfma_f32_16x16x32_bf16 v[56:59], v[160:163], v[184:187], v[56:59]
	v_mfma_f32_16x16x32_bf16 v[44:47], v[146:149], v[192:195], v[44:47]
	v_mfma_f32_16x16x32_bf16 v[40:43], v[160:163], v[192:195], v[40:43]
	v_mfma_f32_16x16x32_bf16 v[28:31], v[146:149], v[200:203], v[28:31]
	v_mfma_f32_16x16x32_bf16 v[24:27], v[160:163], v[200:203], v[24:27]
	v_mfma_f32_16x16x32_bf16 v[12:15], v[146:149], v[210:213], v[12:15]
	v_mfma_f32_16x16x32_bf16 v[8:11], v[160:163], v[210:213], v[8:11]
	v_mfma_f32_16x16x32_bf16 v[60:63], v[156:159], v[188:191], v[60:63]
	v_mfma_f32_16x16x32_bf16 v[56:59], v[164:167], v[188:191], v[56:59]
	v_mfma_f32_16x16x32_bf16 v[44:47], v[156:159], v[196:199], v[44:47]
	v_mfma_f32_16x16x32_bf16 v[40:43], v[164:167], v[196:199], v[40:43]
	v_mfma_f32_16x16x32_bf16 v[28:31], v[156:159], v[206:209], v[28:31]
	v_mfma_f32_16x16x32_bf16 v[24:27], v[164:167], v[206:209], v[24:27]
	v_mfma_f32_16x16x32_bf16 v[12:15], v[156:159], v[214:217], v[12:15]
	v_mfma_f32_16x16x32_bf16 v[8:11], v[164:167], v[214:217], v[8:11]
	v_mfma_f32_16x16x32_bf16 v[52:55], v[168:171], v[184:187], v[52:55]
	v_mfma_f32_16x16x32_bf16 v[48:51], v[176:179], v[184:187], v[48:51]
	v_mfma_f32_16x16x32_bf16 v[36:39], v[168:171], v[192:195], v[36:39]
	v_mfma_f32_16x16x32_bf16 v[32:35], v[176:179], v[192:195], v[32:35]
	v_mfma_f32_16x16x32_bf16 v[20:23], v[168:171], v[200:203], v[20:23]
	v_mfma_f32_16x16x32_bf16 v[16:19], v[176:179], v[200:203], v[16:19]
	v_mfma_f32_16x16x32_bf16 v[4:7], v[168:171], v[210:213], v[4:7]
	v_mfma_f32_16x16x32_bf16 v[0:3], v[176:179], v[210:213], v[0:3]
	v_mfma_f32_16x16x32_bf16 v[52:55], v[172:175], v[188:191], v[52:55]
	v_mfma_f32_16x16x32_bf16 v[48:51], v[180:183], v[188:191], v[48:51]
	v_mfma_f32_16x16x32_bf16 v[36:39], v[172:175], v[196:199], v[36:39]
	v_mfma_f32_16x16x32_bf16 v[32:35], v[180:183], v[196:199], v[32:35]
	v_mfma_f32_16x16x32_bf16 v[20:23], v[172:175], v[206:209], v[20:23]
	v_mfma_f32_16x16x32_bf16 v[16:19], v[180:183], v[206:209], v[16:19]
	v_mfma_f32_16x16x32_bf16 v[4:7], v[172:175], v[214:217], v[4:7]
	v_mfma_f32_16x16x32_bf16 v[0:3], v[180:183], v[214:217], v[0:3]
	s_setprio 0
	s_barrier
; #define PG8_STAGE(bufoff, gbase, voff) do { _Pragma("unroll") for (int _i = 0; _i < 2; ++_i) \
;         __builtin_amdgcn_global_load_lds((const unsigned*)((const char*)(gbase) + (voff)[_i]), (PG8_LAS unsigned*)(lds + (bufoff) + ldsw + _i * 8192), 16, 0, 0); } while (0)
; #define PG8_LDA(dst, b, h) do { _Pragma("unroll") for (int m = 0; m < 4; ++m) _Pragma("unroll") for (int k = 0; k < 2; ++k) dst[m][k] = *(const PG8_LAS bf16x8*)(lds + PG8_SA(b, h) + aoff + m * 2048 + k * 1024); } while (0)
; #define PG8_LDB(dst, b, h) do { _Pragma("unroll") for (int n = 0; n < 2; ++n) _Pragma("unroll") for (int k = 0; k < 2; ++k) dst[n][k] = *(const PG8_LAS bf16x8*)(lds + PG8_SB(b, h) + boff + n * 2048 + k * 1024); } while (0)
; #define PG8_MMA(ai, bj, At, Bt) do { __builtin_amdgcn_s_setprio(1); _Pragma("unroll") for (int m = 0; m < 4; ++m) _Pragma("unroll") for (int n = 0; n < 2; ++n) _Pragma("unroll") for (int k = 0; k < 2; ++k) \
;         acc[ai][bj][m][n] = __builtin_amdgcn_mfma_f32_16x16x32_bf16(Bt[n][k], At[m][k], acc[ai][bj][m][n], 0, 0, 0); __builtin_amdgcn_s_setprio(0); } while (0)
; #define PG8_WAIT_V(n) asm volatile("s_waitcnt vmcnt(" #n ")" ::: "memory")
; #define PG8_WAIT_L(n) asm volatile("s_waitcnt lgkmcnt(" #n ")" ::: "memory")
; #define PG8_BAR __builtin_amdgcn_s_barrier()
; #define PG8_SCHED __builtin_amdgcn_sched_barrier(0)
; template <class Epi, class Sched, bool ALIGN_EPI = false, bool SP2 = false>
; __device__ __forceinline__ void gemm_phase(PG8_LAS unsigned char* lds, const Gemm g, const Sched& S, const Epi& E) {
;     ...
;             PG8_LDB(B0, 1, 0); PG8_LDB(B1, 1, 1); PG8_SCHED; PG8_LDA(At, 1, 0); PG8_STAGE(PG8_SA(0, 1), a2 + hstep, voffA);
;             PG8_WAIT_V(8); PG8_WAIT_L(0); PG8_BAR; PG8_MMA(0, 0, At, B0); PG8_MMA(0, 1, At, B1); PG8_BAR; PG8_SCHED;
;             PG8_LDA(At, 1, 1); PG8_STAGE(PG8_SB(1, 0), b3, voffB); PG8_STAGE(PG8_SB(1, 1), b3 + hstep, voffB); PG8_STAGE(PG8_SA(1, 0), a3, voffA);
;             PG8_WAIT_V(8); PG8_WAIT_L(0); PG8_BAR; PG8_MMA(1, 0, At, B0); PG8_MMA(1, 1, At, B1); PG8_BAR; PG8_SCHED;
	s_add_i32 s64, 0, 0x18000
	s_add_i32 s65, 0, 0x1c000
	ds_read_b128 v[146:149], v240
	ds_read_b128 v[156:159], v240 offset:1024
	ds_read_b128 v[160:163], v240 offset:2048
	ds_read_b128 v[164:167], v240 offset:3072
	ds_read_b128 v[168:171], v241
	ds_read_b128 v[172:175], v241 offset:1024
	ds_read_b128 v[176:179], v241 offset:2048
	ds_read_b128 v[180:183], v241 offset:3072
	ds_read_b128 v[184:187], v154 offset:32768
	ds_read_b128 v[188:191], v154 offset:33792
	ds_read_b128 v[192:195], v154 offset:34816
	ds_read_b128 v[196:199], v154 offset:35840
	ds_read_b128 v[200:203], v154 offset:36864
	ds_read_b128 v[206:209], v154 offset:37888
	ds_read_b128 v[210:213], v154 offset:38912
	ds_read_b128 v[214:217], v154 offset:39936
	s_waitcnt vmcnt(0)
	s_waitcnt lgkmcnt(0)
	s_setprio 1
	s_barrier
	v_mfma_f32_16x16x32_bf16 v[124:127], v[146:149], v[184:187], v[124:127]
	v_mfma_f32_16x16x32_bf16 v[120:123], v[160:163], v[184:187], v[120:123]
	v_mfma_f32_16x16x32_bf16 v[108:111], v[146:149], v[192:195], v[108:111]
	v_mfma_f32_16x16x32_bf16 v[104:107], v[160:163], v[192:195], v[104:107]
	v_mfma_f32_16x16x32_bf16 v[92:95], v[146:149], v[200:203], v[92:95]
	v_mfma_f32_16x16x32_bf16 v[88:91], v[160:163], v[200:203], v[88:91]
	v_mfma_f32_16x16x32_bf16 v[76:79], v[146:149], v[210:213], v[76:79]
	v_mfma_f32_16x16x32_bf16 v[72:75], v[160:163], v[210:213], v[72:75]
	v_mfma_f32_16x16x32_bf16 v[124:127], v[156:159], v[188:191], v[124:127]
	v_mfma_f32_16x16x32_bf16 v[120:123], v[164:167], v[188:191], v[120:123]
	v_mfma_f32_16x16x32_bf16 v[108:111], v[156:159], v[196:199], v[108:111]
	v_mfma_f32_16x16x32_bf16 v[104:107], v[164:167], v[196:199], v[104:107]
	v_mfma_f32_16x16x32_bf16 v[92:95], v[156:159], v[206:209], v[92:95]
	v_mfma_f32_16x16x32_bf16 v[88:91], v[164:167], v[206:209], v[88:91]
	v_mfma_f32_16x16x32_bf16 v[76:79], v[156:159], v[214:217], v[76:79]
	v_mfma_f32_16x16x32_bf16 v[72:75], v[164:167], v[214:217], v[72:75]
	v_mfma_f32_16x16x32_bf16 v[116:119], v[168:171], v[184:187], v[116:119]
	v_mfma_f32_16x16x32_bf16 v[112:115], v[176:179], v[184:187], v[112:115]
	v_mfma_f32_16x16x32_bf16 v[100:103], v[168:171], v[192:195], v[100:103]
	v_mfma_f32_16x16x32_bf16 v[96:99], v[176:179], v[192:195], v[96:99]
	v_mfma_f32_16x16x32_bf16 v[84:87], v[168:171], v[200:203], v[84:87]
	v_mfma_f32_16x16x32_bf16 v[80:83], v[176:179], v[200:203], v[80:83]
	v_mfma_f32_16x16x32_bf16 v[68:71], v[168:171], v[210:213], v[68:71]
	v_mfma_f32_16x16x32_bf16 v[64:67], v[176:179], v[210:213], v[64:67]
	v_mfma_f32_16x16x32_bf16 v[116:119], v[172:175], v[188:191], v[116:119]
	v_mfma_f32_16x16x32_bf16 v[112:115], v[180:183], v[188:191], v[112:115]
	v_mfma_f32_16x16x32_bf16 v[100:103], v[172:175], v[196:199], v[100:103]
	v_mfma_f32_16x16x32_bf16 v[96:99], v[180:183], v[196:199], v[96:99]
	v_mfma_f32_16x16x32_bf16 v[84:87], v[172:175], v[206:209], v[84:87]
	v_mfma_f32_16x16x32_bf16 v[80:83], v[180:183], v[206:209], v[80:83]
	v_mfma_f32_16x16x32_bf16 v[68:71], v[172:175], v[214:217], v[68:71]
	v_mfma_f32_16x16x32_bf16 v[64:67], v[180:183], v[214:217], v[64:67]
	s_setprio 0
	s_barrier
	ds_read_b128 v[184:187], v154 offset:49152
	ds_read_b128 v[188:191], v154 offset:50176
	ds_read_b128 v[192:195], v154 offset:51200
	ds_read_b128 v[196:199], v154 offset:52224
	ds_read_b128 v[200:203], v154 offset:53248
	ds_read_b128 v[206:209], v154 offset:54272
	ds_read_b128 v[210:213], v154 offset:55296
	ds_read_b128 v[214:217], v154 offset:56320
	s_waitcnt lgkmcnt(0)
	s_setprio 1
	s_barrier
	v_mfma_f32_16x16x32_bf16 v[60:63], v[146:149], v[184:187], v[60:63]
	v_mfma_f32_16x16x32_bf16 v[56:59], v[160:163], v[184:187], v[56:59]
	v_mfma_f32_16x16x32_bf16 v[44:47], v[146:149], v[192:195], v[44:47]
	v_mfma_f32_16x16x32_bf16 v[40:43], v[160:163], v[192:195], v[40:43]
	v_mfma_f32_16x16x32_bf16 v[28:31], v[146:149], v[200:203], v[28:31]
	v_mfma_f32_16x16x32_bf16 v[24:27], v[160:163], v[200:203], v[24:27]
	v_mfma_f32_16x16x32_bf16 v[12:15], v[146:149], v[210:213], v[12:15]
	v_mfma_f32_16x16x32_bf16 v[8:11], v[160:163], v[210:213], v[8:11]
	v_mfma_f32_16x16x32_bf16 v[60:63], v[156:159], v[188:191], v[60:63]
	v_mfma_f32_16x16x32_bf16 v[56:59], v[164:167], v[188:191], v[56:59]
	v_mfma_f32_16x16x32_bf16 v[44:47], v[156:159], v[196:199], v[44:47]
	v_mfma_f32_16x16x32_bf16 v[40:43], v[164:167], v[196:199], v[40:43]
	v_mfma_f32_16x16x32_bf16 v[28:31], v[156:159], v[206:209], v[28:31]
	v_mfma_f32_16x16x32_bf16 v[24:27], v[164:167], v[206:209], v[24:27]
	v_mfma_f32_16x16x32_bf16 v[12:15], v[156:159], v[214:217], v[12:15]
	v_mfma_f32_16x16x32_bf16 v[8:11], v[164:167], v[214:217], v[8:11]
	v_mfma_f32_16x16x32_bf16 v[52:55], v[168:171], v[184:187], v[52:55]
	v_mfma_f32_16x16x32_bf16 v[48:51], v[176:179], v[184:187], v[48:51]
	v_mfma_f32_16x16x32_bf16 v[36:39], v[168:171], v[192:195], v[36:39]
	v_mfma_f32_16x16x32_bf16 v[32:35], v[176:179], v[192:195], v[32:35]
	v_mfma_f32_16x16x32_bf16 v[20:23], v[168:171], v[200:203], v[20:23]
	v_mfma_f32_16x16x32_bf16 v[16:19], v[176:179], v[200:203], v[16:19]
	v_mfma_f32_16x16x32_bf16 v[4:7], v[168:171], v[210:213], v[4:7]
	v_mfma_f32_16x16x32_bf16 v[0:3], v[176:179], v[210:213], v[0:3]
	v_mfma_f32_16x16x32_bf16 v[52:55], v[172:175], v[188:191], v[52:55]
	v_mfma_f32_16x16x32_bf16 v[48:51], v[180:183], v[188:191], v[48:51]
	v_mfma_f32_16x16x32_bf16 v[36:39], v[172:175], v[196:199], v[36:39]
	v_mfma_f32_16x16x32_bf16 v[32:35], v[180:183], v[196:199], v[32:35]
	v_mfma_f32_16x16x32_bf16 v[20:23], v[172:175], v[206:209], v[20:23]
	v_mfma_f32_16x16x32_bf16 v[16:19], v[180:183], v[206:209], v[16:19]
	v_mfma_f32_16x16x32_bf16 v[4:7], v[172:175], v[214:217], v[4:7]
	v_mfma_f32_16x16x32_bf16 v[0:3], v[180:183], v[214:217], v[0:3]
	s_setprio 0
	s_barrier
	s_add_i32 s63, s63, 2
	s_add_u32 s44, s44, 0x100
	s_addc_u32 s45, s45, 0
	s_add_u32 s61, s61, 0x100
	s_addc_u32 s62, s62, 0

; #define PG8_STAGE(bufoff, gbase, voff) do { _Pragma("unroll") for (int _i = 0; _i < 2; ++_i) \
;         __builtin_amdgcn_global_load_lds((const unsigned*)((const char*)(gbase) + (voff)[_i]), (PG8_LAS unsigned*)(lds + (bufoff) + ldsw + _i * 8192), 16, 0, 0); } while (0)
; #define PG8_LDA(dst, b, h) do { _Pragma("unroll") for (int m = 0; m < 4; ++m) _Pragma("unroll") for (int k = 0; k < 2; ++k) dst[m][k] = *(const PG8_LAS bf16x8*)(lds + PG8_SA(b, h) + aoff + m * 2048 + k * 1024); } while (0)
; #define PG8_LDB(dst, b, h) do { _Pragma("unroll") for (int n = 0; n < 2; ++n) _Pragma("unroll") for (int k = 0; k < 2; ++k) dst[n][k] = *(const PG8_LAS bf16x8*)(lds + PG8_SB(b, h) + boff + n * 2048 + k * 1024); } while (0)
; #define PG8_MMA(ai, bj, At, Bt) do { __builtin_amdgcn_s_setprio(1); _Pragma("unroll") for (int m = 0; m < 4; ++m) _Pragma("unroll") for (int n = 0; n < 2; ++n) _Pragma("unroll") for (int k = 0; k < 2; ++k) \
;         acc[ai][bj][m][n] = __builtin_amdgcn_mfma_f32_16x16x32_bf16(Bt[n][k], At[m][k], acc[ai][bj][m][n], 0, 0, 0); __builtin_amdgcn_s_setprio(0); } while (0)
; #define PG8_WAIT_V(n) asm volatile("s_waitcnt vmcnt(" #n ")" ::: "memory")
; #define PG8_WAIT_L(n) asm volatile("s_waitcnt lgkmcnt(" #n ")" ::: "memory")
; template <class Epi, class Sched, bool ALIGN_EPI = false, bool SP2 = false>
; __device__ __forceinline__ void gemm_phase(PG8_LAS unsigned char* lds, const Gemm g, const Sched& S, const Epi& E) {
;     ...
;             const bool last = (t == nt - 2);
;             const char* a1 = cA + (size_t)(t + 1) * kstep;
;             const char* a2 = last ? nA : cA + (size_t)(t + 2) * kstep; const char* b2 = last ? nB : cB + (size_t)(t + 2) * kstep;
;             const char* a3 = a2 + kstep; const char* b3 = b2 + kstep;
;             if (last && has_next) S.a_ready(nxt);
;             if constexpr (SP2) {
;             PG8_LDB(B0, 0, 0); PG8_LDB(B1, 0, 1); PG8_SCHED; PG8_LDA(At, 0, 0); PG8_STAGE(PG8_SA(1, 1), a1 + hstep, voffA);
;             PG8_WAIT_V(8); PG8_WAIT_L(0); PG8_BAR; PG8_MMA(0, 0, At, B0); PG8_MMA(0, 1, At, B1); PG8_BAR; PG8_SCHED;
;             PG8_LDA(At, 0, 1); PG8_STAGE(PG8_SB(0, 0), b2, voffB); PG8_STAGE(PG8_SB(0, 1), b2 + hstep, voffB); PG8_STAGE(PG8_SA(0, 0), a2, voffA);
;             PG8_WAIT_V(8); PG8_WAIT_L(0); PG8_BAR; PG8_MMA(1, 0, At, B0); PG8_MMA(1, 1, At, B1); PG8_BAR; PG8_SCHED;
.LBB0_905:
	s_cmp_eq_u32 s62, 12
	s_cbranch_scc0 .Lkf4_norm
	s_cmp_eq_u64 s[6:7], 0
	s_cbranch_scc1 .Lkf4_fin
.Lkf4_norm:
	ds_read_b128 v[146:149], v151
	ds_read_b128 v[156:159], v151 offset:1024
	ds_read_b128 v[160:163], v151 offset:2048
	ds_read_b128 v[164:167], v151 offset:3072
	ds_read_b128 v[168:171], v152
	ds_read_b128 v[172:175], v152 offset:1024
	ds_read_b128 v[176:179], v152 offset:2048
	ds_read_b128 v[180:183], v152 offset:3072
	s_add_u32 s42, s40, 0xfffc0080
	s_addc_u32 s43, s41, -1
	s_cmp_eq_u32 s62, 12
	s_cselect_b32 s45, s35, s43
	s_cselect_b32 s44, s58, s42
	s_cselect_b32 s43, s31, s61
	s_cselect_b32 s42, s59, s60
	s_add_i32 m0, s46, 0xc000
	ds_read_b128 v[184:187], v153
	ds_read_b128 v[188:191], v153 offset:1024
	ds_read_b128 v[192:195], v153 offset:2048
	ds_read_b128 v[196:199], v153 offset:3072
	ds_read_b128 v[200:203], v153 offset:4096
	ds_read_b128 v[206:209], v153 offset:5120
	ds_read_b128 v[210:213], v153 offset:6144
	ds_read_b128 v[214:217], v153 offset:7168
	global_load_lds_dwordx4 v138, s[40:41]
	s_add_i32 m0, s46, 0xe000
	s_nop 0
	global_load_lds_dwordx4 v140, s[40:41]
	s_waitcnt vmcnt(8)
	s_waitcnt lgkmcnt(0)
	s_setprio 1
	s_barrier
	v_mfma_f32_16x16x32_bf16 v[124:127], v[146:149], v[184:187], v[124:127]
	v_mfma_f32_16x16x32_bf16 v[120:123], v[160:163], v[184:187], v[120:123]
	v_mfma_f32_16x16x32_bf16 v[108:111], v[146:149], v[192:195], v[108:111]
	v_mfma_f32_16x16x32_bf16 v[104:107], v[160:163], v[192:195], v[104:107]
	v_mfma_f32_16x16x32_bf16 v[92:95], v[146:149], v[200:203], v[92:95]
	v_mfma_f32_16x16x32_bf16 v[88:91], v[160:163], v[200:203], v[88:91]
	v_mfma_f32_16x16x32_bf16 v[76:79], v[146:149], v[210:213], v[76:79]
	v_mfma_f32_16x16x32_bf16 v[72:75], v[160:163], v[210:213], v[72:75]
	v_mfma_f32_16x16x32_bf16 v[124:127], v[156:159], v[188:191], v[124:127]
	v_mfma_f32_16x16x32_bf16 v[120:123], v[164:167], v[188:191], v[120:123]
	v_mfma_f32_16x16x32_bf16 v[108:111], v[156:159], v[196:199], v[108:111]
	v_mfma_f32_16x16x32_bf16 v[104:107], v[164:167], v[196:199], v[104:107]
	v_mfma_f32_16x16x32_bf16 v[92:95], v[156:159], v[206:209], v[92:95]
	v_mfma_f32_16x16x32_bf16 v[88:91], v[164:167], v[206:209], v[88:91]
	v_mfma_f32_16x16x32_bf16 v[76:79], v[156:159], v[214:217], v[76:79]
	v_mfma_f32_16x16x32_bf16 v[72:75], v[164:167], v[214:217], v[72:75]
	v_mfma_f32_16x16x32_bf16 v[116:119], v[168:171], v[184:187], v[116:119]
	v_mfma_f32_16x16x32_bf16 v[112:115], v[176:179], v[184:187], v[112:115]
	v_mfma_f32_16x16x32_bf16 v[100:103], v[168:171], v[192:195], v[100:103]
	v_mfma_f32_16x16x32_bf16 v[96:99], v[176:179], v[192:195], v[96:99]
	v_mfma_f32_16x16x32_bf16 v[84:87], v[168:171], v[200:203], v[84:87]
	v_mfma_f32_16x16x32_bf16 v[80:83], v[176:179], v[200:203], v[80:83]
	v_mfma_f32_16x16x32_bf16 v[68:71], v[168:171], v[210:213], v[68:71]
	v_mfma_f32_16x16x32_bf16 v[64:67], v[176:179], v[210:213], v[64:67]
	v_mfma_f32_16x16x32_bf16 v[116:119], v[172:175], v[188:191], v[116:119]
	v_mfma_f32_16x16x32_bf16 v[112:115], v[180:183], v[188:191], v[112:115]
	v_mfma_f32_16x16x32_bf16 v[100:103], v[172:175], v[196:199], v[100:103]
	v_mfma_f32_16x16x32_bf16 v[96:99], v[180:183], v[196:199], v[96:99]
	v_mfma_f32_16x16x32_bf16 v[84:87], v[172:175], v[206:209], v[84:87]
	v_mfma_f32_16x16x32_bf16 v[80:83], v[180:183], v[206:209], v[80:83]
	v_mfma_f32_16x16x32_bf16 v[68:71], v[172:175], v[214:217], v[68:71]
	v_mfma_f32_16x16x32_bf16 v[64:67], v[180:183], v[214:217], v[64:67]
	s_setprio 0
	s_barrier
	s_add_i32 s63, s55, s33
	s_mov_b32 m0, s63
	ds_read_b128 v[184:187], v153 offset:16384
	ds_read_b128 v[188:191], v153 offset:17408
	ds_read_b128 v[192:195], v153 offset:18432
	ds_read_b128 v[196:199], v153 offset:19456
	ds_read_b128 v[200:203], v153 offset:20480
	ds_read_b128 v[206:209], v153 offset:21504
	ds_read_b128 v[210:213], v153 offset:22528
	ds_read_b128 v[214:217], v153 offset:23552
	global_load_lds_dwordx4 v132, s[42:43]
	s_add_i32 m0, s63, 0x2000
	s_add_u32 s98, s42, 0x80
	s_addc_u32 s99, s43, 0
	s_add_u32 s64, s42, 0x40000
	s_addc_u32 s65, s43, 0
	s_add_i32 s63, s56, s33
	global_load_lds_dwordx4 v136, s[42:43]
	s_mov_b32 m0, s63
	s_nop 0
	global_load_lds_dwordx4 v132, s[64:65]
	s_add_i32 m0, s63, 0x2000
	s_nop 0
	global_load_lds_dwordx4 v136, s[64:65]
	s_mov_b32 m0, s46
	s_nop 0
	global_load_lds_dwordx4 v130, s[44:45]
	s_mov_b32 m0, s47
	s_nop 0
	global_load_lds_dwordx4 v134, s[44:45]
	s_waitcnt vmcnt(8)
	s_waitcnt lgkmcnt(0)
	s_setprio 1
	s_barrier
	v_mfma_f32_16x16x32_bf16 v[60:63], v[146:149], v[184:187], v[60:63]
	v_mfma_f32_16x16x32_bf16 v[56:59], v[160:163], v[184:187], v[56:59]
	v_mfma_f32_16x16x32_bf16 v[44:47], v[146:149], v[192:195], v[44:47]
	v_mfma_f32_16x16x32_bf16 v[40:43], v[160:163], v[192:195], v[40:43]
	v_mfma_f32_16x16x32_bf16 v[28:31], v[146:149], v[200:203], v[28:31]
	v_mfma_f32_16x16x32_bf16 v[24:27], v[160:163], v[200:203], v[24:27]
	v_mfma_f32_16x16x32_bf16 v[12:15], v[146:149], v[210:213], v[12:15]
	v_mfma_f32_16x16x32_bf16 v[8:11], v[160:163], v[210:213], v[8:11]
	v_mfma_f32_16x16x32_bf16 v[60:63], v[156:159], v[188:191], v[60:63]
	v_mfma_f32_16x16x32_bf16 v[56:59], v[164:167], v[188:191], v[56:59]
	v_mfma_f32_16x16x32_bf16 v[44:47], v[156:159], v[196:199], v[44:47]
	v_mfma_f32_16x16x32_bf16 v[40:43], v[164:167], v[196:199], v[40:43]
	v_mfma_f32_16x16x32_bf16 v[28:31], v[156:159], v[206:209], v[28:31]
	v_mfma_f32_16x16x32_bf16 v[24:27], v[164:167], v[206:209], v[24:27]
	v_mfma_f32_16x16x32_bf16 v[12:15], v[156:159], v[214:217], v[12:15]
	v_mfma_f32_16x16x32_bf16 v[8:11], v[164:167], v[214:217], v[8:11]
	v_mfma_f32_16x16x32_bf16 v[52:55], v[168:171], v[184:187], v[52:55]
	v_mfma_f32_16x16x32_bf16 v[48:51], v[176:179], v[184:187], v[48:51]
	v_mfma_f32_16x16x32_bf16 v[36:39], v[168:171], v[192:195], v[36:39]
	v_mfma_f32_16x16x32_bf16 v[32:35], v[176:179], v[192:195], v[32:35]
	v_mfma_f32_16x16x32_bf16 v[20:23], v[168:171], v[200:203], v[20:23]
	v_mfma_f32_16x16x32_bf16 v[16:19], v[176:179], v[200:203], v[16:19]
	v_mfma_f32_16x16x32_bf16 v[4:7], v[168:171], v[210:213], v[4:7]
	v_mfma_f32_16x16x32_bf16 v[0:3], v[176:179], v[210:213], v[0:3]
	v_mfma_f32_16x16x32_bf16 v[52:55], v[172:175], v[188:191], v[52:55]
	v_mfma_f32_16x16x32_bf16 v[48:51], v[180:183], v[188:191], v[48:51]
	v_mfma_f32_16x16x32_bf16 v[36:39], v[172:175], v[196:199], v[36:39]
	v_mfma_f32_16x16x32_bf16 v[32:35], v[180:183], v[196:199], v[32:35]
	v_mfma_f32_16x16x32_bf16 v[20:23], v[172:175], v[206:209], v[20:23]
	v_mfma_f32_16x16x32_bf16 v[16:19], v[180:183], v[206:209], v[16:19]
	v_mfma_f32_16x16x32_bf16 v[4:7], v[172:175], v[214:217], v[4:7]
	v_mfma_f32_16x16x32_bf16 v[0:3], v[180:183], v[214:217], v[0:3]
	s_setprio 0
	s_barrier
; #define PG8_STAGE(bufoff, gbase, voff) do { _Pragma("unroll") for (int _i = 0; _i < 2; ++_i) \
;         __builtin_amdgcn_global_load_lds((const unsigned*)((const char*)(gbase) + (voff)[_i]), (PG8_LAS unsigned*)(lds + (bufoff) + ldsw + _i * 8192), 16, 0, 0); } while (0)
; #define PG8_LDA(dst, b, h) do { _Pragma("unroll") for (int m = 0; m < 4; ++m) _Pragma("unroll") for (int k = 0; k < 2; ++k) dst[m][k] = *(const PG8_LAS bf16x8*)(lds + PG8_SA(b, h) + aoff + m * 2048 + k * 1024); } while (0)
; #define PG8_LDB(dst, b, h) do { _Pragma("unroll") for (int n = 0; n < 2; ++n) _Pragma("unroll") for (int k = 0; k < 2; ++k) dst[n][k] = *(const PG8_LAS bf16x8*)(lds + PG8_SB(b, h) + boff + n * 2048 + k * 1024); } while (0)
; #define PG8_MMA(ai, bj, At, Bt) do { __builtin_amdgcn_s_setprio(1); _Pragma("unroll") for (int m = 0; m < 4; ++m) _Pragma("unroll") for (int n = 0; n < 2; ++n) _Pragma("unroll") for (int k = 0; k < 2; ++k) \
;         acc[ai][bj][m][n] = __builtin_amdgcn_mfma_f32_16x16x32_bf16(Bt[n][k], At[m][k], acc[ai][bj][m][n], 0, 0, 0); __builtin_amdgcn_s_setprio(0); } while (0)
; #define PG8_WAIT_V(n) asm volatile("s_waitcnt vmcnt(" #n ")" ::: "memory")
; #define PG8_WAIT_L(n) asm volatile("s_waitcnt lgkmcnt(" #n ")" ::: "memory")
; #define PG8_BAR __builtin_amdgcn_s_barrier()
; #define PG8_SCHED __builtin_amdgcn_sched_barrier(0)
; template <class Epi, class Sched, bool ALIGN_EPI = false, bool SP2 = false>
; __device__ __forceinline__ void gemm_phase(PG8_LAS unsigned char* lds, const Gemm g, const Sched& S, const Epi& E) {
;     ...
;             PG8_LDB(B0, 1, 0); PG8_LDB(B1, 1, 1); PG8_SCHED; PG8_LDA(At, 1, 0); PG8_STAGE(PG8_SA(0, 1), a2 + hstep, voffA);
;             PG8_WAIT_V(8); PG8_WAIT_L(0); PG8_BAR; PG8_MMA(0, 0, At, B0); PG8_MMA(0, 1, At, B1); PG8_BAR; PG8_SCHED;
;             PG8_LDA(At, 1, 1); PG8_STAGE(PG8_SB(1, 0), b3, voffB); PG8_STAGE(PG8_SB(1, 1), b3 + hstep, voffB); PG8_STAGE(PG8_SA(1, 0), a3, voffA);
;             PG8_WAIT_V(8); PG8_WAIT_L(0); PG8_BAR; PG8_MMA(1, 0, At, B0); PG8_MMA(1, 1, At, B1); PG8_BAR; PG8_SCHED;
	s_add_i32 s63, 0, 0x18000
	s_add_i32 s64, 0, 0x1c000
	ds_read_b128 v[146:149], v240
	ds_read_b128 v[156:159], v240 offset:1024
	ds_read_b128 v[160:163], v240 offset:2048
	ds_read_b128 v[164:167], v240 offset:3072
	ds_read_b128 v[168:171], v241
	ds_read_b128 v[172:175], v241 offset:1024
	ds_read_b128 v[176:179], v241 offset:2048
	ds_read_b128 v[180:183], v241 offset:3072
	s_add_u32 s100, s44, 0x80
	s_addc_u32 s101, s45, 0
	s_add_u32 s44, s44, 0x40000
	s_addc_u32 s45, s45, 0
	s_mov_b32 m0, s48
	ds_read_b128 v[184:187], v153 offset:32768
	ds_read_b128 v[188:191], v153 offset:33792
	ds_read_b128 v[192:195], v153 offset:34816
	ds_read_b128 v[196:199], v153 offset:35840
	ds_read_b128 v[200:203], v153 offset:36864
	ds_read_b128 v[206:209], v153 offset:37888
	ds_read_b128 v[210:213], v153 offset:38912
	ds_read_b128 v[214:217], v153 offset:39936
	global_load_lds_dwordx4 v130, s[44:45]
	s_mov_b32 m0, s49
	s_nop 0
	global_load_lds_dwordx4 v134, s[44:45]
	s_waitcnt vmcnt(8)
	s_waitcnt lgkmcnt(0)
	s_setprio 1
	s_barrier
	v_mfma_f32_16x16x32_bf16 v[124:127], v[146:149], v[184:187], v[124:127]
	v_mfma_f32_16x16x32_bf16 v[120:123], v[160:163], v[184:187], v[120:123]
	v_mfma_f32_16x16x32_bf16 v[108:111], v[146:149], v[192:195], v[108:111]
	v_mfma_f32_16x16x32_bf16 v[104:107], v[160:163], v[192:195], v[104:107]
	v_mfma_f32_16x16x32_bf16 v[92:95], v[146:149], v[200:203], v[92:95]
	v_mfma_f32_16x16x32_bf16 v[88:91], v[160:163], v[200:203], v[88:91]
	v_mfma_f32_16x16x32_bf16 v[76:79], v[146:149], v[210:213], v[76:79]
	v_mfma_f32_16x16x32_bf16 v[72:75], v[160:163], v[210:213], v[72:75]
	v_mfma_f32_16x16x32_bf16 v[124:127], v[156:159], v[188:191], v[124:127]
	v_mfma_f32_16x16x32_bf16 v[120:123], v[164:167], v[188:191], v[120:123]
	v_mfma_f32_16x16x32_bf16 v[108:111], v[156:159], v[196:199], v[108:111]
	v_mfma_f32_16x16x32_bf16 v[104:107], v[164:167], v[196:199], v[104:107]
	v_mfma_f32_16x16x32_bf16 v[92:95], v[156:159], v[206:209], v[92:95]
	v_mfma_f32_16x16x32_bf16 v[88:91], v[164:167], v[206:209], v[88:91]
	v_mfma_f32_16x16x32_bf16 v[76:79], v[156:159], v[214:217], v[76:79]
	v_mfma_f32_16x16x32_bf16 v[72:75], v[164:167], v[214:217], v[72:75]
	v_mfma_f32_16x16x32_bf16 v[116:119], v[168:171], v[184:187], v[116:119]
	v_mfma_f32_16x16x32_bf16 v[112:115], v[176:179], v[184:187], v[112:115]
	v_mfma_f32_16x16x32_bf16 v[100:103], v[168:171], v[192:195], v[100:103]
	v_mfma_f32_16x16x32_bf16 v[96:99], v[176:179], v[192:195], v[96:99]
	v_mfma_f32_16x16x32_bf16 v[84:87], v[168:171], v[200:203], v[84:87]
	v_mfma_f32_16x16x32_bf16 v[80:83], v[176:179], v[200:203], v[80:83]
	v_mfma_f32_16x16x32_bf16 v[68:71], v[168:171], v[210:213], v[68:71]
	v_mfma_f32_16x16x32_bf16 v[64:67], v[176:179], v[210:213], v[64:67]
	v_mfma_f32_16x16x32_bf16 v[116:119], v[172:175], v[188:191], v[116:119]
	v_mfma_f32_16x16x32_bf16 v[112:115], v[180:183], v[188:191], v[112:115]
	v_mfma_f32_16x16x32_bf16 v[100:103], v[172:175], v[196:199], v[100:103]
	v_mfma_f32_16x16x32_bf16 v[96:99], v[180:183], v[196:199], v[96:99]
	v_mfma_f32_16x16x32_bf16 v[84:87], v[172:175], v[206:209], v[84:87]
	v_mfma_f32_16x16x32_bf16 v[80:83], v[180:183], v[206:209], v[80:83]
	v_mfma_f32_16x16x32_bf16 v[68:71], v[172:175], v[214:217], v[68:71]
	v_mfma_f32_16x16x32_bf16 v[64:67], v[180:183], v[214:217], v[64:67]
	s_setprio 0
	s_barrier
	s_add_i32 s44, s63, s33
	s_mov_b32 m0, s44
	ds_read_b128 v[184:187], v153 offset:49152
	ds_read_b128 v[188:191], v153 offset:50176
	ds_read_b128 v[192:195], v153 offset:51200
	ds_read_b128 v[196:199], v153 offset:52224
	ds_read_b128 v[200:203], v153 offset:53248
	ds_read_b128 v[206:209], v153 offset:54272
	ds_read_b128 v[210:213], v153 offset:55296
	ds_read_b128 v[214:217], v153 offset:56320
	global_load_lds_dwordx4 v132, s[98:99]
	s_add_i32 m0, s44, 0x2000
	s_add_u32 s42, s42, 0x40080
	s_addc_u32 s43, s43, 0
	s_add_i32 s44, s64, s33
	global_load_lds_dwordx4 v136, s[98:99]
	s_mov_b32 m0, s44
	s_nop 0
	global_load_lds_dwordx4 v132, s[42:43]
	s_add_i32 m0, s44, 0x2000
	s_nop 0
	global_load_lds_dwordx4 v136, s[42:43]
	s_mov_b32 m0, s52
	s_nop 0
	global_load_lds_dwordx4 v130, s[100:101]
	s_mov_b32 m0, s53
	s_nop 0
	global_load_lds_dwordx4 v134, s[100:101]
	s_waitcnt vmcnt(8)
	s_waitcnt lgkmcnt(0)
	s_setprio 1
	s_barrier
	v_mfma_f32_16x16x32_bf16 v[60:63], v[146:149], v[184:187], v[60:63]
	v_mfma_f32_16x16x32_bf16 v[56:59], v[160:163], v[184:187], v[56:59]
	v_mfma_f32_16x16x32_bf16 v[44:47], v[146:149], v[192:195], v[44:47]
	v_mfma_f32_16x16x32_bf16 v[40:43], v[160:163], v[192:195], v[40:43]
	v_mfma_f32_16x16x32_bf16 v[28:31], v[146:149], v[200:203], v[28:31]
	v_mfma_f32_16x16x32_bf16 v[24:27], v[160:163], v[200:203], v[24:27]
	v_mfma_f32_16x16x32_bf16 v[12:15], v[146:149], v[210:213], v[12:15]
	v_mfma_f32_16x16x32_bf16 v[8:11], v[160:163], v[210:213], v[8:11]
	v_mfma_f32_16x16x32_bf16 v[60:63], v[156:159], v[188:191], v[60:63]
	v_mfma_f32_16x16x32_bf16 v[56:59], v[164:167], v[188:191], v[56:59]
	v_mfma_f32_16x16x32_bf16 v[44:47], v[156:159], v[196:199], v[44:47]
	v_mfma_f32_16x16x32_bf16 v[40:43], v[164:167], v[196:199], v[40:43]
	v_mfma_f32_16x16x32_bf16 v[28:31], v[156:159], v[206:209], v[28:31]
	v_mfma_f32_16x16x32_bf16 v[24:27], v[164:167], v[206:209], v[24:27]
	v_mfma_f32_16x16x32_bf16 v[12:15], v[156:159], v[214:217], v[12:15]
	v_mfma_f32_16x16x32_bf16 v[8:11], v[164:167], v[214:217], v[8:11]
	v_mfma_f32_16x16x32_bf16 v[52:55], v[168:171], v[184:187], v[52:55]
	v_mfma_f32_16x16x32_bf16 v[48:51], v[176:179], v[184:187], v[48:51]
	v_mfma_f32_16x16x32_bf16 v[36:39], v[168:171], v[192:195], v[36:39]
	v_mfma_f32_16x16x32_bf16 v[32:35], v[176:179], v[192:195], v[32:35]
	v_mfma_f32_16x16x32_bf16 v[20:23], v[168:171], v[200:203], v[20:23]
	v_mfma_f32_16x16x32_bf16 v[16:19], v[176:179], v[200:203], v[16:19]
	v_mfma_f32_16x16x32_bf16 v[4:7], v[168:171], v[210:213], v[4:7]
	v_mfma_f32_16x16x32_bf16 v[0:3], v[176:179], v[210:213], v[0:3]
	v_mfma_f32_16x16x32_bf16 v[52:55], v[172:175], v[188:191], v[52:55]
	v_mfma_f32_16x16x32_bf16 v[48:51], v[180:183], v[188:191], v[48:51]
	v_mfma_f32_16x16x32_bf16 v[36:39], v[172:175], v[196:199], v[36:39]
	v_mfma_f32_16x16x32_bf16 v[32:35], v[180:183], v[196:199], v[32:35]
	v_mfma_f32_16x16x32_bf16 v[20:23], v[172:175], v[206:209], v[20:23]
	v_mfma_f32_16x16x32_bf16 v[16:19], v[180:183], v[206:209], v[16:19]
	v_mfma_f32_16x16x32_bf16 v[4:7], v[172:175], v[214:217], v[4:7]
	v_mfma_f32_16x16x32_bf16 v[0:3], v[180:183], v[214:217], v[0:3]
	s_setprio 0
	s_barrier
	s_add_i32 s62, s62, 2
	s_add_u32 s40, s40, 0x100
	s_addc_u32 s41, s41, 0
	s_add_u32 s60, s60, 0x100
	s_addc_u32 s61, s61, 0
	s_cmp_gt_u32 s62, 13
	s_cbranch_scc0 .LBB0_905
	s_branch .Lkf4_exit
; #define PG8_STAGE(bufoff, gbase, voff) do { _Pragma("unroll") for (int _i = 0; _i < 2; ++_i) \
;         __builtin_amdgcn_global_load_lds((const unsigned*)((const char*)(gbase) + (voff)[_i]), (PG8_LAS unsigned*)(lds + (bufoff) + ldsw + _i * 8192), 16, 0, 0); } while (0)
; #define PG8_LDA(dst, b, h) do { _Pragma("unroll") for (int m = 0; m < 4; ++m) _Pragma("unroll") for (int k = 0; k < 2; ++k) dst[m][k] = *(const PG8_LAS bf16x8*)(lds + PG8_SA(b, h) + aoff + m * 2048 + k * 1024); } while (0)
; #define PG8_LDB(dst, b, h) do { _Pragma("unroll") for (int n = 0; n < 2; ++n) _Pragma("unroll") for (int k = 0; k < 2; ++k) dst[n][k] = *(const PG8_LAS bf16x8*)(lds + PG8_SB(b, h) + boff + n * 2048 + k * 1024); } while (0)
; template <class Epi, class Sched, bool ALIGN_EPI = false, bool SP2 = false>
; __device__ __forceinline__ void gemm_phase(PG8_LAS unsigned char* lds, const Gemm g, const Sched& S, const Epi& E) {
;     ...
;         for (int t = 0; t < nt; t += 2) {
;             const bool last = (t == nt - 2);
;             const char* a1 = cA + (size_t)(t + 1) * kstep;
;             const char* a2 = last ? nA : cA + (size_t)(t + 2) * kstep; const char* b2 = last ? nB : cB + (size_t)(t + 2) * kstep;
;             const char* a3 = a2 + kstep; const char* b3 = b2 + kstep;
;             if (last && has_next) S.a_ready(nxt);
;             if constexpr (SP2) {
;             PG8_LDB(B0, 0, 0); PG8_LDB(B1, 0, 1); PG8_SCHED; PG8_LDA(At, 0, 0); PG8_STAGE(PG8_SA(1, 1), a1 + hstep, voffA);
;             PG8_WAIT_V(8); PG8_WAIT_L(0); PG8_BAR; PG8_MMA(0, 0, At, B0); PG8_MMA(0, 1, At, B1); PG8_BAR; PG8_SCHED;
;             PG8_LDA(At, 0, 1); PG8_STAGE(PG8_SB(0, 0), b2, voffB); PG8_STAGE(PG8_SB(0, 1), b2 + hstep, voffB); PG8_STAGE(PG8_SA(0, 0), a2, voffA);
;             PG8_WAIT_V(8); PG8_WAIT_L(0); PG8_BAR; PG8_MMA(1, 0, At, B0); PG8_MMA(1, 1, At, B1); PG8_BAR; PG8_SCHED;
;             PG8_LDB(B0, 1, 0); PG8_LDB(B1, 1, 1); PG8_SCHED; PG8_LDA(At, 1, 0); PG8_STAGE(PG8_SA(0, 1), a2 + hstep, voffA);
;             PG8_WAIT_V(8); PG8_WAIT_L(0); PG8_BAR; PG8_MMA(0, 0, At, B0); PG8_MMA(0, 1, At, B1); PG8_BAR; PG8_SCHED;
;             PG8_LDA(At, 1, 1); PG8_STAGE(PG8_SB(1, 0), b3, voffB); PG8_STAGE(PG8_SB(1, 1), b3 + hstep, voffB); PG8_STAGE(PG8_SA(1, 0), a3, voffA);
;             PG8_WAIT_V(8); PG8_WAIT_L(0); PG8_BAR; PG8_MMA(1, 0, At, B0); PG8_MMA(1, 1, At, B1); PG8_BAR; PG8_SCHED;
.Lkf4_fin:
	ds_read_b128 v[146:149], v151
	ds_read_b128 v[156:159], v151 offset:1024
	ds_read_b128 v[160:163], v151 offset:2048
	ds_read_b128 v[164:167], v151 offset:3072
	ds_read_b128 v[168:171], v152
	ds_read_b128 v[172:175], v152 offset:1024
	ds_read_b128 v[176:179], v152 offset:2048
	ds_read_b128 v[180:183], v152 offset:3072
	s_add_u32 s42, s40, 0xfffc0080
	s_addc_u32 s43, s41, -1
	s_cmp_eq_u32 s62, 12
	s_cselect_b32 s45, s35, s43
	s_cselect_b32 s44, s58, s42
	s_cselect_b32 s43, s31, s61
	s_cselect_b32 s42, s59, s60
	s_add_i32 m0, s46, 0xc000
	ds_read_b128 v[184:187], v153
	ds_read_b128 v[188:191], v153 offset:1024
	ds_read_b128 v[192:195], v153 offset:2048
	ds_read_b128 v[196:199], v153 offset:3072
	ds_read_b128 v[200:203], v153 offset:4096
	ds_read_b128 v[206:209], v153 offset:5120
	ds_read_b128 v[210:213], v153 offset:6144
	ds_read_b128 v[214:217], v153 offset:7168
	global_load_lds_dwordx4 v138, s[40:41]
	s_add_i32 m0, s46, 0xe000
	s_nop 0
	global_load_lds_dwordx4 v140, s[40:41]
	s_waitcnt vmcnt(8)
	s_waitcnt lgkmcnt(0)
	s_setprio 1
	s_barrier
	v_mfma_f32_16x16x32_bf16 v[124:127], v[146:149], v[184:187], v[124:127]
	v_mfma_f32_16x16x32_bf16 v[120:123], v[160:163], v[184:187], v[120:123]
	v_mfma_f32_16x16x32_bf16 v[108:111], v[146:149], v[192:195], v[108:111]
	v_mfma_f32_16x16x32_bf16 v[104:107], v[160:163], v[192:195], v[104:107]
	v_mfma_f32_16x16x32_bf16 v[92:95], v[146:149], v[200:203], v[92:95]
	v_mfma_f32_16x16x32_bf16 v[88:91], v[160:163], v[200:203], v[88:91]
	v_mfma_f32_16x16x32_bf16 v[76:79], v[146:149], v[210:213], v[76:79]
	v_mfma_f32_16x16x32_bf16 v[72:75], v[160:163], v[210:213], v[72:75]
	v_mfma_f32_16x16x32_bf16 v[124:127], v[156:159], v[188:191], v[124:127]
	v_mfma_f32_16x16x32_bf16 v[120:123], v[164:167], v[188:191], v[120:123]
	v_mfma_f32_16x16x32_bf16 v[108:111], v[156:159], v[196:199], v[108:111]
	v_mfma_f32_16x16x32_bf16 v[104:107], v[164:167], v[196:199], v[104:107]
	v_mfma_f32_16x16x32_bf16 v[92:95], v[156:159], v[206:209], v[92:95]
	v_mfma_f32_16x16x32_bf16 v[88:91], v[164:167], v[206:209], v[88:91]
	v_mfma_f32_16x16x32_bf16 v[76:79], v[156:159], v[214:217], v[76:79]
	v_mfma_f32_16x16x32_bf16 v[72:75], v[164:167], v[214:217], v[72:75]
	v_mfma_f32_16x16x32_bf16 v[116:119], v[168:171], v[184:187], v[116:119]
	v_mfma_f32_16x16x32_bf16 v[112:115], v[176:179], v[184:187], v[112:115]
	v_mfma_f32_16x16x32_bf16 v[100:103], v[168:171], v[192:195], v[100:103]
	v_mfma_f32_16x16x32_bf16 v[96:99], v[176:179], v[192:195], v[96:99]
	v_mfma_f32_16x16x32_bf16 v[84:87], v[168:171], v[200:203], v[84:87]
	v_mfma_f32_16x16x32_bf16 v[80:83], v[176:179], v[200:203], v[80:83]
	v_mfma_f32_16x16x32_bf16 v[68:71], v[168:171], v[210:213], v[68:71]
	v_mfma_f32_16x16x32_bf16 v[64:67], v[176:179], v[210:213], v[64:67]
	v_mfma_f32_16x16x32_bf16 v[116:119], v[172:175], v[188:191], v[116:119]
	v_mfma_f32_16x16x32_bf16 v[112:115], v[180:183], v[188:191], v[112:115]
	v_mfma_f32_16x16x32_bf16 v[100:103], v[172:175], v[196:199], v[100:103]
	v_mfma_f32_16x16x32_bf16 v[96:99], v[180:183], v[196:199], v[96:99]
	v_mfma_f32_16x16x32_bf16 v[84:87], v[172:175], v[206:209], v[84:87]
	v_mfma_f32_16x16x32_bf16 v[80:83], v[180:183], v[206:209], v[80:83]
	v_mfma_f32_16x16x32_bf16 v[68:71], v[172:175], v[214:217], v[68:71]
	v_mfma_f32_16x16x32_bf16 v[64:67], v[180:183], v[214:217], v[64:67]
	s_setprio 0
	s_barrier
	s_add_i32 s63, s55, s33
	s_mov_b32 m0, s63
	ds_read_b128 v[184:187], v153 offset:16384
	ds_read_b128 v[188:191], v153 offset:17408
	ds_read_b128 v[192:195], v153 offset:18432
	ds_read_b128 v[196:199], v153 offset:19456
	ds_read_b128 v[200:203], v153 offset:20480
	ds_read_b128 v[206:209], v153 offset:21504
	ds_read_b128 v[210:213], v153 offset:22528
	ds_read_b128 v[214:217], v153 offset:23552
	s_waitcnt vmcnt(2)
	s_waitcnt lgkmcnt(0)
	s_setprio 1
	s_barrier
	v_mfma_f32_16x16x32_bf16 v[60:63], v[146:149], v[184:187], v[60:63]
	v_mfma_f32_16x16x32_bf16 v[56:59], v[160:163], v[184:187], v[56:59]
	v_mfma_f32_16x16x32_bf16 v[44:47], v[146:149], v[192:195], v[44:47]
	v_mfma_f32_16x16x32_bf16 v[40:43], v[160:163], v[192:195], v[40:43]
	v_mfma_f32_16x16x32_bf16 v[28:31], v[146:149], v[200:203], v[28:31]
	v_mfma_f32_16x16x32_bf16 v[24:27], v[160:163], v[200:203], v[24:27]
	v_mfma_f32_16x16x32_bf16 v[12:15], v[146:149], v[210:213], v[12:15]
	v_mfma_f32_16x16x32_bf16 v[8:11], v[160:163], v[210:213], v[8:11]
	v_mfma_f32_16x16x32_bf16 v[60:63], v[156:159], v[188:191], v[60:63]
	v_mfma_f32_16x16x32_bf16 v[56:59], v[164:167], v[188:191], v[56:59]
	v_mfma_f32_16x16x32_bf16 v[44:47], v[156:159], v[196:199], v[44:47]
	v_mfma_f32_16x16x32_bf16 v[40:43], v[164:167], v[196:199], v[40:43]
	v_mfma_f32_16x16x32_bf16 v[28:31], v[156:159], v[206:209], v[28:31]
	v_mfma_f32_16x16x32_bf16 v[24:27], v[164:167], v[206:209], v[24:27]
	v_mfma_f32_16x16x32_bf16 v[12:15], v[156:159], v[214:217], v[12:15]
	v_mfma_f32_16x16x32_bf16 v[8:11], v[164:167], v[214:217], v[8:11]
	v_mfma_f32_16x16x32_bf16 v[52:55], v[168:171], v[184:187], v[52:55]
	v_mfma_f32_16x16x32_bf16 v[48:51], v[176:179], v[184:187], v[48:51]
	v_mfma_f32_16x16x32_bf16 v[36:39], v[168:171], v[192:195], v[36:39]
	v_mfma_f32_16x16x32_bf16 v[32:35], v[176:179], v[192:195], v[32:35]
	v_mfma_f32_16x16x32_bf16 v[20:23], v[168:171], v[200:203], v[20:23]
	v_mfma_f32_16x16x32_bf16 v[16:19], v[176:179], v[200:203], v[16:19]
	v_mfma_f32_16x16x32_bf16 v[4:7], v[168:171], v[210:213], v[4:7]
	v_mfma_f32_16x16x32_bf16 v[0:3], v[176:179], v[210:213], v[0:3]
	v_mfma_f32_16x16x32_bf16 v[52:55], v[172:175], v[188:191], v[52:55]
	v_mfma_f32_16x16x32_bf16 v[48:51], v[180:183], v[188:191], v[48:51]
	v_mfma_f32_16x16x32_bf16 v[36:39], v[172:175], v[196:199], v[36:39]
	v_mfma_f32_16x16x32_bf16 v[32:35], v[180:183], v[196:199], v[32:35]
	v_mfma_f32_16x16x32_bf16 v[20:23], v[172:175], v[206:209], v[20:23]
	v_mfma_f32_16x16x32_bf16 v[16:19], v[180:183], v[206:209], v[16:19]
	v_mfma_f32_16x16x32_bf16 v[4:7], v[172:175], v[214:217], v[4:7]
	v_mfma_f32_16x16x32_bf16 v[0:3], v[180:183], v[214:217], v[0:3]
	s_setprio 0
	s_barrier
; #define PG8_STAGE(bufoff, gbase, voff) do { _Pragma("unroll") for (int _i = 0; _i < 2; ++_i) \
;         __builtin_amdgcn_global_load_lds((const unsigned*)((const char*)(gbase) + (voff)[_i]), (PG8_LAS unsigned*)(lds + (bufoff) + ldsw + _i * 8192), 16, 0, 0); } while (0)
; #define PG8_LDA(dst, b, h) do { _Pragma("unroll") for (int m = 0; m < 4; ++m) _Pragma("unroll") for (int k = 0; k < 2; ++k) dst[m][k] = *(const PG8_LAS bf16x8*)(lds + PG8_SA(b, h) + aoff + m * 2048 + k * 1024); } while (0)
; #define PG8_LDB(dst, b, h) do { _Pragma("unroll") for (int n = 0; n < 2; ++n) _Pragma("unroll") for (int k = 0; k < 2; ++k) dst[n][k] = *(const PG8_LAS bf16x8*)(lds + PG8_SB(b, h) + boff + n * 2048 + k * 1024); } while (0)
; template <class Epi, class Sched, bool ALIGN_EPI = false, bool SP2 = false>
; __device__ __forceinline__ void gemm_phase(PG8_LAS unsigned char* lds, const Gemm g, const Sched& S, const Epi& E) {
;     ...
;         for (int t = 0; t < nt; t += 2) {
;             const bool last = (t == nt - 2);
;             const char* a1 = cA + (size_t)(t + 1) * kstep;
;             const char* a2 = last ? nA : cA + (size_t)(t + 2) * kstep; const char* b2 = last ? nB : cB + (size_t)(t + 2) * kstep;
;             const char* a3 = a2 + kstep; const char* b3 = b2 + kstep;
;             if (last && has_next) S.a_ready(nxt);
;             if constexpr (SP2) {
;             PG8_LDB(B0, 0, 0); PG8_LDB(B1, 0, 1); PG8_SCHED; PG8_LDA(At, 0, 0); PG8_STAGE(PG8_SA(1, 1), a1 + hstep, voffA);
;             PG8_WAIT_V(8); PG8_WAIT_L(0); PG8_BAR; PG8_MMA(0, 0, At, B0); PG8_MMA(0, 1, At, B1); PG8_BAR; PG8_SCHED;
;             PG8_LDA(At, 0, 1); PG8_STAGE(PG8_SB(0, 0), b2, voffB); PG8_STAGE(PG8_SB(0, 1), b2 + hstep, voffB); PG8_STAGE(PG8_SA(0, 0), a2, voffA);
;             PG8_WAIT_V(8); PG8_WAIT_L(0); PG8_BAR; PG8_MMA(1, 0, At, B0); PG8_MMA(1, 1, At, B1); PG8_BAR; PG8_SCHED;
;             PG8_LDB(B0, 1, 0); PG8_LDB(B1, 1, 1); PG8_SCHED; PG8_LDA(At, 1, 0); PG8_STAGE(PG8_SA(0, 1), a2 + hstep, voffA);
;             PG8_WAIT_V(8); PG8_WAIT_L(0); PG8_BAR; PG8_MMA(0, 0, At, B0); PG8_MMA(0, 1, At, B1); PG8_BAR; PG8_SCHED;
;             PG8_LDA(At, 1, 1); PG8_STAGE(PG8_SB(1, 0), b3, voffB); PG8_STAGE(PG8_SB(1, 1), b3 + hstep, voffB); PG8_STAGE(PG8_SA(1, 0), a3, voffA);
;             PG8_WAIT_V(8); PG8_WAIT_L(0); PG8_BAR; PG8_MMA(1, 0, At, B0); PG8_MMA(1, 1, At, B1); PG8_BAR; PG8_SCHED;
	s_add_i32 s63, 0, 0x18000
	s_add_i32 s64, 0, 0x1c000
	ds_read_b128 v[146:149], v240
	ds_read_b128 v[156:159], v240 offset:1024
	ds_read_b128 v[160:163], v240 offset:2048
	ds_read_b128 v[164:167], v240 offset:3072
	ds_read_b128 v[168:171], v241
	ds_read_b128 v[172:175], v241 offset:1024
	ds_read_b128 v[176:179], v241 offset:2048
	ds_read_b128 v[180:183], v241 offset:3072
	ds_read_b128 v[184:187], v153 offset:32768
	ds_read_b128 v[188:191], v153 offset:33792
	ds_read_b128 v[192:195], v153 offset:34816
	ds_read_b128 v[196:199], v153 offset:35840
	ds_read_b128 v[200:203], v153 offset:36864
	ds_read_b128 v[206:209], v153 offset:37888
	ds_read_b128 v[210:213], v153 offset:38912
	ds_read_b128 v[214:217], v153 offset:39936
	s_waitcnt vmcnt(0)
	s_waitcnt lgkmcnt(0)
	s_setprio 1
	s_barrier
	v_mfma_f32_16x16x32_bf16 v[124:127], v[146:149], v[184:187], v[124:127]
	v_mfma_f32_16x16x32_bf16 v[120:123], v[160:163], v[184:187], v[120:123]
	v_mfma_f32_16x16x32_bf16 v[108:111], v[146:149], v[192:195], v[108:111]
	v_mfma_f32_16x16x32_bf16 v[104:107], v[160:163], v[192:195], v[104:107]
	v_mfma_f32_16x16x32_bf16 v[92:95], v[146:149], v[200:203], v[92:95]
	v_mfma_f32_16x16x32_bf16 v[88:91], v[160:163], v[200:203], v[88:91]
	v_mfma_f32_16x16x32_bf16 v[76:79], v[146:149], v[210:213], v[76:79]
	v_mfma_f32_16x16x32_bf16 v[72:75], v[160:163], v[210:213], v[72:75]
	v_mfma_f32_16x16x32_bf16 v[124:127], v[156:159], v[188:191], v[124:127]
	v_mfma_f32_16x16x32_bf16 v[120:123], v[164:167], v[188:191], v[120:123]
	v_mfma_f32_16x16x32_bf16 v[108:111], v[156:159], v[196:199], v[108:111]
	v_mfma_f32_16x16x32_bf16 v[104:107], v[164:167], v[196:199], v[104:107]
	v_mfma_f32_16x16x32_bf16 v[92:95], v[156:159], v[206:209], v[92:95]
	v_mfma_f32_16x16x32_bf16 v[88:91], v[164:167], v[206:209], v[88:91]
	v_mfma_f32_16x16x32_bf16 v[76:79], v[156:159], v[214:217], v[76:79]
	v_mfma_f32_16x16x32_bf16 v[72:75], v[164:167], v[214:217], v[72:75]
	v_mfma_f32_16x16x32_bf16 v[116:119], v[168:171], v[184:187], v[116:119]
	v_mfma_f32_16x16x32_bf16 v[112:115], v[176:179], v[184:187], v[112:115]
	v_mfma_f32_16x16x32_bf16 v[100:103], v[168:171], v[192:195], v[100:103]
	v_mfma_f32_16x16x32_bf16 v[96:99], v[176:179], v[192:195], v[96:99]
	v_mfma_f32_16x16x32_bf16 v[84:87], v[168:171], v[200:203], v[84:87]
	v_mfma_f32_16x16x32_bf16 v[80:83], v[176:179], v[200:203], v[80:83]
	v_mfma_f32_16x16x32_bf16 v[68:71], v[168:171], v[210:213], v[68:71]
	v_mfma_f32_16x16x32_bf16 v[64:67], v[176:179], v[210:213], v[64:67]
	v_mfma_f32_16x16x32_bf16 v[116:119], v[172:175], v[188:191], v[116:119]
	v_mfma_f32_16x16x32_bf16 v[112:115], v[180:183], v[188:191], v[112:115]
	v_mfma_f32_16x16x32_bf16 v[100:103], v[172:175], v[196:199], v[100:103]
	v_mfma_f32_16x16x32_bf16 v[96:99], v[180:183], v[196:199], v[96:99]
	v_mfma_f32_16x16x32_bf16 v[84:87], v[172:175], v[206:209], v[84:87]
	v_mfma_f32_16x16x32_bf16 v[80:83], v[180:183], v[206:209], v[80:83]
	v_mfma_f32_16x16x32_bf16 v[68:71], v[172:175], v[214:217], v[68:71]
	v_mfma_f32_16x16x32_bf16 v[64:67], v[180:183], v[214:217], v[64:67]
	s_setprio 0
	s_barrier
	ds_read_b128 v[184:187], v153 offset:49152
	ds_read_b128 v[188:191], v153 offset:50176
	ds_read_b128 v[192:195], v153 offset:51200
	ds_read_b128 v[196:199], v153 offset:52224
	ds_read_b128 v[200:203], v153 offset:53248
	ds_read_b128 v[206:209], v153 offset:54272
	ds_read_b128 v[210:213], v153 offset:55296
	ds_read_b128 v[214:217], v153 offset:56320
	s_waitcnt lgkmcnt(0)
	s_setprio 1
	s_barrier
	v_mfma_f32_16x16x32_bf16 v[60:63], v[146:149], v[184:187], v[60:63]
	v_mfma_f32_16x16x32_bf16 v[56:59], v[160:163], v[184:187], v[56:59]
	v_mfma_f32_16x16x32_bf16 v[44:47], v[146:149], v[192:195], v[44:47]
	v_mfma_f32_16x16x32_bf16 v[40:43], v[160:163], v[192:195], v[40:43]
	v_mfma_f32_16x16x32_bf16 v[28:31], v[146:149], v[200:203], v[28:31]
	v_mfma_f32_16x16x32_bf16 v[24:27], v[160:163], v[200:203], v[24:27]
	v_mfma_f32_16x16x32_bf16 v[12:15], v[146:149], v[210:213], v[12:15]
	v_mfma_f32_16x16x32_bf16 v[8:11], v[160:163], v[210:213], v[8:11]
	v_mfma_f32_16x16x32_bf16 v[60:63], v[156:159], v[188:191], v[60:63]
	v_mfma_f32_16x16x32_bf16 v[56:59], v[164:167], v[188:191], v[56:59]
	v_mfma_f32_16x16x32_bf16 v[44:47], v[156:159], v[196:199], v[44:47]
	v_mfma_f32_16x16x32_bf16 v[40:43], v[164:167], v[196:199], v[40:43]
	v_mfma_f32_16x16x32_bf16 v[28:31], v[156:159], v[206:209], v[28:31]
	v_mfma_f32_16x16x32_bf16 v[24:27], v[164:167], v[206:209], v[24:27]
	v_mfma_f32_16x16x32_bf16 v[12:15], v[156:159], v[214:217], v[12:15]
	v_mfma_f32_16x16x32_bf16 v[8:11], v[164:167], v[214:217], v[8:11]
	v_mfma_f32_16x16x32_bf16 v[52:55], v[168:171], v[184:187], v[52:55]
	v_mfma_f32_16x16x32_bf16 v[48:51], v[176:179], v[184:187], v[48:51]
	v_mfma_f32_16x16x32_bf16 v[36:39], v[168:171], v[192:195], v[36:39]
	v_mfma_f32_16x16x32_bf16 v[32:35], v[176:179], v[192:195], v[32:35]
	v_mfma_f32_16x16x32_bf16 v[20:23], v[168:171], v[200:203], v[20:23]
	v_mfma_f32_16x16x32_bf16 v[16:19], v[176:179], v[200:203], v[16:19]
	v_mfma_f32_16x16x32_bf16 v[4:7], v[168:171], v[210:213], v[4:7]
	v_mfma_f32_16x16x32_bf16 v[0:3], v[176:179], v[210:213], v[0:3]
	v_mfma_f32_16x16x32_bf16 v[52:55], v[172:175], v[188:191], v[52:55]
	v_mfma_f32_16x16x32_bf16 v[48:51], v[180:183], v[188:191], v[48:51]
	v_mfma_f32_16x16x32_bf16 v[36:39], v[172:175], v[196:199], v[36:39]
	v_mfma_f32_16x16x32_bf16 v[32:35], v[180:183], v[196:199], v[32:35]
	v_mfma_f32_16x16x32_bf16 v[20:23], v[172:175], v[206:209], v[20:23]
	v_mfma_f32_16x16x32_bf16 v[16:19], v[180:183], v[206:209], v[16:19]
	v_mfma_f32_16x16x32_bf16 v[4:7], v[172:175], v[214:217], v[4:7]
	v_mfma_f32_16x16x32_bf16 v[0:3], v[180:183], v[214:217], v[0:3]
	s_setprio 0
	s_barrier
	s_add_i32 s62, s62, 2
	s_add_u32 s40, s40, 0x100
	s_addc_u32 s41, s41, 0
	s_add_u32 s60, s60, 0x100
	s_addc_u32 s61, s61, 0
